# c10 + NA attention bias LDS reads batched at loop top + remaining lane^16/^32 ds_bpermute exchanges (GEMM residual epilogues, cvt) replaced by v_permlane16/32_swap
# speedup vs baseline: 1.0076x; 1.0076x over previous
; DI unsigned pack_bf16(float lo, float hi) { f32v2 f = {lo, hi}; bf16v2 b = __builtin_convertvector(f, bf16v2); return __builtin_bit_cast(unsigned, b); }
; DI float shx(float v, int o) { int l = (int)__builtin_amdgcn_mbcnt_hi(~0u, __builtin_amdgcn_mbcnt_lo(~0u, 0u)); asm volatile("" : "+v"(l)); return __int_as_float(__builtin_amdgcn_ds_bpermute((l ^ o) << 2, __float_as_int(v))); }
; DI float wave_sum(float v) {
; #pragma unroll
;     for (int o = 32; o >= 1; o >>= 1) v += shx(v, o);
;     return v;
; DI void cvt_phase(const float* __restrict__ x, bf16_t* __restrict__ h, float* __restrict__ ss, int rows) {
;     ...
;             for (int i = 0; i < 4; ++i) v[r][i] = ((const float4*)(x + (size_t)(row0 + r) * D))[i * 64 + lane];
; #pragma unroll
;         for (int r = 0; r < RB; ++r) {
;             float s2 = 0.f;
; #pragma unroll
;             for (int i = 0; i < 4; ++i) s2 += v[r][i].x * v[r][i].x + v[r][i].y * v[r][i].y + v[r][i].z * v[r][i].z + v[r][i].w * v[r][i].w;
;             s2 = wave_sum(s2);
;             if (lane < 4) *(f32x4*)(ss + (size_t)(row0 + r) * 16 + 4 * lane) = (f32x4){lane == 0 ? s2 : 0.f, 0.f, 0.f, 0.f};
; #pragma unroll
;             for (int i = 0; i < 4; ++i) { uint2 w; w.x = pack_bf16(v[r][i].x, v[r][i].y); w.y = pack_bf16(v[r][i].z, v[r][i].w); *(uint2*)(h + (size_t)(row0 + r) * D + (i * 64 + lane) * 4) = w; }
.LBB0_132:
	v_ashrrev_i32_e32 v69, 31, v68
	v_lshlrev_b64 v[2:3], 12, v[68:69]
	v_lshl_add_u64 v[2:3], v[72:73], 0, v[2:3]
	global_load_dwordx4 v[64:67], v[2:3], off
	global_load_dwordx4 v[60:63], v[2:3], off offset:1024
	global_load_dwordx4 v[56:59], v[2:3], off offset:2048
	global_load_dwordx4 v[52:55], v[2:3], off offset:3072
	v_add_u32_e32 v80, 1, v68
	v_add_u32_e32 v78, 2, v68
	v_add_u32_e32 v76, 3, v68
	v_ashrrev_i32_e32 v81, 31, v80
	v_ashrrev_i32_e32 v79, 31, v78
	v_ashrrev_i32_e32 v77, 31, v76
	v_lshlrev_b64 v[2:3], 12, v[80:81]
	v_lshlrev_b64 v[4:5], 12, v[78:79]
	v_lshlrev_b64 v[6:7], 12, v[76:77]
	v_lshl_add_u64 v[2:3], v[72:73], 0, v[2:3]
	v_lshl_add_u64 v[4:5], v[72:73], 0, v[4:5]
	v_lshl_add_u64 v[6:7], v[72:73], 0, v[6:7]
	global_load_dwordx4 v[48:51], v[2:3], off
	global_load_dwordx4 v[44:47], v[2:3], off offset:1024
	global_load_dwordx4 v[40:43], v[2:3], off offset:2048
	global_load_dwordx4 v[36:39], v[2:3], off offset:3072
	global_load_dwordx4 v[32:35], v[4:5], off
	global_load_dwordx4 v[28:31], v[4:5], off offset:1024
	global_load_dwordx4 v[24:27], v[4:5], off offset:2048
	global_load_dwordx4 v[20:23], v[4:5], off offset:3072
	global_load_dwordx4 v[16:19], v[6:7], off
	global_load_dwordx4 v[12:15], v[6:7], off offset:1024
	global_load_dwordx4 v[8:11], v[6:7], off offset:2048
	s_nop 0
	global_load_dwordx4 v[4:7], v[6:7], off offset:3072
	s_waitcnt vmcnt(15)
	v_pk_mul_f32 v[2:3], v[64:65], v[64:65]
	s_waitcnt vmcnt(14)
	v_pk_mul_f32 v[84:85], v[60:61], v[60:61]
	v_pk_mul_f32 v[82:83], v[66:67], v[66:67]
	v_pk_mul_f32 v[86:87], v[62:63], v[62:63]
	s_waitcnt vmcnt(13)
	v_pk_mul_f32 v[88:89], v[56:57], v[56:57]
	v_add_f32_e32 v84, v84, v85
	v_add_f32_e32 v2, v2, v3
	v_pk_mul_f32 v[90:91], v[58:59], v[58:59]
	s_waitcnt vmcnt(12)
	v_pk_mul_f32 v[92:93], v[52:53], v[52:53]
	v_add_f32_e32 v3, v88, v89
	v_add_f32_e32 v84, v84, v86
	v_add_f32_e32 v2, v2, v82
	v_pk_mul_f32 v[94:95], v[54:55], v[54:55]
	v_add_f32_e32 v85, v92, v93
	v_add_f32_e32 v3, v3, v90
	v_add_f32_e32 v84, v84, v87
	v_add_f32_e32 v2, v2, v83
	v_add_f32_e32 v82, v85, v94
	v_add_f32_e32 v3, v3, v91
	v_add_f32_e32 v2, v2, v84
	v_add_f32_e32 v82, v82, v95
	v_add_f32_e32 v2, v2, v3
	v_add_f32_e32 v2, v2, v82
	v_mov_b32_e32 v0, v2
	s_nop 1
	v_permlane32_swap_b32_e32 v0, v2
	v_mov_b32_e32 v3, v205
	s_waitcnt lgkmcnt(0)
	v_add_f32_e32 v0, v2, v0
	v_lshlrev_b32_e32 v3, 2, v3
	v_xor_b32_e32 v3, 64, v3
	ds_bpermute_b32 v2, v3, v0
	v_mov_b32_e32 v3, v205
	s_waitcnt lgkmcnt(0)
	v_add_f32_e32 v0, v0, v2
	v_lshlrev_b32_e32 v3, 2, v3
	v_xor_b32_e32 v3, 32, v3
	ds_bpermute_b32 v2, v3, v0
	v_mov_b32_e32 v3, v205
	s_waitcnt lgkmcnt(0)
	v_add_f32_e32 v0, v0, v2
	v_lshlrev_b32_e32 v3, 2, v3
	v_xor_b32_e32 v3, 16, v3
	ds_bpermute_b32 v2, v3, v0
	v_mov_b32_e32 v3, v205
	s_waitcnt lgkmcnt(0)
	v_add_f32_e32 v0, v0, v2
	v_lshlrev_b32_e32 v3, 2, v3
	v_xor_b32_e32 v3, 8, v3
	ds_bpermute_b32 v2, v3, v0
	v_mov_b32_e32 v3, v205
	s_waitcnt lgkmcnt(0)
	v_add_f32_e32 v0, v0, v2
	v_lshlrev_b32_e32 v3, 2, v3
	v_xor_b32_e32 v2, 4, v3
	ds_bpermute_b32 v2, v2, v0
	s_and_saveexec_b64 s[4:5], vcc
	s_cbranch_execz .LBB0_134
	v_lshlrev_b64 v[82:83], 6, v[68:69]
	s_waitcnt lgkmcnt(0)
	v_add_f32_e32 v0, v0, v2
	v_lshl_add_u64 v[82:83], v[70:71], 0, v[82:83]
	v_cndmask_b32_e64 v0, 0, v0, s[0:1]
	v_mov_b32_e32 v2, v1
	v_mov_b32_e32 v3, v1
	global_store_dwordx4 v[82:83], v[0:3], off
.LBB0_134:
	s_or_b64 exec, exec, s[4:5]
	s_waitcnt lgkmcnt(0)
	v_lshlrev_b64 v[2:3], 11, v[68:69]
	v_cvt_pk_bf16_f32 v64, v64, v65
	v_cvt_pk_bf16_f32 v65, v66, v67
	v_lshl_add_u64 v[2:3], v[74:75], 0, v[2:3]
	v_cvt_pk_bf16_f32 v60, v60, v61
	v_cvt_pk_bf16_f32 v61, v62, v63
	v_cvt_pk_bf16_f32 v56, v56, v57
	v_cvt_pk_bf16_f32 v57, v58, v59
	v_cvt_pk_bf16_f32 v52, v52, v53
	v_cvt_pk_bf16_f32 v53, v54, v55
	global_store_dwordx2 v[2:3], v[64:65], off
	global_store_dwordx2 v[2:3], v[60:61], off offset:512
	global_store_dwordx2 v[2:3], v[56:57], off offset:1024
	global_store_dwordx2 v[2:3], v[52:53], off offset:1536
	s_waitcnt vmcnt(15)
	v_pk_mul_f32 v[2:3], v[48:49], v[48:49]
	s_waitcnt vmcnt(14)
	v_pk_mul_f32 v[54:55], v[44:45], v[44:45]
	v_pk_mul_f32 v[52:53], v[50:51], v[50:51]
	v_pk_mul_f32 v[56:57], v[46:47], v[46:47]
	v_add_f32_e32 v0, v54, v55
	v_add_f32_e32 v2, v2, v3
	v_add_f32_e32 v0, v0, v56
	v_add_f32_e32 v2, v2, v52
	s_waitcnt vmcnt(13)
	v_pk_mul_f32 v[58:59], v[40:41], v[40:41]
	v_add_f32_e32 v0, v0, v57
	v_add_f32_e32 v2, v2, v53
	v_pk_mul_f32 v[60:61], v[42:43], v[42:43]
	v_add_f32_e32 v0, v2, v0
	v_add_f32_e32 v2, v58, v59
	v_add_f32_e32 v2, v2, v60
	s_waitcnt vmcnt(12)
	v_pk_mul_f32 v[62:63], v[36:37], v[36:37]
	v_add_f32_e32 v2, v2, v61
	v_pk_mul_f32 v[64:65], v[38:39], v[38:39]
	v_add_f32_e32 v0, v0, v2
	v_add_f32_e32 v2, v62, v63
	v_add_f32_e32 v2, v2, v64
	v_add_f32_e32 v2, v2, v65
	v_add_f32_e32 v0, v0, v2
	s_nop 0
	v_mov_b32_e32 v2, v0
	s_nop 1
	v_permlane32_swap_b32_e32 v2, v0
	s_waitcnt lgkmcnt(0)
	v_add_f32_e32 v0, v0, v2
	s_nop 0
	v_mov_b32_e32 v2, v0
	s_nop 1
	v_permlane16_swap_b32_e32 v2, v0
	s_waitcnt lgkmcnt(0)
	v_add_f32_e32 v0, v0, v2
	v_mov_b32_e32 v2, v205
	s_nop 0
	v_lshlrev_b32_e32 v2, 2, v2
	v_xor_b32_e32 v2, 32, v2
	ds_bpermute_b32 v2, v2, v0
	s_waitcnt lgkmcnt(0)
	v_add_f32_e32 v0, v0, v2
	v_mov_b32_e32 v2, v205
	s_nop 0
	v_lshlrev_b32_e32 v2, 2, v2
	v_xor_b32_e32 v2, 16, v2
	ds_bpermute_b32 v2, v2, v0
	s_waitcnt lgkmcnt(0)
	v_add_f32_e32 v0, v0, v2
	v_mov_b32_e32 v2, v205
	s_nop 0
	v_lshlrev_b32_e32 v2, 2, v2
	v_xor_b32_e32 v2, 8, v2
	ds_bpermute_b32 v2, v2, v0
	s_waitcnt lgkmcnt(0)
	v_add_f32_e32 v0, v0, v2
	v_mov_b32_e32 v2, v205
	s_nop 0
	v_lshlrev_b32_e32 v2, 2, v2
	v_xor_b32_e32 v2, 4, v2
	ds_bpermute_b32 v2, v2, v0
	s_and_saveexec_b64 s[4:5], vcc
	s_cbranch_execz .LBB0_136
	v_lshlrev_b64 v[52:53], 6, v[80:81]
	s_waitcnt lgkmcnt(0)
	v_add_f32_e32 v0, v0, v2
	v_lshl_add_u64 v[52:53], v[70:71], 0, v[52:53]
	v_cndmask_b32_e64 v0, 0, v0, s[0:1]
	v_mov_b32_e32 v2, v1
	v_mov_b32_e32 v3, v1
	global_store_dwordx4 v[52:53], v[0:3], off
; DI unsigned pack_bf16(float lo, float hi) { f32v2 f = {lo, hi}; bf16v2 b = __builtin_convertvector(f, bf16v2); return __builtin_bit_cast(unsigned, b); }
; DI float shx(float v, int o) { int l = (int)__builtin_amdgcn_mbcnt_hi(~0u, __builtin_amdgcn_mbcnt_lo(~0u, 0u)); asm volatile("" : "+v"(l)); return __int_as_float(__builtin_amdgcn_ds_bpermute((l ^ o) << 2, __float_as_int(v))); }
; DI float wave_sum(float v) {
; #pragma unroll
;     for (int o = 32; o >= 1; o >>= 1) v += shx(v, o);
;     return v;
; DI void cvt_phase(const float* __restrict__ x, bf16_t* __restrict__ h, float* __restrict__ ss, int rows) {
;     ...
;         for (int r = 0; r < RB; ++r) {
;             float s2 = 0.f;
; #pragma unroll
;             for (int i = 0; i < 4; ++i) s2 += v[r][i].x * v[r][i].x + v[r][i].y * v[r][i].y + v[r][i].z * v[r][i].z + v[r][i].w * v[r][i].w;
;             s2 = wave_sum(s2);
;             if (lane < 4) *(f32x4*)(ss + (size_t)(row0 + r) * 16 + 4 * lane) = (f32x4){lane == 0 ? s2 : 0.f, 0.f, 0.f, 0.f};
; #pragma unroll
;             for (int i = 0; i < 4; ++i) { uint2 w; w.x = pack_bf16(v[r][i].x, v[r][i].y); w.y = pack_bf16(v[r][i].z, v[r][i].w); *(uint2*)(h + (size_t)(row0 + r) * D + (i * 64 + lane) * 4) = w; }
.LBB0_136:
	s_or_b64 exec, exec, s[4:5]
	s_waitcnt lgkmcnt(0)
	v_lshlrev_b64 v[2:3], 11, v[80:81]
	v_cvt_pk_bf16_f32 v48, v48, v49
	v_cvt_pk_bf16_f32 v49, v50, v51
	v_lshl_add_u64 v[2:3], v[74:75], 0, v[2:3]
	v_cvt_pk_bf16_f32 v44, v44, v45
	v_cvt_pk_bf16_f32 v45, v46, v47
	v_cvt_pk_bf16_f32 v40, v40, v41
	v_cvt_pk_bf16_f32 v41, v42, v43
	v_cvt_pk_bf16_f32 v36, v36, v37
	v_cvt_pk_bf16_f32 v37, v38, v39
	global_store_dwordx2 v[2:3], v[48:49], off
	global_store_dwordx2 v[2:3], v[44:45], off offset:512
	global_store_dwordx2 v[2:3], v[40:41], off offset:1024
	global_store_dwordx2 v[2:3], v[36:37], off offset:1536
	s_waitcnt vmcnt(15)
	v_pk_mul_f32 v[2:3], v[32:33], v[32:33]
	s_waitcnt vmcnt(14)
	v_pk_mul_f32 v[38:39], v[28:29], v[28:29]
	v_pk_mul_f32 v[36:37], v[34:35], v[34:35]
	v_pk_mul_f32 v[40:41], v[30:31], v[30:31]
	v_add_f32_e32 v0, v38, v39
	v_add_f32_e32 v2, v2, v3
	v_add_f32_e32 v0, v0, v40
	v_add_f32_e32 v2, v2, v36
	s_waitcnt vmcnt(13)
	v_pk_mul_f32 v[42:43], v[24:25], v[24:25]
	v_add_f32_e32 v0, v0, v41
	v_add_f32_e32 v2, v2, v37
	v_pk_mul_f32 v[44:45], v[26:27], v[26:27]
	v_add_f32_e32 v0, v2, v0
	v_add_f32_e32 v2, v42, v43
	v_add_f32_e32 v2, v2, v44
	s_waitcnt vmcnt(12)
	v_pk_mul_f32 v[46:47], v[20:21], v[20:21]
	v_add_f32_e32 v2, v2, v45
	v_pk_mul_f32 v[48:49], v[22:23], v[22:23]
	v_add_f32_e32 v0, v0, v2
	v_add_f32_e32 v2, v46, v47
	v_add_f32_e32 v2, v2, v48
	v_add_f32_e32 v2, v2, v49
	v_add_f32_e32 v0, v0, v2
	s_nop 0
	v_mov_b32_e32 v2, v0
	s_nop 1
	v_permlane32_swap_b32_e32 v2, v0
	s_waitcnt lgkmcnt(0)
	v_add_f32_e32 v0, v0, v2
	s_nop 0
	v_mov_b32_e32 v2, v0
	s_nop 1
	v_permlane16_swap_b32_e32 v2, v0
	s_waitcnt lgkmcnt(0)
	v_add_f32_e32 v0, v0, v2
	v_mov_b32_e32 v2, v205
	s_nop 0
	v_lshlrev_b32_e32 v2, 2, v2
	v_xor_b32_e32 v2, 32, v2
	ds_bpermute_b32 v2, v2, v0
	s_waitcnt lgkmcnt(0)
	v_add_f32_e32 v0, v0, v2
	v_mov_b32_e32 v2, v205
	s_nop 0
	v_lshlrev_b32_e32 v2, 2, v2
	v_xor_b32_e32 v2, 16, v2
	ds_bpermute_b32 v2, v2, v0
	s_waitcnt lgkmcnt(0)
	v_add_f32_e32 v0, v0, v2
	v_mov_b32_e32 v2, v205
	s_nop 0
	v_lshlrev_b32_e32 v2, 2, v2
	v_xor_b32_e32 v2, 8, v2
	ds_bpermute_b32 v2, v2, v0
	s_waitcnt lgkmcnt(0)
	v_add_f32_e32 v0, v0, v2
	v_mov_b32_e32 v2, v205
	s_nop 0
	v_lshlrev_b32_e32 v2, 2, v2
	v_xor_b32_e32 v2, 4, v2
	ds_bpermute_b32 v2, v2, v0
	s_and_saveexec_b64 s[4:5], vcc
	s_cbranch_execz .LBB0_138
	v_lshlrev_b64 v[36:37], 6, v[78:79]
	s_waitcnt lgkmcnt(0)
	v_add_f32_e32 v0, v0, v2
	v_lshl_add_u64 v[36:37], v[70:71], 0, v[36:37]
	v_cndmask_b32_e64 v0, 0, v0, s[0:1]
	v_mov_b32_e32 v2, v1
	v_mov_b32_e32 v3, v1
	global_store_dwordx4 v[36:37], v[0:3], off
.LBB0_138:
	s_or_b64 exec, exec, s[4:5]
	s_waitcnt lgkmcnt(0)
	v_lshlrev_b64 v[2:3], 11, v[78:79]
	v_cvt_pk_bf16_f32 v32, v32, v33
	v_cvt_pk_bf16_f32 v33, v34, v35
	v_lshl_add_u64 v[2:3], v[74:75], 0, v[2:3]
	v_cvt_pk_bf16_f32 v28, v28, v29
	v_cvt_pk_bf16_f32 v29, v30, v31
	v_cvt_pk_bf16_f32 v24, v24, v25
	v_cvt_pk_bf16_f32 v25, v26, v27
	v_cvt_pk_bf16_f32 v20, v20, v21
	v_cvt_pk_bf16_f32 v21, v22, v23
	global_store_dwordx2 v[2:3], v[32:33], off
	global_store_dwordx2 v[2:3], v[28:29], off offset:512
	global_store_dwordx2 v[2:3], v[24:25], off offset:1024
	global_store_dwordx2 v[2:3], v[20:21], off offset:1536
	s_waitcnt vmcnt(15)
	v_pk_mul_f32 v[2:3], v[16:17], v[16:17]
	s_waitcnt vmcnt(14)
	v_pk_mul_f32 v[22:23], v[12:13], v[12:13]
	v_pk_mul_f32 v[20:21], v[18:19], v[18:19]
	v_pk_mul_f32 v[24:25], v[14:15], v[14:15]
	v_add_f32_e32 v0, v22, v23
	v_add_f32_e32 v2, v2, v3
	v_add_f32_e32 v0, v0, v24
	v_add_f32_e32 v2, v2, v20
	s_waitcnt vmcnt(13)
	v_pk_mul_f32 v[26:27], v[8:9], v[8:9]
	v_add_f32_e32 v0, v0, v25
	v_add_f32_e32 v2, v2, v21
	v_pk_mul_f32 v[28:29], v[10:11], v[10:11]
	v_add_f32_e32 v0, v2, v0
	v_add_f32_e32 v2, v26, v27
	v_add_f32_e32 v2, v2, v28
	s_waitcnt vmcnt(12)
	v_pk_mul_f32 v[30:31], v[4:5], v[4:5]
	v_add_f32_e32 v2, v2, v29
	v_pk_mul_f32 v[32:33], v[6:7], v[6:7]
	v_add_f32_e32 v0, v0, v2
	v_add_f32_e32 v2, v30, v31
	v_add_f32_e32 v2, v2, v32
	v_add_f32_e32 v2, v2, v33
	v_add_f32_e32 v0, v0, v2
	s_nop 0
	v_mov_b32_e32 v2, v0
	s_nop 1
	v_permlane32_swap_b32_e32 v2, v0
	s_waitcnt lgkmcnt(0)
	v_add_f32_e32 v0, v0, v2
	s_nop 0
	v_mov_b32_e32 v2, v0
	s_nop 1
	v_permlane16_swap_b32_e32 v2, v0
	s_waitcnt lgkmcnt(0)
	v_add_f32_e32 v0, v0, v2
	v_mov_b32_e32 v2, v205
	s_nop 0
	v_lshlrev_b32_e32 v2, 2, v2
	v_xor_b32_e32 v2, 32, v2
	ds_bpermute_b32 v2, v2, v0
	s_waitcnt lgkmcnt(0)
	v_add_f32_e32 v0, v0, v2
	v_mov_b32_e32 v2, v205
	s_nop 0
	v_lshlrev_b32_e32 v2, 2, v2
	v_xor_b32_e32 v2, 16, v2
	ds_bpermute_b32 v2, v2, v0
	s_waitcnt lgkmcnt(0)
	v_add_f32_e32 v0, v0, v2
	v_mov_b32_e32 v2, v205
	s_nop 0
	v_lshlrev_b32_e32 v2, 2, v2
	v_xor_b32_e32 v2, 8, v2
	ds_bpermute_b32 v2, v2, v0
	s_waitcnt lgkmcnt(0)
	v_add_f32_e32 v0, v0, v2
	v_mov_b32_e32 v2, v205
	s_nop 0
	v_lshlrev_b32_e32 v2, 2, v2
	v_xor_b32_e32 v2, 4, v2
	ds_bpermute_b32 v2, v2, v0
	s_and_saveexec_b64 s[4:5], vcc
	s_cbranch_execz .LBB0_131
	v_lshlrev_b64 v[20:21], 6, v[76:77]
	s_waitcnt lgkmcnt(0)
	v_add_f32_e32 v0, v0, v2
	v_lshl_add_u64 v[20:21], v[70:71], 0, v[20:21]
	v_cndmask_b32_e64 v0, 0, v0, s[0:1]
	v_mov_b32_e32 v2, v1
	v_mov_b32_e32 v3, v1
	global_store_dwordx4 v[20:21], v[0:3], off
	s_branch .LBB0_131

; #define LAS __attribute__((address_space(3)))
; DI float fexp2(float x) { return __builtin_amdgcn_exp2f(x); }
; DI float shx(float v, int o) { int l = (int)__builtin_amdgcn_mbcnt_hi(~0u, __builtin_amdgcn_mbcnt_lo(~0u, 0u)); asm volatile("" : "+v"(l)); return __int_as_float(__builtin_amdgcn_ds_bpermute((l ^ o) << 2, __float_as_int(v))); }
; DI f32x16 mfma32(bf16x8 a, bf16x8 b, f32x16 c) { return __builtin_amdgcn_mfma_f32_32x32x16_bf16(a, b, c, 0, 0, 0); }
;     DI void loadk(int t, bf16x8 (&kn)[4]) const { attn_load_k(P, tokbase, EIN, kcol, 1, 0, SEQ, (rsA + t) * 64 + c0, lane, kn); }
;     DI void loadv(int t, bf16x8 (&vn)[4]) const { attn_load_v(P, tokbase, EIN, vcol, 1, 0, SEQ, (rsA + t) * 64 + c0, lane, vn); }
;     DI void rest(int t, const f32x16& S, LAS unsigned char* LV, int ln, f32x16& O0, f32x16& O1, float& m_run, float& l_run) const { attn_rest(S, LV, ln, O0, O1, m_run, l_run, mask(t)); }
;     DI void loadk(int T, bf16x8 (&kn)[4]) const { const int sh = sh_of(T); attn_load_k(P, tokbase, EIN, kcol, 1 << sh, r & ((1 << sh) - 1), SEQ >> sh, m0_of(T), lane, kn); }
; DI f32x16 attn_scores(LAS unsigned char* LQ, int lane, const bf16x8 (&kf)[4]) {
;     ...
;     for (int c = 0; c < 4; ++c) S = mfma32(kf[c], lds_r128(LQ, c * 1024 + lane * 16), S);
;     return S;
; }
; template <class MaskF>
; DI void attn_rest(const f32x16& S, LAS unsigned char* LV, int lane, f32x16& O0, f32x16& O1, float& m_run, float& l_run, const MaskF& maskf) {
;     const int h = lane >> 5;
;     float sv[16]; float mx = -1e30f;
; #pragma unroll
;     for (int r = 0; r < 16; ++r) { sv[r] = maskf((r & 3) + 8 * (r >> 2), S[r]); mx = fmaxf(mx, sv[r]); }
;     mx = fmaxf(mx, shx(mx, 32));
;     if (__builtin_amdgcn_ballot_w64(mx > m_run) != 0ull) {
;         const float mn = fmaxf(m_run, mx);
;         const float alpha = fexp2(m_run - mn);
;         m_run = mn; l_run *= alpha;
; #pragma unroll
;         for (int i = 0; i < 16; ++i) { O0[i] *= alpha; O1[i] *= alpha; }
;     }
; template <class Desc>
; DI void attn_loop(const Desc& d, int ntiles, const bf16x8 (&qf)[4], LAS unsigned char* LV, int lane, bf16_t* orow) {
;     ...
;     for (int t = 0; t + 1 < ntiles; t += 2) {
;         const f32x16 Sa = attn_scores(LQ, lane, kA);
;         d.loadk(t + 2 < tl ? t + 2 : tl, kA);
;         attn_store_v(LV, lane, vN);
;         d.loadv(t + 1, vN);
;         d.rest(t, Sa, LV, lane, O0, O1, m_run, l_run);
.LBB0_347:
	ds_read2_b32 v[206:207], v173 offset1:1
	ds_read2_b32 v[208:209], v173 offset0:2 offset1:3
	ds_read2_b32 v[210:211], v173 offset0:8 offset1:9
	ds_read2_b32 v[212:213], v173 offset0:10 offset1:11
	ds_read2_b32 v[214:215], v173 offset0:16 offset1:17
	ds_read2_b32 v[216:217], v173 offset0:18 offset1:19
	ds_read2_b32 v[218:219], v173 offset0:24 offset1:25
	ds_read2_b32 v[220:221], v173 offset0:26 offset1:27
	ds_read2_b32 v[178:179], v173 offset0:31 offset1:32
	ds_read2_b32 v[180:181], v173 offset0:33 offset1:34
	ds_read2_b32 v[182:183], v173 offset0:39 offset1:40
	ds_read2_b32 v[184:185], v173 offset0:41 offset1:42
	ds_read2_b32 v[186:187], v173 offset0:47 offset1:48
	ds_read2_b32 v[188:189], v173 offset0:49 offset1:50
	ds_read2_b32 v[190:191], v173 offset0:55 offset1:56
	ds_read2_b32 v[192:193], v173 offset0:57 offset1:58
	s_add_i32 s38, s44, -1
	v_min_i32_e32 v0, s38, v169
	v_add_u32_e32 v0, v0, v165
	v_lshl_or_b32 v15, v0, 6, v135
	s_waitcnt vmcnt(11)
	v_mfma_f32_32x32x16_bf16 v[48:63], v[76:79], v[236:239], 0
	v_add_u32_e32 v0, v15, v121
	v_med3_i32 v0, v0, 0, v228
	v_or_b32_e32 v0, v138, v0
	v_add_u32_e32 v175, v125, v127
	v_add_u32_e32 v14, s44, v170
	s_waitcnt vmcnt(10)
	v_mfma_f32_32x32x16_bf16 v[48:63], v[72:75], v[240:243], v[48:63]
	s_waitcnt vmcnt(9)
	v_mfma_f32_32x32x16_bf16 v[48:63], v[68:71], v[244:247], v[48:63]
	s_waitcnt vmcnt(8)
	v_mfma_f32_32x32x16_bf16 v[48:63], v[64:67], v[248:251], v[48:63]
	v_mad_u64_u32 v[2:3], s[38:39], v0, s90, v[142:143]
	v_min_u32_e32 v0, 0xfff, v174
	v_mad_i32_i24 v3, v139, s90, v3
	v_or_b32_e32 v0, v138, v0
	global_load_dwordx4 v[76:79], v[2:3], off offset:1024
	global_load_dwordx4 v[72:75], v[2:3], off offset:1056
	global_load_dwordx4 v[68:71], v[2:3], off offset:1088
	global_load_dwordx4 v[64:67], v[2:3], off offset:1120
	v_mad_u64_u32 v[2:3], s[38:39], v0, s90, v[140:141]
	v_min_u32_e32 v0, 0xff7, v174
	v_add_u32_e32 v0, 8, v0
	v_lshl_add_u64 v[6:7], v[138:139], 0, v[0:1]
	v_min_u32_e32 v0, 0xfef, v174
	v_add_u32_e32 v0, 16, v0
	v_lshl_add_u64 v[10:11], v[138:139], 0, v[0:1]
	v_min_u32_e32 v0, 0xfe7, v174
	v_add_u32_e32 v0, 24, v0
	s_waitcnt vmcnt(7)
	ds_write_b128 v175, v[96:99] offset:16384
	s_waitcnt vmcnt(6)
	ds_write_b128 v175, v[100:103] offset:17920
	s_waitcnt vmcnt(5)
	ds_write_b128 v175, v[104:107] offset:19456
	s_waitcnt vmcnt(4)
	ds_write_b128 v175, v[108:111] offset:20992
	v_lshl_add_u64 v[96:97], v[138:139], 0, v[0:1]
	v_mad_u64_u32 v[8:9], s[38:39], v6, s90, v[140:141]
	v_mad_u64_u32 v[12:13], s[38:39], v10, s90, v[140:141]
	v_mad_u64_u32 v[98:99], s[38:39], v96, s90, v[140:141]
	v_mad_i32_i24 v3, v139, s90, v3
	v_mad_i32_i24 v9, v7, s90, v9
	v_mad_i32_i24 v13, v11, s90, v13
	v_mad_i32_i24 v99, v97, s90, v99
	global_load_dwordx4 v[2:5], v[2:3], off offset:2048
	global_load_dwordx4 v[6:9], v[8:9], off offset:2048
	v_add_u32_e32 v0, -7, v14
	global_load_dwordx4 v[10:13], v[12:13], off offset:2048
	v_cmp_ge_u32_e32 vcc, v0, v163
	global_load_dwordx4 v[96:99], v[98:99], off offset:2048
	v_cmp_lt_u32_e64 s[38:39], v0, v137
	s_and_b64 vcc, vcc, s[38:39]
	v_cndmask_b32_e32 v102, v230, v171, vcc
	v_cmp_gt_u32_e32 vcc, 16, v102
	s_waitcnt lgkmcnt(0)
	v_add_f32_e32 v0, v48, v206
	v_cndmask_b32_e32 v48, v229, v0, vcc
	v_add_u32_e32 v0, 1, v102
	v_cmp_gt_u32_e32 vcc, 16, v0
	v_add_f32_e32 v0, v49, v207
	v_add_u32_e32 v49, 2, v102
	v_cndmask_b32_e32 v0, v229, v0, vcc
	v_cmp_gt_u32_e32 vcc, 16, v49
	v_max3_f32 v103, v48, s83, v0
	s_waitcnt lgkmcnt(0)
	v_add_f32_e32 v49, v50, v208
	v_cndmask_b32_e32 v50, v229, v49, vcc
	v_add_u32_e32 v49, 3, v102
	v_cmp_gt_u32_e32 vcc, 16, v49
	v_add_f32_e32 v49, v51, v209
	v_add_u32_e32 v51, 8, v102
	v_cndmask_b32_e32 v49, v229, v49, vcc
	v_cmp_gt_u32_e32 vcc, 16, v51
	v_max3_f32 v103, v103, v50, v49
	s_waitcnt lgkmcnt(0)
	v_add_f32_e32 v51, v52, v210
	v_cndmask_b32_e32 v52, v229, v51, vcc
	v_add_u32_e32 v51, 9, v102
	v_cmp_gt_u32_e32 vcc, 16, v51
	v_add_f32_e32 v51, v53, v211
	v_add_u32_e32 v53, 10, v102
	v_cndmask_b32_e32 v51, v229, v51, vcc
	v_cmp_gt_u32_e32 vcc, 16, v53
	v_max3_f32 v103, v103, v52, v51
	s_waitcnt lgkmcnt(0)
	v_add_f32_e32 v53, v54, v212
	v_add_u32_e32 v54, 11, v102
	v_cndmask_b32_e32 v53, v229, v53, vcc
	v_cmp_gt_u32_e32 vcc, 16, v54
	v_add_f32_e32 v54, v55, v213
	v_cndmask_b32_e32 v54, v229, v54, vcc
	v_cmp_lt_u32_e32 vcc, s54, v102
	v_max3_f32 v103, v103, v53, v54
	s_waitcnt lgkmcnt(0)
	v_add_f32_e32 v55, v56, v214
	v_cndmask_b32_e32 v56, v229, v55, vcc
	v_add_u32_e32 v55, 17, v102
	v_cmp_gt_u32_e32 vcc, 16, v55
	v_add_f32_e32 v55, v57, v215
	v_add_u32_e32 v57, 18, v102
	v_cndmask_b32_e32 v55, v229, v55, vcc
	v_cmp_gt_u32_e32 vcc, 16, v57
	v_max3_f32 v103, v103, v56, v55
	s_waitcnt lgkmcnt(0)
	v_add_f32_e32 v57, v58, v216
	v_cndmask_b32_e32 v58, v229, v57, vcc
	v_add_u32_e32 v57, 19, v102
	v_cmp_gt_u32_e32 vcc, 16, v57
	v_add_f32_e32 v57, v59, v217
	v_add_u32_e32 v59, 24, v102
	v_cndmask_b32_e32 v57, v229, v57, vcc
	v_cmp_gt_u32_e32 vcc, 16, v59
	v_max3_f32 v103, v103, v58, v57
	s_waitcnt lgkmcnt(0)
	v_add_f32_e32 v59, v60, v218
	v_add_u32_e32 v60, 25, v102
	v_cndmask_b32_e32 v59, v229, v59, vcc
	v_cmp_gt_u32_e32 vcc, 16, v60
	v_add_f32_e32 v60, v61, v219
	v_add_u32_e32 v61, 26, v102
	v_cndmask_b32_e32 v60, v229, v60, vcc
	v_cmp_gt_u32_e32 vcc, 16, v61
	v_max3_f32 v103, v103, v59, v60
	s_waitcnt lgkmcnt(0)
	v_add_f32_e32 v61, v62, v220
	v_add_u32_e32 v62, 27, v102
	v_cndmask_b32_e32 v61, v229, v61, vcc
	v_cmp_gt_u32_e32 vcc, 16, v62
	v_add_f32_e32 v62, v63, v221
	s_nop 0
	v_cndmask_b32_e32 v62, v229, v62, vcc
	v_max3_f32 v63, v103, v61, v62
	v_mov_b32_e32 v100, v63
	s_nop 1
	v_permlane32_swap_b32_e32 v100, v63
	s_waitcnt lgkmcnt(0)
	v_max_f32_e32 v100, v100, v100
	v_max_f32_e32 v63, v63, v100
	v_cmp_gt_f32_e32 vcc, v63, v133
	s_cbranch_vccz .LBB0_349
	v_max_f32_e32 v63, v63, v63
	v_max_f32_e32 v100, v133, v133
	v_max_f32_e32 v63, v100, v63
	v_sub_f32_e32 v100, v133, v63
	v_exp_f32_e32 v100, v100
	v_mov_b32_e32 v133, v63
	v_mul_f32_e32 v159, v159, v100
	v_pk_mul_f32 v[30:31], v[30:31], v[100:101] op_sel_hi:[1,0]
	v_pk_mul_f32 v[28:29], v[28:29], v[100:101] op_sel_hi:[1,0]
	v_pk_mul_f32 v[26:27], v[26:27], v[100:101] op_sel_hi:[1,0]
	v_pk_mul_f32 v[24:25], v[24:25], v[100:101] op_sel_hi:[1,0]
	v_pk_mul_f32 v[22:23], v[22:23], v[100:101] op_sel_hi:[1,0]
	v_pk_mul_f32 v[20:21], v[20:21], v[100:101] op_sel_hi:[1,0]
	v_pk_mul_f32 v[18:19], v[18:19], v[100:101] op_sel_hi:[1,0]
	v_pk_mul_f32 v[16:17], v[16:17], v[100:101] op_sel_hi:[1,0]
	v_pk_mul_f32 v[46:47], v[46:47], v[100:101] op_sel_hi:[1,0]
	v_pk_mul_f32 v[44:45], v[44:45], v[100:101] op_sel_hi:[1,0]
	v_pk_mul_f32 v[42:43], v[42:43], v[100:101] op_sel_hi:[1,0]
	v_pk_mul_f32 v[40:41], v[40:41], v[100:101] op_sel_hi:[1,0]
	v_pk_mul_f32 v[38:39], v[38:39], v[100:101] op_sel_hi:[1,0]
	v_pk_mul_f32 v[36:37], v[36:37], v[100:101] op_sel_hi:[1,0]
	v_pk_mul_f32 v[34:35], v[34:35], v[100:101] op_sel_hi:[1,0]
	v_pk_mul_f32 v[32:33], v[32:33], v[100:101] op_sel_hi:[1,0]
; DI float fexp2(float x) { return __builtin_amdgcn_exp2f(x); }
; DI s16x4 lds_tr(LAS unsigned char* L, int off) { return __builtin_amdgcn_ds_read_tr16_b64_v4i16((LAS s16x4*)(L + off)); }
; DI bf16x8 cat4(s16x4 lo, s16x4 hi) { return __builtin_shufflevector(lo, hi, 0, 1, 2, 3, 4, 5, 6, 7); }
; DI f32x16 mfma32(bf16x8 a, bf16x8 b, f32x16 c) { return __builtin_amdgcn_mfma_f32_32x32x16_bf16(a, b, c, 0, 0, 0); }
; DI bf16x8 pack8(const float* v) { u32x4 w; w.x = pack_bf16(v[0], v[1]); w.y = pack_bf16(v[2], v[3]); w.z = pack_bf16(v[4], v[5]); w.w = pack_bf16(v[6], v[7]); return __builtin_bit_cast(bf16x8, w); }
;     DI void loadk(int t, bf16x8 (&kn)[4]) const { attn_load_k(P, tokbase, EIN, kcol, 1, 0, SEQ, (rsA + t) * 64 + c0, lane, kn); }
;     DI void loadv(int t, bf16x8 (&vn)[4]) const { attn_load_v(P, tokbase, EIN, vcol, 1, 0, SEQ, (rsA + t) * 64 + c0, lane, vn); }
;     DI void rest(int t, const f32x16& S, LAS unsigned char* LV, int ln, f32x16& O0, f32x16& O1, float& m_run, float& l_run) const { attn_rest(S, LV, ln, O0, O1, m_run, l_run, mask(t)); }
; template <class MaskF>
; DI void attn_rest(const f32x16& S, LAS unsigned char* LV, int lane, f32x16& O0, f32x16& O1, float& m_run, float& l_run, const MaskF& maskf) {
;     ...
;     float ps = 0.f;
; #pragma unroll
;     for (int r = 0; r < 16; ++r) { const float p = fexp2(sv[r] - m_run); sv[r] = p; ps += p; }
;     l_run += ps;
;     const int i16 = lane & 15, q4 = i16 >> 2, p4 = i16 & 3, blk = (lane >> 4) & 1;
; #pragma unroll
;     for (int s = 0; s < 2; ++s) {
;         const bf16x8 pf = pack8(&sv[8 * s]);
;         const int r0 = 16 * s + 4 * h + q4, cb = 2 * (16 * blk + 4 * p4);
;         const s16x4 lo0 = lds_tr(LV, r0 * ATT_RSV + cb), hi0 = lds_tr(LV, (r0 + 8) * ATT_RSV + cb);
;         const s16x4 lo1 = lds_tr(LV, r0 * ATT_RSV + 64 + cb), hi1 = lds_tr(LV, (r0 + 8) * ATT_RSV + 64 + cb);
;         O0 = mfma32(cat4(lo0, hi0), pf, O0);
;         O1 = mfma32(cat4(lo1, hi1), pf, O1);
;     }
; template <class Desc>
; DI void attn_loop(const Desc& d, int ntiles, const bf16x8 (&qf)[4], LAS unsigned char* LV, int lane, bf16_t* orow) {
;     ...
;         const f32x16 Sb = attn_scores(LQ, lane, kB);
;         d.loadk(t + 3 < tl ? t + 3 : tl, kB);
;         attn_store_v(LV, lane, vN);
;         d.loadv(t + 2 < tl ? t + 2 : tl, vN);
;         d.rest(t + 1, Sb, LV, lane, O0, O1, m_run, l_run);
.LBB0_349:
	v_add_u32_e32 v176, -6, v14
	v_sub_f32_e32 v14, v48, v133
	v_exp_f32_e32 v14, v14
	v_sub_f32_e32 v0, v0, v133
	v_exp_f32_e32 v0, v0
	v_sub_f32_e32 v50, v50, v133
	v_exp_f32_e32 v50, v50
	v_sub_f32_e32 v49, v49, v133
	v_exp_f32_e32 v49, v49
	v_sub_f32_e32 v52, v52, v133
	v_add_f32_e32 v48, 0, v14
	v_exp_f32_e32 v52, v52
	v_sub_f32_e32 v51, v51, v133
	v_add_f32_e32 v48, v0, v48
	v_exp_f32_e32 v51, v51
	v_sub_f32_e32 v53, v53, v133
	v_add_f32_e32 v48, v50, v48
	v_exp_f32_e32 v53, v53
	v_sub_f32_e32 v54, v54, v133
	v_add_f32_e32 v48, v49, v48
	v_exp_f32_e32 v54, v54
	v_sub_f32_e32 v56, v56, v133
	v_add_f32_e32 v48, v52, v48
	v_exp_f32_e32 v63, v56
	v_sub_f32_e32 v55, v55, v133
	v_add_f32_e32 v48, v51, v48
	v_exp_f32_e32 v100, v55
	v_sub_f32_e32 v55, v58, v133
	v_add_f32_e32 v48, v53, v48
	v_exp_f32_e32 v101, v55
	v_sub_f32_e32 v55, v57, v133
	v_add_f32_e32 v48, v54, v48
	v_exp_f32_e32 v102, v55
	v_sub_f32_e32 v55, v59, v133
	v_add_f32_e32 v48, v63, v48
	v_exp_f32_e32 v103, v55
	v_sub_f32_e32 v55, v60, v133
	v_add_f32_e32 v48, v100, v48
	v_exp_f32_e32 v60, v55
	v_sub_f32_e32 v55, v61, v133
	v_add_f32_e32 v48, v101, v48
	v_exp_f32_e32 v61, v55
	v_sub_f32_e32 v55, v62, v133
	v_add_f32_e32 v48, v102, v48
	v_exp_f32_e32 v62, v55
	v_add_f32_e32 v48, v103, v48
	v_add_f32_e32 v48, v60, v48
	v_add_f32_e32 v48, v61, v48
	v_add_f32_e32 v48, v62, v48
	v_add_f32_e32 v159, v159, v48
	v_cvt_pk_bf16_f32 v48, v14, v0
	v_add_u32_e32 v14, v144, v145
	v_cvt_pk_bf16_f32 v49, v50, v49
	v_cvt_pk_bf16_f32 v50, v52, v51
	v_cvt_pk_bf16_f32 v51, v53, v54
	ds_read_b64_tr_b16 v[52:53], v14 offset:16384
	v_add_u32_e32 v0, v146, v129
	ds_read_b64_tr_b16 v[54:55], v0 offset:17920
	ds_read_b64_tr_b16 v[56:57], v0 offset:16448
	ds_read_b64_tr_b16 v[58:59], v0 offset:17984
	s_waitcnt lgkmcnt(2)
	v_mfma_f32_32x32x16_bf16 v[16:31], v[52:55], v[48:51], v[16:31]
	v_cmp_ge_u32_e32 vcc, v176, v163
	s_waitcnt lgkmcnt(0)
	v_mfma_f32_32x32x16_bf16 v[32:47], v[56:59], v[48:51], v[32:47]
	ds_read_b64_tr_b16 v[52:53], v14 offset:19456
	ds_read_b64_tr_b16 v[54:55], v0 offset:20992
	ds_read_b64_tr_b16 v[56:57], v0 offset:19520
	ds_read_b64_tr_b16 v[58:59], v0 offset:21056
	v_cvt_pk_bf16_f32 v48, v63, v100
	v_cvt_pk_bf16_f32 v49, v101, v102
	v_cvt_pk_bf16_f32 v50, v103, v60
	v_cvt_pk_bf16_f32 v51, v61, v62
	s_waitcnt lgkmcnt(2)
	s_nop 0
	v_mfma_f32_32x32x16_bf16 v[16:31], v[52:55], v[48:51], v[16:31]
	s_waitcnt lgkmcnt(0)
	v_mfma_f32_32x32x16_bf16 v[32:47], v[56:59], v[48:51], v[32:47]
	s_waitcnt vmcnt(8) lgkmcnt(0)
	v_mfma_f32_32x32x16_bf16 v[48:63], v[92:95], v[236:239], 0
	s_waitcnt lgkmcnt(0)
	v_mfma_f32_32x32x16_bf16 v[48:63], v[88:91], v[240:243], v[48:63]
	s_waitcnt lgkmcnt(0)
	v_mfma_f32_32x32x16_bf16 v[48:63], v[84:87], v[244:247], v[48:63]
	s_waitcnt lgkmcnt(0)
	v_mfma_f32_32x32x16_bf16 v[48:63], v[80:83], v[248:251], v[48:63]
	v_min_i32_e32 v80, s44, v169
	v_add_u32_e32 v80, v80, v165
	v_lshl_add_u32 v80, v80, 6, v172
	v_med3_i32 v80, v80, 0, v228
	v_or_b32_e32 v80, v138, v80
	v_mad_u64_u32 v[80:81], s[38:39], v80, s90, v[142:143]
	v_mad_i32_i24 v81, v139, s90, v81
	global_load_dwordx4 v[92:95], v[80:81], off offset:1024
	global_load_dwordx4 v[88:91], v[80:81], off offset:1056
	global_load_dwordx4 v[84:87], v[80:81], off offset:1088
	s_nop 0
	global_load_dwordx4 v[80:83], v[80:81], off offset:1120
	s_waitcnt vmcnt(7)
	ds_write_b128 v175, v[2:5] offset:16384
	s_waitcnt vmcnt(6)
	ds_write_b128 v175, v[6:9] offset:17920
	s_waitcnt vmcnt(5)
	ds_write_b128 v175, v[10:13] offset:19456
	s_waitcnt vmcnt(4)
	ds_write_b128 v175, v[96:99] offset:20992
	v_or_b32_e32 v4, v15, v123
	v_med3_i32 v2, v4, 0, v228
	v_or_b32_e32 v2, v138, v2
	v_mad_u64_u32 v[2:3], s[38:39], v2, s90, v[140:141]
	v_mad_i32_i24 v3, v139, s90, v3
	global_load_dwordx4 v[96:99], v[2:3], off offset:2048
	v_add_u32_e32 v2, 8, v4
	v_med3_i32 v2, v2, 0, v228
	v_or_b32_e32 v2, v138, v2
	v_mad_u64_u32 v[2:3], s[38:39], v2, s90, v[140:141]
	v_mad_i32_i24 v3, v139, s90, v3
	global_load_dwordx4 v[100:103], v[2:3], off offset:2048
	v_add_u32_e32 v2, 16, v4
	v_med3_i32 v2, v2, 0, v228
	v_or_b32_e32 v2, v138, v2
	v_mad_u64_u32 v[2:3], s[38:39], v2, s90, v[140:141]
	v_mad_i32_i24 v3, v139, s90, v3
	global_load_dwordx4 v[104:107], v[2:3], off offset:2048
	v_add_u32_e32 v2, 24, v4
	v_med3_i32 v2, v2, 0, v228
	v_or_b32_e32 v2, v138, v2
	v_mad_u64_u32 v[2:3], s[38:39], v2, s90, v[140:141]
	v_mad_i32_i24 v3, v139, s90, v3
	global_load_dwordx4 v[108:111], v[2:3], off offset:2048
	v_cmp_lt_u32_e64 s[38:39], v176, v137
	s_and_b64 vcc, vcc, s[38:39]
	v_cndmask_b32_e32 v175, v230, v171, vcc
	v_cmp_gt_u32_e32 vcc, 16, v175
	s_waitcnt lgkmcnt(2)
; DI float fexp2(float x) { return __builtin_amdgcn_exp2f(x); }
; DI float shx(float v, int o) { int l = (int)__builtin_amdgcn_mbcnt_hi(~0u, __builtin_amdgcn_mbcnt_lo(~0u, 0u)); asm volatile("" : "+v"(l)); return __int_as_float(__builtin_amdgcn_ds_bpermute((l ^ o) << 2, __float_as_int(v))); }
; template <class MaskF>
; DI void attn_rest(const f32x16& S, LAS unsigned char* LV, int lane, f32x16& O0, f32x16& O1, float& m_run, float& l_run, const MaskF& maskf) {
;     ...
;     for (int r = 0; r < 16; ++r) { sv[r] = maskf((r & 3) + 8 * (r >> 2), S[r]); mx = fmaxf(mx, sv[r]); }
;     mx = fmaxf(mx, shx(mx, 32));
;     if (__builtin_amdgcn_ballot_w64(mx > m_run) != 0ull) {
;         const float mn = fmaxf(m_run, mx);
;         const float alpha = fexp2(m_run - mn);
;         m_run = mn; l_run *= alpha;
; #pragma unroll
;         for (int i = 0; i < 16; ++i) { O0[i] *= alpha; O1[i] *= alpha; }
;     }
	v_add_f32_e32 v2, v48, v178
	v_add_u32_e32 v4, 2, v175
	v_cndmask_b32_e32 v3, v229, v2, vcc
	v_add_u32_e32 v2, 1, v175
	v_cmp_gt_u32_e32 vcc, 16, v2
	v_add_f32_e32 v2, v49, v179
	v_cndmask_b32_e32 v2, v229, v2, vcc
	v_cmp_gt_u32_e32 vcc, 16, v4
	s_waitcnt lgkmcnt(2)
	v_add_f32_e32 v4, v50, v180
	v_max3_f32 v8, v3, s83, v2
	v_cndmask_b32_e32 v5, v229, v4, vcc
	v_add_u32_e32 v4, 3, v175
	v_cmp_gt_u32_e32 vcc, 16, v4
	v_add_f32_e32 v4, v51, v181
	v_add_u32_e32 v6, 8, v175
	v_cndmask_b32_e32 v4, v229, v4, vcc
	v_max3_f32 v10, v8, v5, v4
	v_cmp_gt_u32_e32 vcc, 16, v6
	v_add_u32_e32 v11, 10, v175
	s_waitcnt lgkmcnt(0)
	v_add_f32_e32 v6, v52, v182
	v_cndmask_b32_e32 v7, v229, v6, vcc
	v_add_u32_e32 v6, 9, v175
	v_cmp_gt_u32_e32 vcc, 16, v6
	v_add_f32_e32 v6, v53, v183
	v_cndmask_b32_e32 v6, v229, v6, vcc
	v_cmp_gt_u32_e32 vcc, 16, v11
	v_add_u32_e32 v11, 11, v175
	v_max3_f32 v10, v10, v7, v6
	s_waitcnt lgkmcnt(0)
	v_add_f32_e32 v8, v54, v184
	v_cndmask_b32_e32 v8, v229, v8, vcc
	v_cmp_gt_u32_e32 vcc, 16, v11
	v_add_f32_e32 v9, v55, v185
	s_nop 0
	v_cndmask_b32_e32 v9, v229, v9, vcc
	v_max3_f32 v15, v10, v8, v9
	v_cmp_lt_u32_e32 vcc, s54, v175
	v_add_f32_e32 v10, v56, v186
	v_add_u32_e32 v12, 18, v175
	v_cndmask_b32_e32 v11, v229, v10, vcc
	v_add_u32_e32 v10, 17, v175
	v_cmp_gt_u32_e32 vcc, 16, v10
	v_add_f32_e32 v10, v57, v187
	s_nop 0
	v_cndmask_b32_e32 v10, v229, v10, vcc
	v_cmp_gt_u32_e32 vcc, 16, v12
	v_add_f32_e32 v12, v58, v188
	v_max3_f32 v15, v15, v11, v10
	v_cndmask_b32_e32 v13, v229, v12, vcc
	v_add_u32_e32 v12, 19, v175
	v_cmp_gt_u32_e32 vcc, 16, v12
	v_add_f32_e32 v12, v59, v189
	v_cndmask_b32_e32 v12, v229, v12, vcc
	v_max3_f32 v50, v15, v13, v12
	v_add_u32_e32 v15, 24, v175
	v_cmp_gt_u32_e32 vcc, 16, v15
	s_waitcnt lgkmcnt(0)
	v_add_f32_e32 v15, v60, v190
	v_add_u32_e32 v48, 25, v175
	v_cndmask_b32_e32 v15, v229, v15, vcc
	v_cmp_gt_u32_e32 vcc, 16, v48
	v_add_f32_e32 v48, v61, v191
	v_add_u32_e32 v49, 26, v175
	v_cndmask_b32_e32 v48, v229, v48, vcc
	v_max3_f32 v52, v50, v15, v48
	v_cmp_gt_u32_e32 vcc, 16, v49
	s_waitcnt lgkmcnt(0)
	v_add_f32_e32 v49, v62, v192
	v_add_u32_e32 v50, 27, v175
	v_cndmask_b32_e32 v49, v229, v49, vcc
	v_cmp_gt_u32_e32 vcc, 16, v50
	v_add_f32_e32 v50, v63, v193
	s_nop 0
	v_cndmask_b32_e32 v50, v229, v50, vcc
	v_max3_f32 v51, v52, v49, v50
	s_nop 0
	v_mov_b32_e32 v52, v51
	s_nop 1
	v_permlane32_swap_b32_e32 v52, v51
	s_waitcnt lgkmcnt(0)
	v_max_f32_e32 v52, v52, v52
	v_max_f32_e32 v51, v51, v52
	v_cmp_gt_f32_e32 vcc, v51, v133
	s_cbranch_vccz .LBB0_346
	v_max_f32_e32 v51, v51, v51
	v_max_f32_e32 v52, v133, v133
	v_max_f32_e32 v51, v52, v51
	v_sub_f32_e32 v52, v133, v51
	v_exp_f32_e32 v52, v52
	v_mov_b32_e32 v133, v51
	v_mul_f32_e32 v159, v159, v52
	v_pk_mul_f32 v[30:31], v[30:31], v[52:53] op_sel_hi:[1,0]
	v_pk_mul_f32 v[28:29], v[28:29], v[52:53] op_sel_hi:[1,0]
	v_pk_mul_f32 v[26:27], v[26:27], v[52:53] op_sel_hi:[1,0]
	v_pk_mul_f32 v[24:25], v[24:25], v[52:53] op_sel_hi:[1,0]
	v_pk_mul_f32 v[22:23], v[22:23], v[52:53] op_sel_hi:[1,0]
	v_pk_mul_f32 v[20:21], v[20:21], v[52:53] op_sel_hi:[1,0]
	v_pk_mul_f32 v[18:19], v[18:19], v[52:53] op_sel_hi:[1,0]
	v_pk_mul_f32 v[16:17], v[16:17], v[52:53] op_sel_hi:[1,0]
	v_pk_mul_f32 v[46:47], v[46:47], v[52:53] op_sel_hi:[1,0]
	v_pk_mul_f32 v[44:45], v[44:45], v[52:53] op_sel_hi:[1,0]
	v_pk_mul_f32 v[42:43], v[42:43], v[52:53] op_sel_hi:[1,0]
	v_pk_mul_f32 v[40:41], v[40:41], v[52:53] op_sel_hi:[1,0]
	v_pk_mul_f32 v[38:39], v[38:39], v[52:53] op_sel_hi:[1,0]
	v_pk_mul_f32 v[36:37], v[36:37], v[52:53] op_sel_hi:[1,0]
	v_pk_mul_f32 v[34:35], v[34:35], v[52:53] op_sel_hi:[1,0]
	v_pk_mul_f32 v[32:33], v[32:33], v[52:53] op_sel_hi:[1,0]
	s_branch .LBB0_346

; DI unsigned pack_bf16(float lo, float hi) { f32v2 f = {lo, hi}; bf16v2 b = __builtin_convertvector(f, bf16v2); return __builtin_bit_cast(unsigned, b); }
; DI float bf_lo(unsigned u) { return __uint_as_float(u << 16); }
; DI float bf_hi(unsigned u) { return __uint_as_float(u & 0xffff0000u); }
; DI float shx(float v, int o) { int l = (int)__builtin_amdgcn_mbcnt_hi(~0u, __builtin_amdgcn_mbcnt_lo(~0u, 0u)); asm volatile("" : "+v"(l)); return __int_as_float(__builtin_amdgcn_ds_bpermute((l ^ o) << 2, __float_as_int(v))); }
;     DI void operator()(const f32x4 (&acc)[2][2][4][2], const pg8::Unit& u, int wr, int wc, int fr, int fq, int) const {
;     ...
;             for (int m = 0; m < 4; ++m) { const size_t ro = (size_t)(row0 + ai * 128 + m * 16) * D + col0;
; #pragma unroll
;                 for (int bj = 0; bj < 2; ++bj) r[m][bj] = *(const u32x4*)(hb + ro + bj * 128); }
;             asm volatile("" ::: "memory");
; #pragma unroll
;             for (int m = 0; m < 4; ++m) { const size_t ro = (size_t)(row0 + ai * 128 + m * 16) * D + col0;
;                 float sq = 0.f;
; #pragma unroll
;                 for (int bj = 0; bj < 2; ++bj) {
;                     const u32x4 rr = r[m][bj];
;                     const f32x4 v0 = (f32x4){bf_lo(rr[0]), bf_hi(rr[0]), bf_lo(rr[1]), bf_hi(rr[1])} + acc[ai][bj][m][0];
;                     const f32x4 v1 = (f32x4){bf_lo(rr[2]), bf_hi(rr[2]), bf_lo(rr[3]), bf_hi(rr[3])} + acc[ai][bj][m][1];
;                     if (LAST) { *(f32x4*)(out + ro + bj * 128) = v0; *(f32x4*)(out + ro + bj * 128 + 4) = v1; }
;                     else {
;                         u32x4 w; w.x = pack_bf16(v0[0], v0[1]); w.y = pack_bf16(v0[2], v0[3]); w.z = pack_bf16(v1[0], v1[1]); w.w = pack_bf16(v1[2], v1[3]);
;                         *(u32x4*)(ho + ro + bj * 128) = w;
;                         sq += v0[0] * v0[0] + v0[1] * v0[1] + v0[2] * v0[2] + v0[3] * v0[3] + v1[0] * v1[0] + v1[1] * v1[1] + v1[2] * v1[2] + v1[3] * v1[3];
;                     }
;                 }
;                 if (!LAST) {
;                     sq += shx(sq, 16); sq += shx(sq, 32);
;                     if (fq == 0) ss[(size_t)(row0 + ai * 128 + m * 16) * 16 + u.pn * 4 + wc] = sq;
.LBB0_428:
	v_lshl_or_b32 v164, s28, 8, v184
	v_lshl_add_u32 v168, s30, 8, v182
	v_ashrrev_i32_e32 v165, 31, v164
	v_lshlrev_b64 v[196:197], 1, v[164:165]
	v_ashrrev_i32_e32 v169, 31, v168
	v_lshl_add_u64 v[166:167], s[10:11], 0, v[196:197]
	v_lshlrev_b64 v[198:199], 11, v[168:169]
	v_lshl_add_u64 v[118:119], v[166:167], 0, v[198:199]
	global_load_dwordx4 v[186:189], v[118:119], off
	global_load_dwordx4 v[190:193], v[118:119], off offset:256
	v_or_b32_e32 v178, 16, v168
	v_ashrrev_i32_e32 v179, 31, v178
	v_or_b32_e32 v172, 32, v168
	v_lshlrev_b64 v[180:181], 11, v[178:179]
	v_ashrrev_i32_e32 v173, 31, v172
	v_or_b32_e32 v170, 48, v168
	v_lshl_add_u64 v[118:119], v[166:167], 0, v[180:181]
	v_lshlrev_b64 v[176:177], 11, v[172:173]
	v_ashrrev_i32_e32 v171, 31, v170
	global_load_dwordx4 v[150:153], v[118:119], off
	global_load_dwordx4 v[146:149], v[118:119], off offset:256
	v_lshl_add_u64 v[118:119], v[166:167], 0, v[176:177]
	v_lshlrev_b64 v[174:175], 11, v[170:171]
	global_load_dwordx4 v[142:145], v[118:119], off
	global_load_dwordx4 v[134:137], v[118:119], off offset:256
	v_lshl_add_u64 v[118:119], v[166:167], 0, v[174:175]
	global_load_dwordx4 v[126:129], v[118:119], off
	s_nop 0
	global_load_dwordx4 v[118:121], v[118:119], off offset:256
	v_lshl_add_u64 v[198:199], s[14:15], 0, v[198:199]
	v_lshl_add_u64 v[196:197], v[198:199], 0, v[196:197]
	s_lshl_b32 s28, s28, 2
	s_ashr_i32 s29, s28, 31
	s_waitcnt vmcnt(0)
	v_lshlrev_b32_e32 v200, 16, v186
	v_and_b32_e32 v201, 0xffff0000, v186
	v_lshlrev_b32_e32 v186, 16, v187
	v_and_b32_e32 v187, 0xffff0000, v187
	v_pk_add_f32 v[140:141], v[140:141], v[186:187]
	v_lshlrev_b32_e32 v186, 16, v188
	v_and_b32_e32 v187, 0xffff0000, v188
	v_lshlrev_b32_e32 v188, 16, v189
	v_and_b32_e32 v189, 0xffff0000, v189
	v_pk_add_f32 v[138:139], v[138:139], v[200:201]
	v_pk_add_f32 v[188:189], v[132:133], v[188:189]
	v_pk_add_f32 v[186:187], v[130:131], v[186:187]
	v_cvt_pk_bf16_f32 v130, v138, v139
	v_cvt_pk_bf16_f32 v131, v140, v141
	v_cvt_pk_bf16_f32 v132, v186, v187
	v_cvt_pk_bf16_f32 v133, v188, v189
	global_store_dwordx4 v[196:197], v[130:133], off
	v_mul_f32_e32 v139, v139, v139
	v_fmac_f32_e32 v139, v138, v138
	v_lshlrev_b32_e32 v130, 16, v190
	v_and_b32_e32 v131, 0xffff0000, v190
	v_lshlrev_b32_e32 v132, 16, v191
	v_and_b32_e32 v133, 0xffff0000, v191
	v_pk_add_f32 v[124:125], v[124:125], v[132:133]
	v_pk_add_f32 v[122:123], v[122:123], v[130:131]
	v_lshlrev_b32_e32 v130, 16, v192
	v_and_b32_e32 v131, 0xffff0000, v192
	v_lshlrev_b32_e32 v132, 16, v193
	v_and_b32_e32 v133, 0xffff0000, v193
	v_pk_add_f32 v[132:133], v[116:117], v[132:133]
	v_pk_add_f32 v[130:131], v[114:115], v[130:131]
	v_cvt_pk_bf16_f32 v114, v122, v123
	v_cvt_pk_bf16_f32 v115, v124, v125
	v_cvt_pk_bf16_f32 v116, v130, v131
	v_cvt_pk_bf16_f32 v117, v132, v133
	global_store_dwordx4 v[196:197], v[114:117], off offset:256
	v_fmac_f32_e32 v139, v140, v140
	v_fmac_f32_e32 v139, v141, v141
	v_mul_f32_e32 v114, v123, v123
	v_fmac_f32_e32 v114, v122, v122
	v_fmac_f32_e32 v114, v124, v124
	v_fmac_f32_e32 v114, v125, v125
	v_fmac_f32_e32 v139, v186, v186
	v_fmac_f32_e32 v114, v130, v130
	v_fmac_f32_e32 v139, v187, v187
	v_fmac_f32_e32 v114, v131, v131
	v_fmac_f32_e32 v139, v188, v188
	v_fmac_f32_e32 v114, v132, v132
	v_fmac_f32_e32 v139, v189, v189
	v_fmac_f32_e32 v114, v133, v133
	v_add_f32_e32 v114, v139, v114
	v_mov_b32_e32 v115, v114
	s_nop 1
	v_permlane16_swap_b32_e32 v115, v114
	s_waitcnt lgkmcnt(0)
	v_add_f32_e32 v114, v114, v115
	s_nop 0
	v_mov_b32_e32 v115, v114
	s_nop 1
	v_permlane32_swap_b32_e32 v115, v114
	s_and_saveexec_b64 s[30:31], s[4:5]
	v_readlane_b32 s38, v255, 31
	v_readlane_b32 s39, v255, 32
	s_cbranch_execz .LBB0_430
	v_lshlrev_b64 v[116:117], 6, v[168:169]
	v_lshl_add_u64 v[116:117], s[12:13], 0, v[116:117]
	v_lshl_add_u64 v[116:117], s[28:29], 2, v[116:117]
	s_lshl_b32 s50, s52, 2
	v_lshl_add_u64 v[116:117], v[116:117], 0, s[50:51]
	s_waitcnt lgkmcnt(0)
	v_add_f32_e32 v114, v114, v115
	global_store_dword v[116:117], v114, off
.LBB0_430:
	s_or_b64 exec, exec, s[30:31]
	v_lshlrev_b32_e32 v114, 16, v150
	s_waitcnt lgkmcnt(0)
	v_and_b32_e32 v115, 0xffff0000, v150
	v_lshlrev_b32_e32 v116, 16, v151
	v_and_b32_e32 v117, 0xffff0000, v151
	v_pk_add_f32 v[112:113], v[112:113], v[116:117]
	v_pk_add_f32 v[110:111], v[110:111], v[114:115]
	v_lshlrev_b32_e32 v114, 16, v152
	v_and_b32_e32 v115, 0xffff0000, v152
	v_lshlrev_b32_e32 v116, 16, v153
	v_and_b32_e32 v117, 0xffff0000, v153
	v_pk_add_f32 v[116:117], v[108:109], v[116:117]
	v_pk_add_f32 v[114:115], v[106:107], v[114:115]
	v_lshl_add_u64 v[122:123], s[14:15], 0, v[180:181]
	v_cvt_pk_bf16_f32 v106, v110, v111
	v_cvt_pk_bf16_f32 v107, v112, v113
	v_cvt_pk_bf16_f32 v108, v114, v115
	v_cvt_pk_bf16_f32 v109, v116, v117
	v_lshl_add_u64 v[122:123], v[164:165], 1, v[122:123]
	global_store_dwordx4 v[122:123], v[106:109], off
	v_mul_f32_e32 v111, v111, v111
	v_fmac_f32_e32 v111, v110, v110
	v_lshlrev_b32_e32 v106, 16, v146
	v_and_b32_e32 v107, 0xffff0000, v146
	v_lshlrev_b32_e32 v108, 16, v147
	v_and_b32_e32 v109, 0xffff0000, v147
	v_pk_add_f32 v[104:105], v[104:105], v[108:109]
	v_pk_add_f32 v[102:103], v[102:103], v[106:107]
	v_lshlrev_b32_e32 v106, 16, v148
	v_and_b32_e32 v107, 0xffff0000, v148
	v_lshlrev_b32_e32 v108, 16, v149
	v_and_b32_e32 v109, 0xffff0000, v149
	v_pk_add_f32 v[108:109], v[100:101], v[108:109]
	v_pk_add_f32 v[106:107], v[98:99], v[106:107]
	v_cvt_pk_bf16_f32 v98, v102, v103
	v_cvt_pk_bf16_f32 v99, v104, v105
	v_cvt_pk_bf16_f32 v100, v106, v107
	v_cvt_pk_bf16_f32 v101, v108, v109
	global_store_dwordx4 v[122:123], v[98:101], off offset:256
	v_fmac_f32_e32 v111, v112, v112
	v_fmac_f32_e32 v111, v113, v113
	v_mul_f32_e32 v98, v103, v103
	v_fmac_f32_e32 v98, v102, v102
	v_fmac_f32_e32 v98, v104, v104
	v_fmac_f32_e32 v98, v105, v105
	v_fmac_f32_e32 v111, v114, v114
	v_fmac_f32_e32 v98, v106, v106
	v_fmac_f32_e32 v111, v115, v115
	v_fmac_f32_e32 v98, v107, v107
	v_fmac_f32_e32 v111, v116, v116
	v_fmac_f32_e32 v98, v108, v108
	v_fmac_f32_e32 v111, v117, v117
	v_fmac_f32_e32 v98, v109, v109
	v_add_f32_e32 v98, v111, v98
	v_mov_b32_e32 v99, v98
	s_nop 1
	v_permlane16_swap_b32_e32 v99, v98
	s_waitcnt lgkmcnt(0)
	v_add_f32_e32 v98, v98, v99
	s_nop 0
	v_mov_b32_e32 v99, v98
	s_nop 1
	v_permlane32_swap_b32_e32 v99, v98
	s_and_saveexec_b64 s[30:31], s[4:5]
	s_cbranch_execz .LBB0_432
	v_lshlrev_b64 v[100:101], 6, v[178:179]
	v_lshl_add_u64 v[100:101], s[12:13], 0, v[100:101]
	v_lshl_add_u64 v[100:101], s[28:29], 2, v[100:101]
	s_lshl_b32 s50, s52, 2
	v_lshl_add_u64 v[100:101], v[100:101], 0, s[50:51]
	s_waitcnt lgkmcnt(0)
	v_add_f32_e32 v98, v98, v99
	global_store_dword v[100:101], v98, off
; DI unsigned pack_bf16(float lo, float hi) { f32v2 f = {lo, hi}; bf16v2 b = __builtin_convertvector(f, bf16v2); return __builtin_bit_cast(unsigned, b); }
; DI float bf_lo(unsigned u) { return __uint_as_float(u << 16); }
; DI float bf_hi(unsigned u) { return __uint_as_float(u & 0xffff0000u); }
; DI float shx(float v, int o) { int l = (int)__builtin_amdgcn_mbcnt_hi(~0u, __builtin_amdgcn_mbcnt_lo(~0u, 0u)); asm volatile("" : "+v"(l)); return __int_as_float(__builtin_amdgcn_ds_bpermute((l ^ o) << 2, __float_as_int(v))); }
;     DI void operator()(const f32x4 (&acc)[2][2][4][2], const pg8::Unit& u, int wr, int wc, int fr, int fq, int) const {
;     ...
;             for (int m = 0; m < 4; ++m) { const size_t ro = (size_t)(row0 + ai * 128 + m * 16) * D + col0;
; #pragma unroll
;                 for (int bj = 0; bj < 2; ++bj) r[m][bj] = *(const u32x4*)(hb + ro + bj * 128); }
;             asm volatile("" ::: "memory");
; #pragma unroll
;             for (int m = 0; m < 4; ++m) { const size_t ro = (size_t)(row0 + ai * 128 + m * 16) * D + col0;
;                 float sq = 0.f;
; #pragma unroll
;                 for (int bj = 0; bj < 2; ++bj) {
;                     const u32x4 rr = r[m][bj];
;                     const f32x4 v0 = (f32x4){bf_lo(rr[0]), bf_hi(rr[0]), bf_lo(rr[1]), bf_hi(rr[1])} + acc[ai][bj][m][0];
;                     const f32x4 v1 = (f32x4){bf_lo(rr[2]), bf_hi(rr[2]), bf_lo(rr[3]), bf_hi(rr[3])} + acc[ai][bj][m][1];
;                     if (LAST) { *(f32x4*)(out + ro + bj * 128) = v0; *(f32x4*)(out + ro + bj * 128 + 4) = v1; }
;                     else {
;                         u32x4 w; w.x = pack_bf16(v0[0], v0[1]); w.y = pack_bf16(v0[2], v0[3]); w.z = pack_bf16(v1[0], v1[1]); w.w = pack_bf16(v1[2], v1[3]);
;                         *(u32x4*)(ho + ro + bj * 128) = w;
;                         sq += v0[0] * v0[0] + v0[1] * v0[1] + v0[2] * v0[2] + v0[3] * v0[3] + v1[0] * v1[0] + v1[1] * v1[1] + v1[2] * v1[2] + v1[3] * v1[3];
;                     }
;                 }
;                 if (!LAST) {
;                     sq += shx(sq, 16); sq += shx(sq, 32);
;                     if (fq == 0) ss[(size_t)(row0 + ai * 128 + m * 16) * 16 + u.pn * 4 + wc] = sq;
.LBB0_432:
	s_or_b64 exec, exec, s[30:31]
	v_lshlrev_b32_e32 v98, 16, v142
	s_waitcnt lgkmcnt(0)
	v_and_b32_e32 v99, 0xffff0000, v142
	v_lshlrev_b32_e32 v100, 16, v143
	v_and_b32_e32 v101, 0xffff0000, v143
	v_pk_add_f32 v[96:97], v[96:97], v[100:101]
	v_pk_add_f32 v[94:95], v[94:95], v[98:99]
	v_lshlrev_b32_e32 v98, 16, v144
	v_and_b32_e32 v99, 0xffff0000, v144
	v_lshlrev_b32_e32 v100, 16, v145
	v_and_b32_e32 v101, 0xffff0000, v145
	v_pk_add_f32 v[100:101], v[92:93], v[100:101]
	v_pk_add_f32 v[98:99], v[90:91], v[98:99]
	v_lshl_add_u64 v[102:103], s[14:15], 0, v[176:177]
	v_cvt_pk_bf16_f32 v90, v94, v95
	v_cvt_pk_bf16_f32 v91, v96, v97
	v_cvt_pk_bf16_f32 v92, v98, v99
	v_cvt_pk_bf16_f32 v93, v100, v101
	v_lshl_add_u64 v[102:103], v[164:165], 1, v[102:103]
	global_store_dwordx4 v[102:103], v[90:93], off
	v_mul_f32_e32 v95, v95, v95
	v_fmac_f32_e32 v95, v94, v94
	v_lshlrev_b32_e32 v90, 16, v134
	v_and_b32_e32 v91, 0xffff0000, v134
	v_lshlrev_b32_e32 v92, 16, v135
	v_and_b32_e32 v93, 0xffff0000, v135
	v_pk_add_f32 v[88:89], v[88:89], v[92:93]
	v_pk_add_f32 v[86:87], v[86:87], v[90:91]
	v_lshlrev_b32_e32 v90, 16, v136
	v_and_b32_e32 v91, 0xffff0000, v136
	v_lshlrev_b32_e32 v92, 16, v137
	v_and_b32_e32 v93, 0xffff0000, v137
	v_pk_add_f32 v[92:93], v[84:85], v[92:93]
	v_pk_add_f32 v[90:91], v[82:83], v[90:91]
	v_cvt_pk_bf16_f32 v82, v86, v87
	v_cvt_pk_bf16_f32 v83, v88, v89
	v_cvt_pk_bf16_f32 v84, v90, v91
	v_cvt_pk_bf16_f32 v85, v92, v93
	global_store_dwordx4 v[102:103], v[82:85], off offset:256
	v_fmac_f32_e32 v95, v96, v96
	v_fmac_f32_e32 v95, v97, v97
	v_mul_f32_e32 v82, v87, v87
	v_fmac_f32_e32 v82, v86, v86
	v_fmac_f32_e32 v82, v88, v88
	v_fmac_f32_e32 v82, v89, v89
	v_fmac_f32_e32 v95, v98, v98
	v_fmac_f32_e32 v82, v90, v90
	v_fmac_f32_e32 v95, v99, v99
	v_fmac_f32_e32 v82, v91, v91
	v_fmac_f32_e32 v95, v100, v100
	v_fmac_f32_e32 v82, v92, v92
	v_fmac_f32_e32 v95, v101, v101
	v_fmac_f32_e32 v82, v93, v93
	v_add_f32_e32 v82, v95, v82
	v_mov_b32_e32 v83, v82
	s_nop 1
	v_permlane16_swap_b32_e32 v83, v82
	s_waitcnt lgkmcnt(0)
	v_add_f32_e32 v82, v82, v83
	s_nop 0
	v_mov_b32_e32 v83, v82
	s_nop 1
	v_permlane32_swap_b32_e32 v83, v82
	s_and_saveexec_b64 s[30:31], s[4:5]
	s_cbranch_execz .LBB0_434
	v_lshlrev_b64 v[84:85], 6, v[172:173]
	v_lshl_add_u64 v[84:85], s[12:13], 0, v[84:85]
	v_lshl_add_u64 v[84:85], s[28:29], 2, v[84:85]
	s_lshl_b32 s50, s52, 2
	v_lshl_add_u64 v[84:85], v[84:85], 0, s[50:51]
	s_waitcnt lgkmcnt(0)
	v_add_f32_e32 v82, v82, v83
	global_store_dword v[84:85], v82, off
.LBB0_434:
	s_or_b64 exec, exec, s[30:31]
	v_lshlrev_b32_e32 v82, 16, v126
	s_waitcnt lgkmcnt(0)
	v_and_b32_e32 v83, 0xffff0000, v126
	v_lshlrev_b32_e32 v84, 16, v127
	v_and_b32_e32 v85, 0xffff0000, v127
	v_pk_add_f32 v[80:81], v[80:81], v[84:85]
	v_pk_add_f32 v[78:79], v[78:79], v[82:83]
	v_lshlrev_b32_e32 v82, 16, v128
	v_and_b32_e32 v83, 0xffff0000, v128
	v_lshlrev_b32_e32 v84, 16, v129
	v_and_b32_e32 v85, 0xffff0000, v129
	v_pk_add_f32 v[84:85], v[76:77], v[84:85]
	v_pk_add_f32 v[82:83], v[74:75], v[82:83]
	v_lshl_add_u64 v[86:87], s[14:15], 0, v[174:175]
	v_cvt_pk_bf16_f32 v74, v78, v79
	v_cvt_pk_bf16_f32 v75, v80, v81
	v_cvt_pk_bf16_f32 v76, v82, v83
	v_cvt_pk_bf16_f32 v77, v84, v85
	v_lshl_add_u64 v[86:87], v[164:165], 1, v[86:87]
	global_store_dwordx4 v[86:87], v[74:77], off
	v_mul_f32_e32 v79, v79, v79
	v_fmac_f32_e32 v79, v78, v78
	v_lshlrev_b32_e32 v74, 16, v118
	v_and_b32_e32 v75, 0xffff0000, v118
	v_lshlrev_b32_e32 v76, 16, v119
	v_and_b32_e32 v77, 0xffff0000, v119
	v_pk_add_f32 v[72:73], v[72:73], v[76:77]
	v_pk_add_f32 v[70:71], v[70:71], v[74:75]
	v_lshlrev_b32_e32 v74, 16, v120
	v_and_b32_e32 v75, 0xffff0000, v120
	v_lshlrev_b32_e32 v76, 16, v121
	v_and_b32_e32 v77, 0xffff0000, v121
	v_pk_add_f32 v[76:77], v[68:69], v[76:77]
	v_pk_add_f32 v[74:75], v[66:67], v[74:75]
	v_cvt_pk_bf16_f32 v66, v70, v71
	v_cvt_pk_bf16_f32 v67, v72, v73
	v_cvt_pk_bf16_f32 v68, v74, v75
	v_cvt_pk_bf16_f32 v69, v76, v77
	global_store_dwordx4 v[86:87], v[66:69], off offset:256
	v_fmac_f32_e32 v79, v80, v80
	v_fmac_f32_e32 v79, v81, v81
	v_mul_f32_e32 v66, v71, v71
	v_fmac_f32_e32 v66, v70, v70
	v_fmac_f32_e32 v66, v72, v72
	v_fmac_f32_e32 v66, v73, v73
	v_fmac_f32_e32 v79, v82, v82
	v_fmac_f32_e32 v66, v74, v74
	v_fmac_f32_e32 v79, v83, v83
	v_fmac_f32_e32 v66, v75, v75
	v_fmac_f32_e32 v79, v84, v84
	v_fmac_f32_e32 v66, v76, v76
	v_fmac_f32_e32 v79, v85, v85
	v_fmac_f32_e32 v66, v77, v77
	v_add_f32_e32 v66, v79, v66
	v_mov_b32_e32 v67, v66
	s_nop 1
	v_permlane16_swap_b32_e32 v67, v66
	s_waitcnt lgkmcnt(0)
	v_add_f32_e32 v66, v66, v67
	s_nop 0
	v_mov_b32_e32 v67, v66
	s_nop 1
	v_permlane32_swap_b32_e32 v67, v66
	s_and_saveexec_b64 s[30:31], s[4:5]
	s_cbranch_execz .LBB0_436
	v_lshlrev_b64 v[68:69], 6, v[170:171]
	v_lshl_add_u64 v[68:69], s[12:13], 0, v[68:69]
	v_lshl_add_u64 v[68:69], s[28:29], 2, v[68:69]
	s_lshl_b32 s50, s52, 2
	v_lshl_add_u64 v[68:69], v[68:69], 0, s[50:51]
	s_waitcnt lgkmcnt(0)
	v_add_f32_e32 v66, v66, v67
	global_store_dword v[68:69], v66, off
; DI unsigned pack_bf16(float lo, float hi) { f32v2 f = {lo, hi}; bf16v2 b = __builtin_convertvector(f, bf16v2); return __builtin_bit_cast(unsigned, b); }
; DI float bf_lo(unsigned u) { return __uint_as_float(u << 16); }
; DI float bf_hi(unsigned u) { return __uint_as_float(u & 0xffff0000u); }
; DI float shx(float v, int o) { int l = (int)__builtin_amdgcn_mbcnt_hi(~0u, __builtin_amdgcn_mbcnt_lo(~0u, 0u)); asm volatile("" : "+v"(l)); return __int_as_float(__builtin_amdgcn_ds_bpermute((l ^ o) << 2, __float_as_int(v))); }
;     DI void operator()(const f32x4 (&acc)[2][2][4][2], const pg8::Unit& u, int wr, int wc, int fr, int fq, int) const {
;     ...
;             for (int m = 0; m < 4; ++m) { const size_t ro = (size_t)(row0 + ai * 128 + m * 16) * D + col0;
; #pragma unroll
;                 for (int bj = 0; bj < 2; ++bj) r[m][bj] = *(const u32x4*)(hb + ro + bj * 128); }
;             asm volatile("" ::: "memory");
; #pragma unroll
;             for (int m = 0; m < 4; ++m) { const size_t ro = (size_t)(row0 + ai * 128 + m * 16) * D + col0;
;                 float sq = 0.f;
; #pragma unroll
;                 for (int bj = 0; bj < 2; ++bj) {
;                     const u32x4 rr = r[m][bj];
;                     const f32x4 v0 = (f32x4){bf_lo(rr[0]), bf_hi(rr[0]), bf_lo(rr[1]), bf_hi(rr[1])} + acc[ai][bj][m][0];
;                     const f32x4 v1 = (f32x4){bf_lo(rr[2]), bf_hi(rr[2]), bf_lo(rr[3]), bf_hi(rr[3])} + acc[ai][bj][m][1];
;                     if (LAST) { *(f32x4*)(out + ro + bj * 128) = v0; *(f32x4*)(out + ro + bj * 128 + 4) = v1; }
;                     else {
;                         u32x4 w; w.x = pack_bf16(v0[0], v0[1]); w.y = pack_bf16(v0[2], v0[3]); w.z = pack_bf16(v1[0], v1[1]); w.w = pack_bf16(v1[2], v1[3]);
;                         *(u32x4*)(ho + ro + bj * 128) = w;
;                         sq += v0[0] * v0[0] + v0[1] * v0[1] + v0[2] * v0[2] + v0[3] * v0[3] + v1[0] * v1[0] + v1[1] * v1[1] + v1[2] * v1[2] + v1[3] * v1[3];
;                     }
;                 }
;                 if (!LAST) {
;                     sq += shx(sq, 16); sq += shx(sq, 32);
;                     if (fq == 0) ss[(size_t)(row0 + ai * 128 + m * 16) * 16 + u.pn * 4 + wc] = sq;
.LBB0_436:
	s_or_b64 exec, exec, s[30:31]
	v_add_u32_e32 v102, 0x80, v168
	v_ashrrev_i32_e32 v103, 31, v102
	v_lshlrev_b64 v[112:113], 11, v[102:103]
	s_waitcnt lgkmcnt(0)
	v_lshl_add_u64 v[66:67], v[166:167], 0, v[112:113]
	global_load_dwordx4 v[104:107], v[66:67], off
	global_load_dwordx4 v[108:111], v[66:67], off offset:256
	v_add_u32_e32 v98, 0x90, v168
	v_ashrrev_i32_e32 v99, 31, v98
	v_add_u32_e32 v92, 0xa0, v168
	v_lshlrev_b64 v[100:101], 11, v[98:99]
	v_ashrrev_i32_e32 v93, 31, v92
	v_add_u32_e32 v90, 0xb0, v168
	v_lshl_add_u64 v[66:67], v[166:167], 0, v[100:101]
	v_lshlrev_b64 v[96:97], 11, v[92:93]
	v_ashrrev_i32_e32 v91, 31, v90
	global_load_dwordx4 v[86:89], v[66:67], off
	global_load_dwordx4 v[82:85], v[66:67], off offset:256
	v_lshl_add_u64 v[66:67], v[166:167], 0, v[96:97]
	v_lshlrev_b64 v[94:95], 11, v[90:91]
	global_load_dwordx4 v[78:81], v[66:67], off
	global_load_dwordx4 v[74:77], v[66:67], off offset:256
	v_lshl_add_u64 v[66:67], v[166:167], 0, v[94:95]
	global_load_dwordx4 v[70:73], v[66:67], off
	s_nop 0
	global_load_dwordx4 v[66:69], v[66:67], off offset:256
	v_lshl_add_u64 v[112:113], s[14:15], 0, v[112:113]
	v_lshl_add_u64 v[112:113], v[164:165], 1, v[112:113]
	s_waitcnt vmcnt(7)
	v_lshlrev_b32_e32 v114, 16, v104
	v_and_b32_e32 v115, 0xffff0000, v104
	v_lshlrev_b32_e32 v104, 16, v105
	v_and_b32_e32 v105, 0xffff0000, v105
	v_pk_add_f32 v[64:65], v[64:65], v[104:105]
	v_lshlrev_b32_e32 v104, 16, v106
	v_and_b32_e32 v105, 0xffff0000, v106
	v_lshlrev_b32_e32 v106, 16, v107
	v_and_b32_e32 v107, 0xffff0000, v107
	v_pk_add_f32 v[62:63], v[62:63], v[114:115]
	v_pk_add_f32 v[106:107], v[60:61], v[106:107]
	v_pk_add_f32 v[104:105], v[58:59], v[104:105]
	v_cvt_pk_bf16_f32 v58, v62, v63
	v_cvt_pk_bf16_f32 v59, v64, v65
	v_cvt_pk_bf16_f32 v60, v104, v105
	v_cvt_pk_bf16_f32 v61, v106, v107
	global_store_dwordx4 v[112:113], v[58:61], off
	v_mul_f32_e32 v63, v63, v63
	v_fmac_f32_e32 v63, v62, v62
	s_waitcnt vmcnt(7)
	v_lshlrev_b32_e32 v58, 16, v108
	v_and_b32_e32 v59, 0xffff0000, v108
	v_lshlrev_b32_e32 v60, 16, v109
	v_and_b32_e32 v61, 0xffff0000, v109
	v_pk_add_f32 v[56:57], v[56:57], v[60:61]
	v_pk_add_f32 v[54:55], v[54:55], v[58:59]
	v_lshlrev_b32_e32 v58, 16, v110
	v_and_b32_e32 v59, 0xffff0000, v110
	v_lshlrev_b32_e32 v60, 16, v111
	v_and_b32_e32 v61, 0xffff0000, v111
	v_pk_add_f32 v[60:61], v[52:53], v[60:61]
	v_pk_add_f32 v[58:59], v[50:51], v[58:59]
	v_cvt_pk_bf16_f32 v50, v54, v55
	v_cvt_pk_bf16_f32 v51, v56, v57
	v_cvt_pk_bf16_f32 v52, v58, v59
	v_cvt_pk_bf16_f32 v53, v60, v61
	global_store_dwordx4 v[112:113], v[50:53], off offset:256
	v_fmac_f32_e32 v63, v64, v64
	v_fmac_f32_e32 v63, v65, v65
	v_mul_f32_e32 v50, v55, v55
	v_fmac_f32_e32 v50, v54, v54
	v_fmac_f32_e32 v50, v56, v56
	v_fmac_f32_e32 v50, v57, v57
	v_fmac_f32_e32 v63, v104, v104
	v_fmac_f32_e32 v50, v58, v58
	v_fmac_f32_e32 v63, v105, v105
	v_fmac_f32_e32 v50, v59, v59
	v_fmac_f32_e32 v63, v106, v106
	v_fmac_f32_e32 v50, v60, v60
	v_fmac_f32_e32 v63, v107, v107
	v_fmac_f32_e32 v50, v61, v61
	v_add_f32_e32 v50, v63, v50
	v_mov_b32_e32 v51, v50
	s_nop 1
	v_permlane16_swap_b32_e32 v51, v50
	s_waitcnt lgkmcnt(0)
	v_add_f32_e32 v50, v50, v51
	s_nop 0
	v_mov_b32_e32 v51, v50
	s_nop 1
	v_permlane32_swap_b32_e32 v51, v50
	s_and_saveexec_b64 s[30:31], s[4:5]
	s_cbranch_execz .LBB0_438
	v_lshlrev_b64 v[52:53], 6, v[102:103]
	v_lshl_add_u64 v[52:53], s[12:13], 0, v[52:53]
	v_lshl_add_u64 v[52:53], s[28:29], 2, v[52:53]
	s_lshl_b32 s50, s52, 2
	v_lshl_add_u64 v[52:53], v[52:53], 0, s[50:51]
	s_waitcnt lgkmcnt(0)
	v_add_f32_e32 v50, v50, v51
	global_store_dword v[52:53], v50, off
.LBB0_438:
	s_or_b64 exec, exec, s[30:31]
	s_waitcnt vmcnt(7)
	v_lshlrev_b32_e32 v50, 16, v86
	s_waitcnt lgkmcnt(0)
	v_and_b32_e32 v51, 0xffff0000, v86
	v_lshlrev_b32_e32 v52, 16, v87
	v_and_b32_e32 v53, 0xffff0000, v87
	v_pk_add_f32 v[48:49], v[48:49], v[52:53]
	v_pk_add_f32 v[46:47], v[46:47], v[50:51]
	v_lshlrev_b32_e32 v50, 16, v88
	v_and_b32_e32 v51, 0xffff0000, v88
	v_lshlrev_b32_e32 v52, 16, v89
	v_and_b32_e32 v53, 0xffff0000, v89
	v_pk_add_f32 v[52:53], v[44:45], v[52:53]
	v_pk_add_f32 v[50:51], v[42:43], v[50:51]
	v_lshl_add_u64 v[54:55], s[14:15], 0, v[100:101]
	v_cvt_pk_bf16_f32 v42, v46, v47
	v_cvt_pk_bf16_f32 v43, v48, v49
	v_cvt_pk_bf16_f32 v44, v50, v51
	v_cvt_pk_bf16_f32 v45, v52, v53
	v_lshl_add_u64 v[54:55], v[164:165], 1, v[54:55]
	global_store_dwordx4 v[54:55], v[42:45], off
	v_mul_f32_e32 v47, v47, v47
	v_fmac_f32_e32 v47, v46, v46
	s_waitcnt vmcnt(7)
	v_lshlrev_b32_e32 v42, 16, v82
	v_and_b32_e32 v43, 0xffff0000, v82
	v_lshlrev_b32_e32 v44, 16, v83
	v_and_b32_e32 v45, 0xffff0000, v83
	v_pk_add_f32 v[40:41], v[40:41], v[44:45]
	v_pk_add_f32 v[38:39], v[38:39], v[42:43]
	v_lshlrev_b32_e32 v42, 16, v84
	v_and_b32_e32 v43, 0xffff0000, v84
	v_lshlrev_b32_e32 v44, 16, v85
	v_and_b32_e32 v45, 0xffff0000, v85
	v_pk_add_f32 v[44:45], v[36:37], v[44:45]
	v_pk_add_f32 v[42:43], v[34:35], v[42:43]
	v_cvt_pk_bf16_f32 v34, v38, v39
	v_cvt_pk_bf16_f32 v35, v40, v41
	v_cvt_pk_bf16_f32 v36, v42, v43
	v_cvt_pk_bf16_f32 v37, v44, v45
	global_store_dwordx4 v[54:55], v[34:37], off offset:256
	v_fmac_f32_e32 v47, v48, v48
	v_fmac_f32_e32 v47, v49, v49
	v_mul_f32_e32 v34, v39, v39
	v_fmac_f32_e32 v34, v38, v38
	v_fmac_f32_e32 v34, v40, v40
	v_fmac_f32_e32 v34, v41, v41
	v_fmac_f32_e32 v47, v50, v50
	v_fmac_f32_e32 v34, v42, v42
	v_fmac_f32_e32 v47, v51, v51
	v_fmac_f32_e32 v34, v43, v43
	v_fmac_f32_e32 v47, v52, v52
	v_fmac_f32_e32 v34, v44, v44
	v_fmac_f32_e32 v47, v53, v53
	v_fmac_f32_e32 v34, v45, v45
	v_add_f32_e32 v34, v47, v34
	v_mov_b32_e32 v35, v34
	s_nop 1
	v_permlane16_swap_b32_e32 v35, v34
	s_waitcnt lgkmcnt(0)
	v_add_f32_e32 v34, v34, v35
	s_nop 0
	v_mov_b32_e32 v35, v34
	s_nop 1
	v_permlane32_swap_b32_e32 v35, v34
	s_and_saveexec_b64 s[30:31], s[4:5]
	s_cbranch_execz .LBB0_440
	v_lshlrev_b64 v[36:37], 6, v[98:99]
	v_lshl_add_u64 v[36:37], s[12:13], 0, v[36:37]
	v_lshl_add_u64 v[36:37], s[28:29], 2, v[36:37]
	s_lshl_b32 s50, s52, 2
	v_lshl_add_u64 v[36:37], v[36:37], 0, s[50:51]
	s_waitcnt lgkmcnt(0)
	v_add_f32_e32 v34, v34, v35
	global_store_dword v[36:37], v34, off
; DI unsigned pack_bf16(float lo, float hi) { f32v2 f = {lo, hi}; bf16v2 b = __builtin_convertvector(f, bf16v2); return __builtin_bit_cast(unsigned, b); }
; DI float bf_lo(unsigned u) { return __uint_as_float(u << 16); }
; DI float bf_hi(unsigned u) { return __uint_as_float(u & 0xffff0000u); }
; DI float shx(float v, int o) { int l = (int)__builtin_amdgcn_mbcnt_hi(~0u, __builtin_amdgcn_mbcnt_lo(~0u, 0u)); asm volatile("" : "+v"(l)); return __int_as_float(__builtin_amdgcn_ds_bpermute((l ^ o) << 2, __float_as_int(v))); }
;     DI void operator()(const f32x4 (&acc)[2][2][4][2], const pg8::Unit& u, int wr, int wc, int fr, int fq, int) const {
;     ...
;             for (int m = 0; m < 4; ++m) { const size_t ro = (size_t)(row0 + ai * 128 + m * 16) * D + col0;
; #pragma unroll
;                 for (int bj = 0; bj < 2; ++bj) r[m][bj] = *(const u32x4*)(hb + ro + bj * 128); }
;             asm volatile("" ::: "memory");
; #pragma unroll
;             for (int m = 0; m < 4; ++m) { const size_t ro = (size_t)(row0 + ai * 128 + m * 16) * D + col0;
;                 float sq = 0.f;
; #pragma unroll
;                 for (int bj = 0; bj < 2; ++bj) {
;                     const u32x4 rr = r[m][bj];
;                     const f32x4 v0 = (f32x4){bf_lo(rr[0]), bf_hi(rr[0]), bf_lo(rr[1]), bf_hi(rr[1])} + acc[ai][bj][m][0];
;                     const f32x4 v1 = (f32x4){bf_lo(rr[2]), bf_hi(rr[2]), bf_lo(rr[3]), bf_hi(rr[3])} + acc[ai][bj][m][1];
;                     if (LAST) { *(f32x4*)(out + ro + bj * 128) = v0; *(f32x4*)(out + ro + bj * 128 + 4) = v1; }
;                     else {
;                         u32x4 w; w.x = pack_bf16(v0[0], v0[1]); w.y = pack_bf16(v0[2], v0[3]); w.z = pack_bf16(v1[0], v1[1]); w.w = pack_bf16(v1[2], v1[3]);
;                         *(u32x4*)(ho + ro + bj * 128) = w;
;                         sq += v0[0] * v0[0] + v0[1] * v0[1] + v0[2] * v0[2] + v0[3] * v0[3] + v1[0] * v1[0] + v1[1] * v1[1] + v1[2] * v1[2] + v1[3] * v1[3];
;                     }
;                 }
;                 if (!LAST) {
;                     sq += shx(sq, 16); sq += shx(sq, 32);
;                     if (fq == 0) ss[(size_t)(row0 + ai * 128 + m * 16) * 16 + u.pn * 4 + wc] = sq;
.LBB0_440:
	s_or_b64 exec, exec, s[30:31]
	s_waitcnt vmcnt(7)
	v_lshlrev_b32_e32 v34, 16, v78
	s_waitcnt lgkmcnt(0)
	v_and_b32_e32 v35, 0xffff0000, v78
	v_lshlrev_b32_e32 v36, 16, v79
	v_and_b32_e32 v37, 0xffff0000, v79
	v_pk_add_f32 v[32:33], v[32:33], v[36:37]
	v_pk_add_f32 v[30:31], v[30:31], v[34:35]
	v_lshlrev_b32_e32 v34, 16, v80
	v_and_b32_e32 v35, 0xffff0000, v80
	v_lshlrev_b32_e32 v36, 16, v81
	v_and_b32_e32 v37, 0xffff0000, v81
	v_pk_add_f32 v[36:37], v[28:29], v[36:37]
	v_pk_add_f32 v[34:35], v[26:27], v[34:35]
	v_lshl_add_u64 v[38:39], s[14:15], 0, v[96:97]
	v_cvt_pk_bf16_f32 v26, v30, v31
	v_cvt_pk_bf16_f32 v27, v32, v33
	v_cvt_pk_bf16_f32 v28, v34, v35
	v_cvt_pk_bf16_f32 v29, v36, v37
	v_lshl_add_u64 v[38:39], v[164:165], 1, v[38:39]
	global_store_dwordx4 v[38:39], v[26:29], off
	v_mul_f32_e32 v31, v31, v31
	v_fmac_f32_e32 v31, v30, v30
	s_waitcnt vmcnt(7)
	v_lshlrev_b32_e32 v26, 16, v74
	v_and_b32_e32 v27, 0xffff0000, v74
	v_lshlrev_b32_e32 v28, 16, v75
	v_and_b32_e32 v29, 0xffff0000, v75
	v_pk_add_f32 v[24:25], v[24:25], v[28:29]
	v_pk_add_f32 v[22:23], v[22:23], v[26:27]
	v_lshlrev_b32_e32 v26, 16, v76
	v_and_b32_e32 v27, 0xffff0000, v76
	v_lshlrev_b32_e32 v28, 16, v77
	v_and_b32_e32 v29, 0xffff0000, v77
	v_pk_add_f32 v[28:29], v[20:21], v[28:29]
	v_pk_add_f32 v[26:27], v[18:19], v[26:27]
	v_cvt_pk_bf16_f32 v18, v22, v23
	v_cvt_pk_bf16_f32 v19, v24, v25
	v_cvt_pk_bf16_f32 v20, v26, v27
	v_cvt_pk_bf16_f32 v21, v28, v29
	global_store_dwordx4 v[38:39], v[18:21], off offset:256
	v_fmac_f32_e32 v31, v32, v32
	v_fmac_f32_e32 v31, v33, v33
	v_mul_f32_e32 v18, v23, v23
	v_fmac_f32_e32 v18, v22, v22
	v_fmac_f32_e32 v18, v24, v24
	v_fmac_f32_e32 v18, v25, v25
	v_fmac_f32_e32 v31, v34, v34
	v_fmac_f32_e32 v18, v26, v26
	v_fmac_f32_e32 v31, v35, v35
	v_fmac_f32_e32 v18, v27, v27
	v_fmac_f32_e32 v31, v36, v36
	v_fmac_f32_e32 v18, v28, v28
	v_fmac_f32_e32 v31, v37, v37
	v_fmac_f32_e32 v18, v29, v29
	v_add_f32_e32 v18, v31, v18
	v_mov_b32_e32 v19, v18
	s_nop 1
	v_permlane16_swap_b32_e32 v19, v18
	s_waitcnt lgkmcnt(0)
	v_add_f32_e32 v18, v18, v19
	s_nop 0
	v_mov_b32_e32 v19, v18
	s_nop 1
	v_permlane32_swap_b32_e32 v19, v18
	s_and_saveexec_b64 s[30:31], s[4:5]
	s_cbranch_execz .LBB0_442
	v_lshlrev_b64 v[20:21], 6, v[92:93]
	v_lshl_add_u64 v[20:21], s[12:13], 0, v[20:21]
	v_lshl_add_u64 v[20:21], s[28:29], 2, v[20:21]
	s_lshl_b32 s50, s52, 2
	v_lshl_add_u64 v[20:21], v[20:21], 0, s[50:51]
	s_waitcnt lgkmcnt(0)
	v_add_f32_e32 v18, v18, v19
	global_store_dword v[20:21], v18, off
.LBB0_442:
	s_or_b64 exec, exec, s[30:31]
	s_waitcnt vmcnt(7)
	v_lshlrev_b32_e32 v18, 16, v70
	s_waitcnt lgkmcnt(0)
	v_and_b32_e32 v19, 0xffff0000, v70
	v_lshlrev_b32_e32 v20, 16, v71
	v_and_b32_e32 v21, 0xffff0000, v71
	v_pk_add_f32 v[16:17], v[16:17], v[20:21]
	v_pk_add_f32 v[14:15], v[14:15], v[18:19]
	v_lshlrev_b32_e32 v18, 16, v72
	v_and_b32_e32 v19, 0xffff0000, v72
	v_lshlrev_b32_e32 v20, 16, v73
	v_and_b32_e32 v21, 0xffff0000, v73
	v_pk_add_f32 v[20:21], v[12:13], v[20:21]
	v_pk_add_f32 v[18:19], v[10:11], v[18:19]
	v_lshl_add_u64 v[22:23], s[14:15], 0, v[94:95]
	v_cvt_pk_bf16_f32 v10, v14, v15
	v_cvt_pk_bf16_f32 v11, v16, v17
	v_cvt_pk_bf16_f32 v12, v18, v19
	v_cvt_pk_bf16_f32 v13, v20, v21
	v_lshl_add_u64 v[22:23], v[164:165], 1, v[22:23]
	global_store_dwordx4 v[22:23], v[10:13], off
	v_mul_f32_e32 v15, v15, v15
	v_fmac_f32_e32 v15, v14, v14
	s_waitcnt vmcnt(7)
	v_lshlrev_b32_e32 v10, 16, v66
	v_and_b32_e32 v11, 0xffff0000, v66
	v_lshlrev_b32_e32 v12, 16, v67
	v_and_b32_e32 v13, 0xffff0000, v67
	v_pk_add_f32 v[8:9], v[8:9], v[12:13]
	v_pk_add_f32 v[6:7], v[6:7], v[10:11]
	v_lshlrev_b32_e32 v10, 16, v68
	v_and_b32_e32 v11, 0xffff0000, v68
	v_lshlrev_b32_e32 v12, 16, v69
	v_and_b32_e32 v13, 0xffff0000, v69
	v_pk_add_f32 v[12:13], v[4:5], v[12:13]
	v_pk_add_f32 v[10:11], v[2:3], v[10:11]
	v_cvt_pk_bf16_f32 v2, v6, v7
	v_cvt_pk_bf16_f32 v3, v8, v9
	v_cvt_pk_bf16_f32 v4, v10, v11
	v_cvt_pk_bf16_f32 v5, v12, v13
	global_store_dwordx4 v[22:23], v[2:5], off offset:256
	v_fmac_f32_e32 v15, v16, v16
	v_fmac_f32_e32 v15, v17, v17
	v_mul_f32_e32 v2, v7, v7
	v_fmac_f32_e32 v2, v6, v6
	v_fmac_f32_e32 v2, v8, v8
	v_fmac_f32_e32 v2, v9, v9
	v_fmac_f32_e32 v15, v18, v18
	v_fmac_f32_e32 v2, v10, v10
	v_fmac_f32_e32 v15, v19, v19
	v_fmac_f32_e32 v2, v11, v11
	v_fmac_f32_e32 v15, v20, v20
	v_fmac_f32_e32 v2, v12, v12
	v_fmac_f32_e32 v15, v21, v21
	v_fmac_f32_e32 v2, v13, v13
	v_add_f32_e32 v2, v15, v2
	v_mov_b32_e32 v3, v2
	s_nop 1
	v_permlane16_swap_b32_e32 v3, v2
	s_waitcnt lgkmcnt(0)
	v_add_f32_e32 v2, v2, v3
	s_nop 0
	v_mov_b32_e32 v3, v2
	s_nop 1
	v_permlane32_swap_b32_e32 v3, v2
	s_and_saveexec_b64 s[30:31], s[4:5]
	s_cbranch_execz .LBB0_444
	v_lshlrev_b64 v[4:5], 6, v[90:91]
	v_lshl_add_u64 v[4:5], s[12:13], 0, v[4:5]
	v_lshl_add_u64 v[4:5], s[28:29], 2, v[4:5]
	s_lshl_b32 s50, s52, 2
	v_lshl_add_u64 v[4:5], v[4:5], 0, s[50:51]
	s_waitcnt lgkmcnt(0)
	v_add_f32_e32 v2, v2, v3
	global_store_dword v[4:5], v2, off

; DI unsigned pack_bf16(float lo, float hi) { f32v2 f = {lo, hi}; bf16v2 b = __builtin_convertvector(f, bf16v2); return __builtin_bit_cast(unsigned, b); }
; DI float bf_lo(unsigned u) { return __uint_as_float(u << 16); }
; DI float bf_hi(unsigned u) { return __uint_as_float(u & 0xffff0000u); }
; DI float shx(float v, int o) { int l = (int)__builtin_amdgcn_mbcnt_hi(~0u, __builtin_amdgcn_mbcnt_lo(~0u, 0u)); asm volatile("" : "+v"(l)); return __int_as_float(__builtin_amdgcn_ds_bpermute((l ^ o) << 2, __float_as_int(v))); }
;     DI void operator()(const f32x4 (&acc)[2][2][4][2], const pg8::Unit& u, int wr, int wc, int fr, int fq, int) const {
;     ...
;             for (int m = 0; m < 4; ++m) { const size_t ro = (size_t)(row0 + ai * 128 + m * 16) * D + col0;
; #pragma unroll
;                 for (int bj = 0; bj < 2; ++bj) r[m][bj] = *(const u32x4*)(hb + ro + bj * 128); }
;             asm volatile("" ::: "memory");
; #pragma unroll
;             for (int m = 0; m < 4; ++m) { const size_t ro = (size_t)(row0 + ai * 128 + m * 16) * D + col0;
;                 float sq = 0.f;
; #pragma unroll
;                 for (int bj = 0; bj < 2; ++bj) {
;                     const u32x4 rr = r[m][bj];
;                     const f32x4 v0 = (f32x4){bf_lo(rr[0]), bf_hi(rr[0]), bf_lo(rr[1]), bf_hi(rr[1])} + acc[ai][bj][m][0];
;                     const f32x4 v1 = (f32x4){bf_lo(rr[2]), bf_hi(rr[2]), bf_lo(rr[3]), bf_hi(rr[3])} + acc[ai][bj][m][1];
;                     if (LAST) { *(f32x4*)(out + ro + bj * 128) = v0; *(f32x4*)(out + ro + bj * 128 + 4) = v1; }
;                     else {
;                         u32x4 w; w.x = pack_bf16(v0[0], v0[1]); w.y = pack_bf16(v0[2], v0[3]); w.z = pack_bf16(v1[0], v1[1]); w.w = pack_bf16(v1[2], v1[3]);
;                         *(u32x4*)(ho + ro + bj * 128) = w;
;                         sq += v0[0] * v0[0] + v0[1] * v0[1] + v0[2] * v0[2] + v0[3] * v0[3] + v1[0] * v1[0] + v1[1] * v1[1] + v1[2] * v1[2] + v1[3] * v1[3];
;                     }
;                 }
;                 if (!LAST) {
;                     sq += shx(sq, 16); sq += shx(sq, 32);
;                     if (fq == 0) ss[(size_t)(row0 + ai * 128 + m * 16) * 16 + u.pn * 4 + wc] = sq;
.LBB0_715:
	v_lshl_or_b32 v164, s66, 8, v184
	v_lshl_add_u32 v168, s68, 8, v182
	v_ashrrev_i32_e32 v165, 31, v164
	v_lshlrev_b64 v[196:197], 1, v[164:165]
	v_ashrrev_i32_e32 v169, 31, v168
	v_lshl_add_u64 v[166:167], s[14:15], 0, v[196:197]
	v_lshlrev_b64 v[198:199], 11, v[168:169]
	v_lshl_add_u64 v[118:119], v[166:167], 0, v[198:199]
	global_load_dwordx4 v[186:189], v[118:119], off
	global_load_dwordx4 v[190:193], v[118:119], off offset:256
	v_or_b32_e32 v178, 16, v168
	v_ashrrev_i32_e32 v179, 31, v178
	v_or_b32_e32 v172, 32, v168
	v_lshlrev_b64 v[180:181], 11, v[178:179]
	v_ashrrev_i32_e32 v173, 31, v172
	v_or_b32_e32 v170, 48, v168
	v_lshl_add_u64 v[118:119], v[166:167], 0, v[180:181]
	v_lshlrev_b64 v[176:177], 11, v[172:173]
	v_ashrrev_i32_e32 v171, 31, v170
	global_load_dwordx4 v[150:153], v[118:119], off
	global_load_dwordx4 v[146:149], v[118:119], off offset:256
	v_lshl_add_u64 v[118:119], v[166:167], 0, v[176:177]
	v_lshlrev_b64 v[174:175], 11, v[170:171]
	global_load_dwordx4 v[142:145], v[118:119], off
	global_load_dwordx4 v[134:137], v[118:119], off offset:256
	v_lshl_add_u64 v[118:119], v[166:167], 0, v[174:175]
	global_load_dwordx4 v[126:129], v[118:119], off
	s_nop 0
	global_load_dwordx4 v[118:121], v[118:119], off offset:256
	v_lshl_add_u64 v[198:199], s[18:19], 0, v[198:199]
	v_lshl_add_u64 v[196:197], v[198:199], 0, v[196:197]
	s_lshl_b32 s28, s66, 2
	s_ashr_i32 s29, s28, 31
	s_waitcnt vmcnt(0)
	v_lshlrev_b32_e32 v200, 16, v186
	v_and_b32_e32 v201, 0xffff0000, v186
	v_lshlrev_b32_e32 v186, 16, v187
	v_and_b32_e32 v187, 0xffff0000, v187
	v_pk_add_f32 v[140:141], v[140:141], v[186:187]
	v_lshlrev_b32_e32 v186, 16, v188
	v_and_b32_e32 v187, 0xffff0000, v188
	v_lshlrev_b32_e32 v188, 16, v189
	v_and_b32_e32 v189, 0xffff0000, v189
	v_pk_add_f32 v[138:139], v[138:139], v[200:201]
	v_pk_add_f32 v[188:189], v[132:133], v[188:189]
	v_pk_add_f32 v[186:187], v[130:131], v[186:187]
	v_cvt_pk_bf16_f32 v130, v138, v139
	v_cvt_pk_bf16_f32 v131, v140, v141
	v_cvt_pk_bf16_f32 v132, v186, v187
	v_cvt_pk_bf16_f32 v133, v188, v189
	global_store_dwordx4 v[196:197], v[130:133], off
	v_mul_f32_e32 v139, v139, v139
	v_fmac_f32_e32 v139, v138, v138
	v_lshlrev_b32_e32 v130, 16, v190
	v_and_b32_e32 v131, 0xffff0000, v190
	v_lshlrev_b32_e32 v132, 16, v191
	v_and_b32_e32 v133, 0xffff0000, v191
	v_pk_add_f32 v[124:125], v[124:125], v[132:133]
	v_pk_add_f32 v[122:123], v[122:123], v[130:131]
	v_lshlrev_b32_e32 v130, 16, v192
	v_and_b32_e32 v131, 0xffff0000, v192
	v_lshlrev_b32_e32 v132, 16, v193
	v_and_b32_e32 v133, 0xffff0000, v193
	v_pk_add_f32 v[132:133], v[116:117], v[132:133]
	v_pk_add_f32 v[130:131], v[114:115], v[130:131]
	v_cvt_pk_bf16_f32 v114, v122, v123
	v_cvt_pk_bf16_f32 v115, v124, v125
	v_cvt_pk_bf16_f32 v116, v130, v131
	v_cvt_pk_bf16_f32 v117, v132, v133
	global_store_dwordx4 v[196:197], v[114:117], off offset:256
	v_fmac_f32_e32 v139, v140, v140
	v_fmac_f32_e32 v139, v141, v141
	v_mul_f32_e32 v114, v123, v123
	v_fmac_f32_e32 v114, v122, v122
	v_fmac_f32_e32 v114, v124, v124
	v_fmac_f32_e32 v114, v125, v125
	v_fmac_f32_e32 v139, v186, v186
	v_fmac_f32_e32 v114, v130, v130
	v_fmac_f32_e32 v139, v187, v187
	v_fmac_f32_e32 v114, v131, v131
	v_fmac_f32_e32 v139, v188, v188
	v_fmac_f32_e32 v114, v132, v132
	v_fmac_f32_e32 v139, v189, v189
	v_fmac_f32_e32 v114, v133, v133
	v_add_f32_e32 v114, v139, v114
	v_mov_b32_e32 v115, v114
	s_nop 1
	v_permlane16_swap_b32_e32 v115, v114
	s_waitcnt lgkmcnt(0)
	v_add_f32_e32 v114, v114, v115
	s_nop 0
	v_mov_b32_e32 v115, v114
	s_nop 1
	v_permlane32_swap_b32_e32 v115, v114
	s_and_saveexec_b64 s[30:31], s[6:7]
	s_cbranch_execz .LBB0_717
	v_lshlrev_b64 v[116:117], 6, v[168:169]
	v_lshl_add_u64 v[116:117], s[16:17], 0, v[116:117]
	v_lshl_add_u64 v[116:117], s[28:29], 2, v[116:117]
	s_lshl_b32 s50, s45, 2
	v_lshl_add_u64 v[116:117], v[116:117], 0, s[50:51]
	s_waitcnt lgkmcnt(0)
	v_add_f32_e32 v114, v114, v115
	global_store_dword v[116:117], v114, off
.LBB0_717:
	s_or_b64 exec, exec, s[30:31]
	v_lshlrev_b32_e32 v114, 16, v150
	s_waitcnt lgkmcnt(0)
	v_and_b32_e32 v115, 0xffff0000, v150
	v_lshlrev_b32_e32 v116, 16, v151
	v_and_b32_e32 v117, 0xffff0000, v151
	v_pk_add_f32 v[112:113], v[112:113], v[116:117]
	v_pk_add_f32 v[110:111], v[110:111], v[114:115]
	v_lshlrev_b32_e32 v114, 16, v152
	v_and_b32_e32 v115, 0xffff0000, v152
	v_lshlrev_b32_e32 v116, 16, v153
	v_and_b32_e32 v117, 0xffff0000, v153
	v_pk_add_f32 v[116:117], v[108:109], v[116:117]
	v_pk_add_f32 v[114:115], v[106:107], v[114:115]
	v_lshl_add_u64 v[122:123], s[18:19], 0, v[180:181]
	v_cvt_pk_bf16_f32 v106, v110, v111
	v_cvt_pk_bf16_f32 v107, v112, v113
	v_cvt_pk_bf16_f32 v108, v114, v115
	v_cvt_pk_bf16_f32 v109, v116, v117
	v_lshl_add_u64 v[122:123], v[164:165], 1, v[122:123]
	global_store_dwordx4 v[122:123], v[106:109], off
	v_mul_f32_e32 v111, v111, v111
	v_fmac_f32_e32 v111, v110, v110
	v_lshlrev_b32_e32 v106, 16, v146
	v_and_b32_e32 v107, 0xffff0000, v146
	v_lshlrev_b32_e32 v108, 16, v147
	v_and_b32_e32 v109, 0xffff0000, v147
	v_pk_add_f32 v[104:105], v[104:105], v[108:109]
	v_pk_add_f32 v[102:103], v[102:103], v[106:107]
	v_lshlrev_b32_e32 v106, 16, v148
	v_and_b32_e32 v107, 0xffff0000, v148
	v_lshlrev_b32_e32 v108, 16, v149
	v_and_b32_e32 v109, 0xffff0000, v149
	v_pk_add_f32 v[108:109], v[100:101], v[108:109]
	v_pk_add_f32 v[106:107], v[98:99], v[106:107]
	v_cvt_pk_bf16_f32 v98, v102, v103
	v_cvt_pk_bf16_f32 v99, v104, v105
	v_cvt_pk_bf16_f32 v100, v106, v107
	v_cvt_pk_bf16_f32 v101, v108, v109
	global_store_dwordx4 v[122:123], v[98:101], off offset:256
	v_fmac_f32_e32 v111, v112, v112
	v_fmac_f32_e32 v111, v113, v113
	v_mul_f32_e32 v98, v103, v103
	v_fmac_f32_e32 v98, v102, v102
	v_fmac_f32_e32 v98, v104, v104
	v_fmac_f32_e32 v98, v105, v105
	v_fmac_f32_e32 v111, v114, v114
	v_fmac_f32_e32 v98, v106, v106
	v_fmac_f32_e32 v111, v115, v115
	v_fmac_f32_e32 v98, v107, v107
	v_fmac_f32_e32 v111, v116, v116
	v_fmac_f32_e32 v98, v108, v108
	v_fmac_f32_e32 v111, v117, v117
	v_fmac_f32_e32 v98, v109, v109
	v_add_f32_e32 v98, v111, v98
	v_mov_b32_e32 v99, v98
	s_nop 1
	v_permlane16_swap_b32_e32 v99, v98
	s_waitcnt lgkmcnt(0)
	v_add_f32_e32 v98, v98, v99
	s_nop 0
	v_mov_b32_e32 v99, v98
	s_nop 1
	v_permlane32_swap_b32_e32 v99, v98
	s_and_saveexec_b64 s[30:31], s[6:7]
	s_cbranch_execz .LBB0_719
	v_lshlrev_b64 v[100:101], 6, v[178:179]
	v_lshl_add_u64 v[100:101], s[16:17], 0, v[100:101]
	v_lshl_add_u64 v[100:101], s[28:29], 2, v[100:101]
	s_lshl_b32 s50, s45, 2
	v_lshl_add_u64 v[100:101], v[100:101], 0, s[50:51]
	s_waitcnt lgkmcnt(0)
	v_add_f32_e32 v98, v98, v99
	global_store_dword v[100:101], v98, off
; DI unsigned pack_bf16(float lo, float hi) { f32v2 f = {lo, hi}; bf16v2 b = __builtin_convertvector(f, bf16v2); return __builtin_bit_cast(unsigned, b); }
; DI float bf_lo(unsigned u) { return __uint_as_float(u << 16); }
; DI float bf_hi(unsigned u) { return __uint_as_float(u & 0xffff0000u); }
; DI float shx(float v, int o) { int l = (int)__builtin_amdgcn_mbcnt_hi(~0u, __builtin_amdgcn_mbcnt_lo(~0u, 0u)); asm volatile("" : "+v"(l)); return __int_as_float(__builtin_amdgcn_ds_bpermute((l ^ o) << 2, __float_as_int(v))); }
;     DI void operator()(const f32x4 (&acc)[2][2][4][2], const pg8::Unit& u, int wr, int wc, int fr, int fq, int) const {
;     ...
;             for (int m = 0; m < 4; ++m) { const size_t ro = (size_t)(row0 + ai * 128 + m * 16) * D + col0;
; #pragma unroll
;                 for (int bj = 0; bj < 2; ++bj) r[m][bj] = *(const u32x4*)(hb + ro + bj * 128); }
;             asm volatile("" ::: "memory");
; #pragma unroll
;             for (int m = 0; m < 4; ++m) { const size_t ro = (size_t)(row0 + ai * 128 + m * 16) * D + col0;
;                 float sq = 0.f;
; #pragma unroll
;                 for (int bj = 0; bj < 2; ++bj) {
;                     const u32x4 rr = r[m][bj];
;                     const f32x4 v0 = (f32x4){bf_lo(rr[0]), bf_hi(rr[0]), bf_lo(rr[1]), bf_hi(rr[1])} + acc[ai][bj][m][0];
;                     const f32x4 v1 = (f32x4){bf_lo(rr[2]), bf_hi(rr[2]), bf_lo(rr[3]), bf_hi(rr[3])} + acc[ai][bj][m][1];
;                     if (LAST) { *(f32x4*)(out + ro + bj * 128) = v0; *(f32x4*)(out + ro + bj * 128 + 4) = v1; }
;                     else {
;                         u32x4 w; w.x = pack_bf16(v0[0], v0[1]); w.y = pack_bf16(v0[2], v0[3]); w.z = pack_bf16(v1[0], v1[1]); w.w = pack_bf16(v1[2], v1[3]);
;                         *(u32x4*)(ho + ro + bj * 128) = w;
;                         sq += v0[0] * v0[0] + v0[1] * v0[1] + v0[2] * v0[2] + v0[3] * v0[3] + v1[0] * v1[0] + v1[1] * v1[1] + v1[2] * v1[2] + v1[3] * v1[3];
;                     }
;                 }
;                 if (!LAST) {
;                     sq += shx(sq, 16); sq += shx(sq, 32);
;                     if (fq == 0) ss[(size_t)(row0 + ai * 128 + m * 16) * 16 + u.pn * 4 + wc] = sq;
.LBB0_719:
	s_or_b64 exec, exec, s[30:31]
	v_lshlrev_b32_e32 v98, 16, v142
	s_waitcnt lgkmcnt(0)
	v_and_b32_e32 v99, 0xffff0000, v142
	v_lshlrev_b32_e32 v100, 16, v143
	v_and_b32_e32 v101, 0xffff0000, v143
	v_pk_add_f32 v[96:97], v[96:97], v[100:101]
	v_pk_add_f32 v[94:95], v[94:95], v[98:99]
	v_lshlrev_b32_e32 v98, 16, v144
	v_and_b32_e32 v99, 0xffff0000, v144
	v_lshlrev_b32_e32 v100, 16, v145
	v_and_b32_e32 v101, 0xffff0000, v145
	v_pk_add_f32 v[100:101], v[92:93], v[100:101]
	v_pk_add_f32 v[98:99], v[90:91], v[98:99]
	v_lshl_add_u64 v[102:103], s[18:19], 0, v[176:177]
	v_cvt_pk_bf16_f32 v90, v94, v95
	v_cvt_pk_bf16_f32 v91, v96, v97
	v_cvt_pk_bf16_f32 v92, v98, v99
	v_cvt_pk_bf16_f32 v93, v100, v101
	v_lshl_add_u64 v[102:103], v[164:165], 1, v[102:103]
	global_store_dwordx4 v[102:103], v[90:93], off
	v_mul_f32_e32 v95, v95, v95
	v_fmac_f32_e32 v95, v94, v94
	v_lshlrev_b32_e32 v90, 16, v134
	v_and_b32_e32 v91, 0xffff0000, v134
	v_lshlrev_b32_e32 v92, 16, v135
	v_and_b32_e32 v93, 0xffff0000, v135
	v_pk_add_f32 v[88:89], v[88:89], v[92:93]
	v_pk_add_f32 v[86:87], v[86:87], v[90:91]
	v_lshlrev_b32_e32 v90, 16, v136
	v_and_b32_e32 v91, 0xffff0000, v136
	v_lshlrev_b32_e32 v92, 16, v137
	v_and_b32_e32 v93, 0xffff0000, v137
	v_pk_add_f32 v[92:93], v[84:85], v[92:93]
	v_pk_add_f32 v[90:91], v[82:83], v[90:91]
	v_cvt_pk_bf16_f32 v82, v86, v87
	v_cvt_pk_bf16_f32 v83, v88, v89
	v_cvt_pk_bf16_f32 v84, v90, v91
	v_cvt_pk_bf16_f32 v85, v92, v93
	global_store_dwordx4 v[102:103], v[82:85], off offset:256
	v_fmac_f32_e32 v95, v96, v96
	v_fmac_f32_e32 v95, v97, v97
	v_mul_f32_e32 v82, v87, v87
	v_fmac_f32_e32 v82, v86, v86
	v_fmac_f32_e32 v82, v88, v88
	v_fmac_f32_e32 v82, v89, v89
	v_fmac_f32_e32 v95, v98, v98
	v_fmac_f32_e32 v82, v90, v90
	v_fmac_f32_e32 v95, v99, v99
	v_fmac_f32_e32 v82, v91, v91
	v_fmac_f32_e32 v95, v100, v100
	v_fmac_f32_e32 v82, v92, v92
	v_fmac_f32_e32 v95, v101, v101
	v_fmac_f32_e32 v82, v93, v93
	v_add_f32_e32 v82, v95, v82
	v_mov_b32_e32 v83, v82
	s_nop 1
	v_permlane16_swap_b32_e32 v83, v82
	s_waitcnt lgkmcnt(0)
	v_add_f32_e32 v82, v82, v83
	s_nop 0
	v_mov_b32_e32 v83, v82
	s_nop 1
	v_permlane32_swap_b32_e32 v83, v82
	s_and_saveexec_b64 s[30:31], s[6:7]
	s_cbranch_execz .LBB0_721
	v_lshlrev_b64 v[84:85], 6, v[172:173]
	v_lshl_add_u64 v[84:85], s[16:17], 0, v[84:85]
	v_lshl_add_u64 v[84:85], s[28:29], 2, v[84:85]
	s_lshl_b32 s50, s45, 2
	v_lshl_add_u64 v[84:85], v[84:85], 0, s[50:51]
	s_waitcnt lgkmcnt(0)
	v_add_f32_e32 v82, v82, v83
	global_store_dword v[84:85], v82, off
.LBB0_721:
	s_or_b64 exec, exec, s[30:31]
	v_lshlrev_b32_e32 v82, 16, v126
	s_waitcnt lgkmcnt(0)
	v_and_b32_e32 v83, 0xffff0000, v126
	v_lshlrev_b32_e32 v84, 16, v127
	v_and_b32_e32 v85, 0xffff0000, v127
	v_pk_add_f32 v[80:81], v[80:81], v[84:85]
	v_pk_add_f32 v[78:79], v[78:79], v[82:83]
	v_lshlrev_b32_e32 v82, 16, v128
	v_and_b32_e32 v83, 0xffff0000, v128
	v_lshlrev_b32_e32 v84, 16, v129
	v_and_b32_e32 v85, 0xffff0000, v129
	v_pk_add_f32 v[84:85], v[76:77], v[84:85]
	v_pk_add_f32 v[82:83], v[74:75], v[82:83]
	v_lshl_add_u64 v[86:87], s[18:19], 0, v[174:175]
	v_cvt_pk_bf16_f32 v74, v78, v79
	v_cvt_pk_bf16_f32 v75, v80, v81
	v_cvt_pk_bf16_f32 v76, v82, v83
	v_cvt_pk_bf16_f32 v77, v84, v85
	v_lshl_add_u64 v[86:87], v[164:165], 1, v[86:87]
	global_store_dwordx4 v[86:87], v[74:77], off
	v_mul_f32_e32 v79, v79, v79
	v_fmac_f32_e32 v79, v78, v78
	v_lshlrev_b32_e32 v74, 16, v118
	v_and_b32_e32 v75, 0xffff0000, v118
	v_lshlrev_b32_e32 v76, 16, v119
	v_and_b32_e32 v77, 0xffff0000, v119
	v_pk_add_f32 v[72:73], v[72:73], v[76:77]
	v_pk_add_f32 v[70:71], v[70:71], v[74:75]
	v_lshlrev_b32_e32 v74, 16, v120
	v_and_b32_e32 v75, 0xffff0000, v120
	v_lshlrev_b32_e32 v76, 16, v121
	v_and_b32_e32 v77, 0xffff0000, v121
	v_pk_add_f32 v[76:77], v[68:69], v[76:77]
	v_pk_add_f32 v[74:75], v[66:67], v[74:75]
	v_cvt_pk_bf16_f32 v66, v70, v71
	v_cvt_pk_bf16_f32 v67, v72, v73
	v_cvt_pk_bf16_f32 v68, v74, v75
	v_cvt_pk_bf16_f32 v69, v76, v77
	global_store_dwordx4 v[86:87], v[66:69], off offset:256
	v_fmac_f32_e32 v79, v80, v80
	v_fmac_f32_e32 v79, v81, v81
	v_mul_f32_e32 v66, v71, v71
	v_fmac_f32_e32 v66, v70, v70
	v_fmac_f32_e32 v66, v72, v72
	v_fmac_f32_e32 v66, v73, v73
	v_fmac_f32_e32 v79, v82, v82
	v_fmac_f32_e32 v66, v74, v74
	v_fmac_f32_e32 v79, v83, v83
	v_fmac_f32_e32 v66, v75, v75
	v_fmac_f32_e32 v79, v84, v84
	v_fmac_f32_e32 v66, v76, v76
	v_fmac_f32_e32 v79, v85, v85
	v_fmac_f32_e32 v66, v77, v77
	v_add_f32_e32 v66, v79, v66
	v_mov_b32_e32 v67, v66
	s_nop 1
	v_permlane16_swap_b32_e32 v67, v66
	s_waitcnt lgkmcnt(0)
	v_add_f32_e32 v66, v66, v67
	s_nop 0
	v_mov_b32_e32 v67, v66
	s_nop 1
	v_permlane32_swap_b32_e32 v67, v66
	s_and_saveexec_b64 s[30:31], s[6:7]
	s_cbranch_execz .LBB0_723
	v_lshlrev_b64 v[68:69], 6, v[170:171]
	v_lshl_add_u64 v[68:69], s[16:17], 0, v[68:69]
	v_lshl_add_u64 v[68:69], s[28:29], 2, v[68:69]
	s_lshl_b32 s50, s45, 2
	v_lshl_add_u64 v[68:69], v[68:69], 0, s[50:51]
	s_waitcnt lgkmcnt(0)
	v_add_f32_e32 v66, v66, v67
	global_store_dword v[68:69], v66, off
; DI unsigned pack_bf16(float lo, float hi) { f32v2 f = {lo, hi}; bf16v2 b = __builtin_convertvector(f, bf16v2); return __builtin_bit_cast(unsigned, b); }
; DI float bf_lo(unsigned u) { return __uint_as_float(u << 16); }
; DI float bf_hi(unsigned u) { return __uint_as_float(u & 0xffff0000u); }
; DI float shx(float v, int o) { int l = (int)__builtin_amdgcn_mbcnt_hi(~0u, __builtin_amdgcn_mbcnt_lo(~0u, 0u)); asm volatile("" : "+v"(l)); return __int_as_float(__builtin_amdgcn_ds_bpermute((l ^ o) << 2, __float_as_int(v))); }
;     DI void operator()(const f32x4 (&acc)[2][2][4][2], const pg8::Unit& u, int wr, int wc, int fr, int fq, int) const {
;     ...
;             for (int m = 0; m < 4; ++m) { const size_t ro = (size_t)(row0 + ai * 128 + m * 16) * D + col0;
; #pragma unroll
;                 for (int bj = 0; bj < 2; ++bj) r[m][bj] = *(const u32x4*)(hb + ro + bj * 128); }
;             asm volatile("" ::: "memory");
; #pragma unroll
;             for (int m = 0; m < 4; ++m) { const size_t ro = (size_t)(row0 + ai * 128 + m * 16) * D + col0;
;                 float sq = 0.f;
; #pragma unroll
;                 for (int bj = 0; bj < 2; ++bj) {
;                     const u32x4 rr = r[m][bj];
;                     const f32x4 v0 = (f32x4){bf_lo(rr[0]), bf_hi(rr[0]), bf_lo(rr[1]), bf_hi(rr[1])} + acc[ai][bj][m][0];
;                     const f32x4 v1 = (f32x4){bf_lo(rr[2]), bf_hi(rr[2]), bf_lo(rr[3]), bf_hi(rr[3])} + acc[ai][bj][m][1];
;                     if (LAST) { *(f32x4*)(out + ro + bj * 128) = v0; *(f32x4*)(out + ro + bj * 128 + 4) = v1; }
;                     else {
;                         u32x4 w; w.x = pack_bf16(v0[0], v0[1]); w.y = pack_bf16(v0[2], v0[3]); w.z = pack_bf16(v1[0], v1[1]); w.w = pack_bf16(v1[2], v1[3]);
;                         *(u32x4*)(ho + ro + bj * 128) = w;
;                         sq += v0[0] * v0[0] + v0[1] * v0[1] + v0[2] * v0[2] + v0[3] * v0[3] + v1[0] * v1[0] + v1[1] * v1[1] + v1[2] * v1[2] + v1[3] * v1[3];
;                     }
;                 }
;                 if (!LAST) {
;                     sq += shx(sq, 16); sq += shx(sq, 32);
;                     if (fq == 0) ss[(size_t)(row0 + ai * 128 + m * 16) * 16 + u.pn * 4 + wc] = sq;
.LBB0_723:
	s_or_b64 exec, exec, s[30:31]
	v_add_u32_e32 v102, 0x80, v168
	v_ashrrev_i32_e32 v103, 31, v102
	v_lshlrev_b64 v[112:113], 11, v[102:103]
	s_waitcnt lgkmcnt(0)
	v_lshl_add_u64 v[66:67], v[166:167], 0, v[112:113]
	global_load_dwordx4 v[104:107], v[66:67], off
	global_load_dwordx4 v[108:111], v[66:67], off offset:256
	v_add_u32_e32 v98, 0x90, v168
	v_ashrrev_i32_e32 v99, 31, v98
	v_add_u32_e32 v92, 0xa0, v168
	v_lshlrev_b64 v[100:101], 11, v[98:99]
	v_ashrrev_i32_e32 v93, 31, v92
	v_add_u32_e32 v90, 0xb0, v168
	v_lshl_add_u64 v[66:67], v[166:167], 0, v[100:101]
	v_lshlrev_b64 v[96:97], 11, v[92:93]
	v_ashrrev_i32_e32 v91, 31, v90
	global_load_dwordx4 v[86:89], v[66:67], off
	global_load_dwordx4 v[82:85], v[66:67], off offset:256
	v_lshl_add_u64 v[66:67], v[166:167], 0, v[96:97]
	v_lshlrev_b64 v[94:95], 11, v[90:91]
	global_load_dwordx4 v[78:81], v[66:67], off
	global_load_dwordx4 v[74:77], v[66:67], off offset:256
	v_lshl_add_u64 v[66:67], v[166:167], 0, v[94:95]
	global_load_dwordx4 v[70:73], v[66:67], off
	s_nop 0
	global_load_dwordx4 v[66:69], v[66:67], off offset:256
	v_lshl_add_u64 v[112:113], s[18:19], 0, v[112:113]
	v_lshl_add_u64 v[112:113], v[164:165], 1, v[112:113]
	s_waitcnt vmcnt(7)
	v_lshlrev_b32_e32 v114, 16, v104
	v_and_b32_e32 v115, 0xffff0000, v104
	v_lshlrev_b32_e32 v104, 16, v105
	v_and_b32_e32 v105, 0xffff0000, v105
	v_pk_add_f32 v[64:65], v[64:65], v[104:105]
	v_lshlrev_b32_e32 v104, 16, v106
	v_and_b32_e32 v105, 0xffff0000, v106
	v_lshlrev_b32_e32 v106, 16, v107
	v_and_b32_e32 v107, 0xffff0000, v107
	v_pk_add_f32 v[62:63], v[62:63], v[114:115]
	v_pk_add_f32 v[106:107], v[60:61], v[106:107]
	v_pk_add_f32 v[104:105], v[58:59], v[104:105]
	v_cvt_pk_bf16_f32 v58, v62, v63
	v_cvt_pk_bf16_f32 v59, v64, v65
	v_cvt_pk_bf16_f32 v60, v104, v105
	v_cvt_pk_bf16_f32 v61, v106, v107
	global_store_dwordx4 v[112:113], v[58:61], off
	v_mul_f32_e32 v63, v63, v63
	v_fmac_f32_e32 v63, v62, v62
	s_waitcnt vmcnt(7)
	v_lshlrev_b32_e32 v58, 16, v108
	v_and_b32_e32 v59, 0xffff0000, v108
	v_lshlrev_b32_e32 v60, 16, v109
	v_and_b32_e32 v61, 0xffff0000, v109
	v_pk_add_f32 v[56:57], v[56:57], v[60:61]
	v_pk_add_f32 v[54:55], v[54:55], v[58:59]
	v_lshlrev_b32_e32 v58, 16, v110
	v_and_b32_e32 v59, 0xffff0000, v110
	v_lshlrev_b32_e32 v60, 16, v111
	v_and_b32_e32 v61, 0xffff0000, v111
	v_pk_add_f32 v[60:61], v[52:53], v[60:61]
	v_pk_add_f32 v[58:59], v[50:51], v[58:59]
	v_cvt_pk_bf16_f32 v50, v54, v55
	v_cvt_pk_bf16_f32 v51, v56, v57
	v_cvt_pk_bf16_f32 v52, v58, v59
	v_cvt_pk_bf16_f32 v53, v60, v61
	global_store_dwordx4 v[112:113], v[50:53], off offset:256
	v_fmac_f32_e32 v63, v64, v64
	v_fmac_f32_e32 v63, v65, v65
	v_mul_f32_e32 v50, v55, v55
	v_fmac_f32_e32 v50, v54, v54
	v_fmac_f32_e32 v50, v56, v56
	v_fmac_f32_e32 v50, v57, v57
	v_fmac_f32_e32 v63, v104, v104
	v_fmac_f32_e32 v50, v58, v58
	v_fmac_f32_e32 v63, v105, v105
	v_fmac_f32_e32 v50, v59, v59
	v_fmac_f32_e32 v63, v106, v106
	v_fmac_f32_e32 v50, v60, v60
	v_fmac_f32_e32 v63, v107, v107
	v_fmac_f32_e32 v50, v61, v61
	v_add_f32_e32 v50, v63, v50
	v_mov_b32_e32 v51, v50
	s_nop 1
	v_permlane16_swap_b32_e32 v51, v50
	s_waitcnt lgkmcnt(0)
	v_add_f32_e32 v50, v50, v51
	s_nop 0
	v_mov_b32_e32 v51, v50
	s_nop 1
	v_permlane32_swap_b32_e32 v51, v50
	s_and_saveexec_b64 s[30:31], s[6:7]
	s_cbranch_execz .LBB0_725
	v_lshlrev_b64 v[52:53], 6, v[102:103]
	v_lshl_add_u64 v[52:53], s[16:17], 0, v[52:53]
	v_lshl_add_u64 v[52:53], s[28:29], 2, v[52:53]
	s_lshl_b32 s50, s45, 2
	v_lshl_add_u64 v[52:53], v[52:53], 0, s[50:51]
	s_waitcnt lgkmcnt(0)
	v_add_f32_e32 v50, v50, v51
	global_store_dword v[52:53], v50, off
.LBB0_725:
	s_or_b64 exec, exec, s[30:31]
	s_waitcnt vmcnt(7)
	v_lshlrev_b32_e32 v50, 16, v86
	s_waitcnt lgkmcnt(0)
	v_and_b32_e32 v51, 0xffff0000, v86
	v_lshlrev_b32_e32 v52, 16, v87
	v_and_b32_e32 v53, 0xffff0000, v87
	v_pk_add_f32 v[48:49], v[48:49], v[52:53]
	v_pk_add_f32 v[46:47], v[46:47], v[50:51]
	v_lshlrev_b32_e32 v50, 16, v88
	v_and_b32_e32 v51, 0xffff0000, v88
	v_lshlrev_b32_e32 v52, 16, v89
	v_and_b32_e32 v53, 0xffff0000, v89
	v_pk_add_f32 v[52:53], v[44:45], v[52:53]
	v_pk_add_f32 v[50:51], v[42:43], v[50:51]
	v_lshl_add_u64 v[54:55], s[18:19], 0, v[100:101]
	v_cvt_pk_bf16_f32 v42, v46, v47
	v_cvt_pk_bf16_f32 v43, v48, v49
	v_cvt_pk_bf16_f32 v44, v50, v51
	v_cvt_pk_bf16_f32 v45, v52, v53
	v_lshl_add_u64 v[54:55], v[164:165], 1, v[54:55]
	global_store_dwordx4 v[54:55], v[42:45], off
	v_mul_f32_e32 v47, v47, v47
	v_fmac_f32_e32 v47, v46, v46
	s_waitcnt vmcnt(7)
	v_lshlrev_b32_e32 v42, 16, v82
	v_and_b32_e32 v43, 0xffff0000, v82
	v_lshlrev_b32_e32 v44, 16, v83
	v_and_b32_e32 v45, 0xffff0000, v83
	v_pk_add_f32 v[40:41], v[40:41], v[44:45]
	v_pk_add_f32 v[38:39], v[38:39], v[42:43]
	v_lshlrev_b32_e32 v42, 16, v84
	v_and_b32_e32 v43, 0xffff0000, v84
	v_lshlrev_b32_e32 v44, 16, v85
	v_and_b32_e32 v45, 0xffff0000, v85
	v_pk_add_f32 v[44:45], v[36:37], v[44:45]
	v_pk_add_f32 v[42:43], v[34:35], v[42:43]
	v_cvt_pk_bf16_f32 v34, v38, v39
	v_cvt_pk_bf16_f32 v35, v40, v41
	v_cvt_pk_bf16_f32 v36, v42, v43
	v_cvt_pk_bf16_f32 v37, v44, v45
	global_store_dwordx4 v[54:55], v[34:37], off offset:256
	v_fmac_f32_e32 v47, v48, v48
	v_fmac_f32_e32 v47, v49, v49
	v_mul_f32_e32 v34, v39, v39
	v_fmac_f32_e32 v34, v38, v38
	v_fmac_f32_e32 v34, v40, v40
	v_fmac_f32_e32 v34, v41, v41
	v_fmac_f32_e32 v47, v50, v50
	v_fmac_f32_e32 v34, v42, v42
	v_fmac_f32_e32 v47, v51, v51
	v_fmac_f32_e32 v34, v43, v43
	v_fmac_f32_e32 v47, v52, v52
	v_fmac_f32_e32 v34, v44, v44
	v_fmac_f32_e32 v47, v53, v53
	v_fmac_f32_e32 v34, v45, v45
	v_add_f32_e32 v34, v47, v34
	v_mov_b32_e32 v35, v34
	s_nop 1
	v_permlane16_swap_b32_e32 v35, v34
	s_waitcnt lgkmcnt(0)
	v_add_f32_e32 v34, v34, v35
	s_nop 0
	v_mov_b32_e32 v35, v34
	s_nop 1
	v_permlane32_swap_b32_e32 v35, v34
	s_and_saveexec_b64 s[30:31], s[6:7]
	s_cbranch_execz .LBB0_727
	v_lshlrev_b64 v[36:37], 6, v[98:99]
	v_lshl_add_u64 v[36:37], s[16:17], 0, v[36:37]
	v_lshl_add_u64 v[36:37], s[28:29], 2, v[36:37]
	s_lshl_b32 s50, s45, 2
	v_lshl_add_u64 v[36:37], v[36:37], 0, s[50:51]
	s_waitcnt lgkmcnt(0)
	v_add_f32_e32 v34, v34, v35
	global_store_dword v[36:37], v34, off
; DI unsigned pack_bf16(float lo, float hi) { f32v2 f = {lo, hi}; bf16v2 b = __builtin_convertvector(f, bf16v2); return __builtin_bit_cast(unsigned, b); }
; DI float bf_lo(unsigned u) { return __uint_as_float(u << 16); }
; DI float bf_hi(unsigned u) { return __uint_as_float(u & 0xffff0000u); }
; DI float shx(float v, int o) { int l = (int)__builtin_amdgcn_mbcnt_hi(~0u, __builtin_amdgcn_mbcnt_lo(~0u, 0u)); asm volatile("" : "+v"(l)); return __int_as_float(__builtin_amdgcn_ds_bpermute((l ^ o) << 2, __float_as_int(v))); }
;     DI void operator()(const f32x4 (&acc)[2][2][4][2], const pg8::Unit& u, int wr, int wc, int fr, int fq, int) const {
;     ...
;             for (int m = 0; m < 4; ++m) { const size_t ro = (size_t)(row0 + ai * 128 + m * 16) * D + col0;
; #pragma unroll
;                 for (int bj = 0; bj < 2; ++bj) r[m][bj] = *(const u32x4*)(hb + ro + bj * 128); }
;             asm volatile("" ::: "memory");
; #pragma unroll
;             for (int m = 0; m < 4; ++m) { const size_t ro = (size_t)(row0 + ai * 128 + m * 16) * D + col0;
;                 float sq = 0.f;
; #pragma unroll
;                 for (int bj = 0; bj < 2; ++bj) {
;                     const u32x4 rr = r[m][bj];
;                     const f32x4 v0 = (f32x4){bf_lo(rr[0]), bf_hi(rr[0]), bf_lo(rr[1]), bf_hi(rr[1])} + acc[ai][bj][m][0];
;                     const f32x4 v1 = (f32x4){bf_lo(rr[2]), bf_hi(rr[2]), bf_lo(rr[3]), bf_hi(rr[3])} + acc[ai][bj][m][1];
;                     if (LAST) { *(f32x4*)(out + ro + bj * 128) = v0; *(f32x4*)(out + ro + bj * 128 + 4) = v1; }
;                     else {
;                         u32x4 w; w.x = pack_bf16(v0[0], v0[1]); w.y = pack_bf16(v0[2], v0[3]); w.z = pack_bf16(v1[0], v1[1]); w.w = pack_bf16(v1[2], v1[3]);
;                         *(u32x4*)(ho + ro + bj * 128) = w;
;                         sq += v0[0] * v0[0] + v0[1] * v0[1] + v0[2] * v0[2] + v0[3] * v0[3] + v1[0] * v1[0] + v1[1] * v1[1] + v1[2] * v1[2] + v1[3] * v1[3];
;                     }
;                 }
;                 if (!LAST) {
;                     sq += shx(sq, 16); sq += shx(sq, 32);
;                     if (fq == 0) ss[(size_t)(row0 + ai * 128 + m * 16) * 16 + u.pn * 4 + wc] = sq;
.LBB0_727:
	s_or_b64 exec, exec, s[30:31]
	s_waitcnt vmcnt(7)
	v_lshlrev_b32_e32 v34, 16, v78
	s_waitcnt lgkmcnt(0)
	v_and_b32_e32 v35, 0xffff0000, v78
	v_lshlrev_b32_e32 v36, 16, v79
	v_and_b32_e32 v37, 0xffff0000, v79
	v_pk_add_f32 v[32:33], v[32:33], v[36:37]
	v_pk_add_f32 v[30:31], v[30:31], v[34:35]
	v_lshlrev_b32_e32 v34, 16, v80
	v_and_b32_e32 v35, 0xffff0000, v80
	v_lshlrev_b32_e32 v36, 16, v81
	v_and_b32_e32 v37, 0xffff0000, v81
	v_pk_add_f32 v[36:37], v[28:29], v[36:37]
	v_pk_add_f32 v[34:35], v[26:27], v[34:35]
	v_lshl_add_u64 v[38:39], s[18:19], 0, v[96:97]
	v_cvt_pk_bf16_f32 v26, v30, v31
	v_cvt_pk_bf16_f32 v27, v32, v33
	v_cvt_pk_bf16_f32 v28, v34, v35
	v_cvt_pk_bf16_f32 v29, v36, v37
	v_lshl_add_u64 v[38:39], v[164:165], 1, v[38:39]
	global_store_dwordx4 v[38:39], v[26:29], off
	v_mul_f32_e32 v31, v31, v31
	v_fmac_f32_e32 v31, v30, v30
	s_waitcnt vmcnt(7)
	v_lshlrev_b32_e32 v26, 16, v74
	v_and_b32_e32 v27, 0xffff0000, v74
	v_lshlrev_b32_e32 v28, 16, v75
	v_and_b32_e32 v29, 0xffff0000, v75
	v_pk_add_f32 v[24:25], v[24:25], v[28:29]
	v_pk_add_f32 v[22:23], v[22:23], v[26:27]
	v_lshlrev_b32_e32 v26, 16, v76
	v_and_b32_e32 v27, 0xffff0000, v76
	v_lshlrev_b32_e32 v28, 16, v77
	v_and_b32_e32 v29, 0xffff0000, v77
	v_pk_add_f32 v[28:29], v[20:21], v[28:29]
	v_pk_add_f32 v[26:27], v[18:19], v[26:27]
	v_cvt_pk_bf16_f32 v18, v22, v23
	v_cvt_pk_bf16_f32 v19, v24, v25
	v_cvt_pk_bf16_f32 v20, v26, v27
	v_cvt_pk_bf16_f32 v21, v28, v29
	global_store_dwordx4 v[38:39], v[18:21], off offset:256
	v_fmac_f32_e32 v31, v32, v32
	v_fmac_f32_e32 v31, v33, v33
	v_mul_f32_e32 v18, v23, v23
	v_fmac_f32_e32 v18, v22, v22
	v_fmac_f32_e32 v18, v24, v24
	v_fmac_f32_e32 v18, v25, v25
	v_fmac_f32_e32 v31, v34, v34
	v_fmac_f32_e32 v18, v26, v26
	v_fmac_f32_e32 v31, v35, v35
	v_fmac_f32_e32 v18, v27, v27
	v_fmac_f32_e32 v31, v36, v36
	v_fmac_f32_e32 v18, v28, v28
	v_fmac_f32_e32 v31, v37, v37
	v_fmac_f32_e32 v18, v29, v29
	v_add_f32_e32 v18, v31, v18
	v_mov_b32_e32 v19, v18
	s_nop 1
	v_permlane16_swap_b32_e32 v19, v18
	s_waitcnt lgkmcnt(0)
	v_add_f32_e32 v18, v18, v19
	s_nop 0
	v_mov_b32_e32 v19, v18
	s_nop 1
	v_permlane32_swap_b32_e32 v19, v18
	s_and_saveexec_b64 s[30:31], s[6:7]
	s_cbranch_execz .LBB0_729
	v_lshlrev_b64 v[20:21], 6, v[92:93]
	v_lshl_add_u64 v[20:21], s[16:17], 0, v[20:21]
	v_lshl_add_u64 v[20:21], s[28:29], 2, v[20:21]
	s_lshl_b32 s50, s45, 2
	v_lshl_add_u64 v[20:21], v[20:21], 0, s[50:51]
	s_waitcnt lgkmcnt(0)
	v_add_f32_e32 v18, v18, v19
	global_store_dword v[20:21], v18, off
.LBB0_729:
	s_or_b64 exec, exec, s[30:31]
	s_waitcnt vmcnt(7)
	v_lshlrev_b32_e32 v18, 16, v70
	s_waitcnt lgkmcnt(0)
	v_and_b32_e32 v19, 0xffff0000, v70
	v_lshlrev_b32_e32 v20, 16, v71
	v_and_b32_e32 v21, 0xffff0000, v71
	v_pk_add_f32 v[16:17], v[16:17], v[20:21]
	v_pk_add_f32 v[14:15], v[14:15], v[18:19]
	v_lshlrev_b32_e32 v18, 16, v72
	v_and_b32_e32 v19, 0xffff0000, v72
	v_lshlrev_b32_e32 v20, 16, v73
	v_and_b32_e32 v21, 0xffff0000, v73
	v_pk_add_f32 v[20:21], v[12:13], v[20:21]
	v_pk_add_f32 v[18:19], v[10:11], v[18:19]
	v_lshl_add_u64 v[22:23], s[18:19], 0, v[94:95]
	v_cvt_pk_bf16_f32 v10, v14, v15
	v_cvt_pk_bf16_f32 v11, v16, v17
	v_cvt_pk_bf16_f32 v12, v18, v19
	v_cvt_pk_bf16_f32 v13, v20, v21
	v_lshl_add_u64 v[22:23], v[164:165], 1, v[22:23]
	global_store_dwordx4 v[22:23], v[10:13], off
	v_mul_f32_e32 v15, v15, v15
	v_fmac_f32_e32 v15, v14, v14
	s_waitcnt vmcnt(7)
	v_lshlrev_b32_e32 v10, 16, v66
	v_and_b32_e32 v11, 0xffff0000, v66
	v_lshlrev_b32_e32 v12, 16, v67
	v_and_b32_e32 v13, 0xffff0000, v67
	v_pk_add_f32 v[8:9], v[8:9], v[12:13]
	v_pk_add_f32 v[6:7], v[6:7], v[10:11]
	v_lshlrev_b32_e32 v10, 16, v68
	v_and_b32_e32 v11, 0xffff0000, v68
	v_lshlrev_b32_e32 v12, 16, v69
	v_and_b32_e32 v13, 0xffff0000, v69
	v_pk_add_f32 v[12:13], v[4:5], v[12:13]
	v_pk_add_f32 v[10:11], v[2:3], v[10:11]
	v_cvt_pk_bf16_f32 v2, v6, v7
	v_cvt_pk_bf16_f32 v3, v8, v9
	v_cvt_pk_bf16_f32 v4, v10, v11
	v_cvt_pk_bf16_f32 v5, v12, v13
	global_store_dwordx4 v[22:23], v[2:5], off offset:256
	v_fmac_f32_e32 v15, v16, v16
	v_fmac_f32_e32 v15, v17, v17
	v_mul_f32_e32 v2, v7, v7
	v_fmac_f32_e32 v2, v6, v6
	v_fmac_f32_e32 v2, v8, v8
	v_fmac_f32_e32 v2, v9, v9
	v_fmac_f32_e32 v15, v18, v18
	v_fmac_f32_e32 v2, v10, v10
	v_fmac_f32_e32 v15, v19, v19
	v_fmac_f32_e32 v2, v11, v11
	v_fmac_f32_e32 v15, v20, v20
	v_fmac_f32_e32 v2, v12, v12
	v_fmac_f32_e32 v15, v21, v21
	v_fmac_f32_e32 v2, v13, v13
	v_add_f32_e32 v2, v15, v2
	v_mov_b32_e32 v3, v2
	s_nop 1
	v_permlane16_swap_b32_e32 v3, v2
	s_waitcnt lgkmcnt(0)
	v_add_f32_e32 v2, v2, v3
	s_nop 0
	v_mov_b32_e32 v3, v2
	s_nop 1
	v_permlane32_swap_b32_e32 v3, v2
	s_and_saveexec_b64 s[30:31], s[6:7]
	s_cbranch_execz .LBB0_731
	v_lshlrev_b64 v[4:5], 6, v[90:91]
	v_lshl_add_u64 v[4:5], s[16:17], 0, v[4:5]
	v_lshl_add_u64 v[4:5], s[28:29], 2, v[4:5]
	s_lshl_b32 s50, s45, 2
	v_lshl_add_u64 v[4:5], v[4:5], 0, s[50:51]
	s_waitcnt lgkmcnt(0)
	v_add_f32_e32 v2, v2, v3
	global_store_dword v[4:5], v2, off

; DI unsigned pack_bf16(float lo, float hi) { f32v2 f = {lo, hi}; bf16v2 b = __builtin_convertvector(f, bf16v2); return __builtin_bit_cast(unsigned, b); }
; DI float bf_lo(unsigned u) { return __uint_as_float(u << 16); }
; DI float bf_hi(unsigned u) { return __uint_as_float(u & 0xffff0000u); }
; DI float shx(float v, int o) { int l = (int)__builtin_amdgcn_mbcnt_hi(~0u, __builtin_amdgcn_mbcnt_lo(~0u, 0u)); asm volatile("" : "+v"(l)); return __int_as_float(__builtin_amdgcn_ds_bpermute((l ^ o) << 2, __float_as_int(v))); }
;     DI void operator()(const f32x4 (&acc)[2][2][4][2], const pg8::Unit& u, int wr, int wc, int fr, int fq, int) const {
;     ...
;         for (int ai = 0; ai < 2; ++ai) {
;             u32x4 r[4][2];
; #pragma unroll
;             for (int m = 0; m < 4; ++m) { const size_t ro = (size_t)(row0 + ai * 128 + m * 16) * D + col0;
; #pragma unroll
;                 for (int bj = 0; bj < 2; ++bj) r[m][bj] = *(const u32x4*)(hb + ro + bj * 128); }
;             asm volatile("" ::: "memory");
; #pragma unroll
;             for (int m = 0; m < 4; ++m) { const size_t ro = (size_t)(row0 + ai * 128 + m * 16) * D + col0;
;                 float sq = 0.f;
; #pragma unroll
;                 for (int bj = 0; bj < 2; ++bj) {
;                     const u32x4 rr = r[m][bj];
;                     const f32x4 v0 = (f32x4){bf_lo(rr[0]), bf_hi(rr[0]), bf_lo(rr[1]), bf_hi(rr[1])} + acc[ai][bj][m][0];
;                     const f32x4 v1 = (f32x4){bf_lo(rr[2]), bf_hi(rr[2]), bf_lo(rr[3]), bf_hi(rr[3])} + acc[ai][bj][m][1];
;                     if (LAST) { *(f32x4*)(out + ro + bj * 128) = v0; *(f32x4*)(out + ro + bj * 128 + 4) = v1; }
;                     else {
;                         u32x4 w; w.x = pack_bf16(v0[0], v0[1]); w.y = pack_bf16(v0[2], v0[3]); w.z = pack_bf16(v1[0], v1[1]); w.w = pack_bf16(v1[2], v1[3]);
;                         *(u32x4*)(ho + ro + bj * 128) = w;
;                         sq += v0[0] * v0[0] + v0[1] * v0[1] + v0[2] * v0[2] + v0[3] * v0[3] + v1[0] * v1[0] + v1[1] * v1[1] + v1[2] * v1[2] + v1[3] * v1[3];
;                     }
;                 }
;                 if (!LAST) {
;                     sq += shx(sq, 16); sq += shx(sq, 32);
;                     if (fq == 0) ss[(size_t)(row0 + ai * 128 + m * 16) * 16 + u.pn * 4 + wc] = sq;
.LBB0_1028:
	v_lshl_or_b32 v164, s34, 8, v184
	v_lshl_add_u32 v168, s36, 8, v182
	v_ashrrev_i32_e32 v165, 31, v164
	v_lshlrev_b64 v[196:197], 1, v[164:165]
	v_ashrrev_i32_e32 v169, 31, v168
	v_lshl_add_u64 v[166:167], s[12:13], 0, v[196:197]
	v_lshlrev_b64 v[198:199], 11, v[168:169]
	v_lshl_add_u64 v[118:119], v[166:167], 0, v[198:199]
	global_load_dwordx4 v[186:189], v[118:119], off
	global_load_dwordx4 v[190:193], v[118:119], off offset:256
	v_or_b32_e32 v178, 16, v168
	v_ashrrev_i32_e32 v179, 31, v178
	v_or_b32_e32 v172, 32, v168
	v_lshlrev_b64 v[180:181], 11, v[178:179]
	v_ashrrev_i32_e32 v173, 31, v172
	v_or_b32_e32 v170, 48, v168
	v_lshl_add_u64 v[118:119], v[166:167], 0, v[180:181]
	v_lshlrev_b64 v[176:177], 11, v[172:173]
	v_ashrrev_i32_e32 v171, 31, v170
	global_load_dwordx4 v[150:153], v[118:119], off
	global_load_dwordx4 v[146:149], v[118:119], off offset:256
	v_lshl_add_u64 v[118:119], v[166:167], 0, v[176:177]
	v_lshlrev_b64 v[174:175], 11, v[170:171]
	global_load_dwordx4 v[142:145], v[118:119], off
	global_load_dwordx4 v[134:137], v[118:119], off offset:256
	v_lshl_add_u64 v[118:119], v[166:167], 0, v[174:175]
	global_load_dwordx4 v[126:129], v[118:119], off
	s_nop 0
	global_load_dwordx4 v[118:121], v[118:119], off offset:256
	v_lshl_add_u64 v[198:199], s[16:17], 0, v[198:199]
	v_lshl_add_u64 v[196:197], v[198:199], 0, v[196:197]
	s_lshl_b32 s34, s34, 2
	s_ashr_i32 s35, s34, 31
	s_waitcnt vmcnt(0)
	v_lshlrev_b32_e32 v200, 16, v186
	v_and_b32_e32 v201, 0xffff0000, v186
	v_lshlrev_b32_e32 v186, 16, v187
	v_and_b32_e32 v187, 0xffff0000, v187
	v_pk_add_f32 v[140:141], v[140:141], v[186:187]
	v_lshlrev_b32_e32 v186, 16, v188
	v_and_b32_e32 v187, 0xffff0000, v188
	v_lshlrev_b32_e32 v188, 16, v189
	v_and_b32_e32 v189, 0xffff0000, v189
	v_pk_add_f32 v[138:139], v[138:139], v[200:201]
	v_pk_add_f32 v[188:189], v[132:133], v[188:189]
	v_pk_add_f32 v[186:187], v[130:131], v[186:187]
	v_cvt_pk_bf16_f32 v130, v138, v139
	v_cvt_pk_bf16_f32 v131, v140, v141
	v_cvt_pk_bf16_f32 v132, v186, v187
	v_cvt_pk_bf16_f32 v133, v188, v189
	global_store_dwordx4 v[196:197], v[130:133], off
	v_mul_f32_e32 v139, v139, v139
	v_fmac_f32_e32 v139, v138, v138
	v_lshlrev_b32_e32 v130, 16, v190
	v_and_b32_e32 v131, 0xffff0000, v190
	v_lshlrev_b32_e32 v132, 16, v191
	v_and_b32_e32 v133, 0xffff0000, v191
	v_pk_add_f32 v[124:125], v[124:125], v[132:133]
	v_pk_add_f32 v[122:123], v[122:123], v[130:131]
	v_lshlrev_b32_e32 v130, 16, v192
	v_and_b32_e32 v131, 0xffff0000, v192
	v_lshlrev_b32_e32 v132, 16, v193
	v_and_b32_e32 v133, 0xffff0000, v193
	v_pk_add_f32 v[132:133], v[116:117], v[132:133]
	v_pk_add_f32 v[130:131], v[114:115], v[130:131]
	v_cvt_pk_bf16_f32 v114, v122, v123
	v_cvt_pk_bf16_f32 v115, v124, v125
	v_cvt_pk_bf16_f32 v116, v130, v131
	v_cvt_pk_bf16_f32 v117, v132, v133
	global_store_dwordx4 v[196:197], v[114:117], off offset:256
	v_fmac_f32_e32 v139, v140, v140
	v_fmac_f32_e32 v139, v141, v141
	v_mul_f32_e32 v114, v123, v123
	v_fmac_f32_e32 v114, v122, v122
	v_fmac_f32_e32 v114, v124, v124
	v_fmac_f32_e32 v114, v125, v125
	v_fmac_f32_e32 v139, v186, v186
	v_fmac_f32_e32 v114, v130, v130
	v_fmac_f32_e32 v139, v187, v187
	v_fmac_f32_e32 v114, v131, v131
	v_fmac_f32_e32 v139, v188, v188
	v_fmac_f32_e32 v114, v132, v132
	v_fmac_f32_e32 v139, v189, v189
	v_fmac_f32_e32 v114, v133, v133
	v_add_f32_e32 v114, v139, v114
	v_mov_b32_e32 v115, v114
	s_nop 1
	v_permlane16_swap_b32_e32 v115, v114
	s_waitcnt lgkmcnt(0)
	v_add_f32_e32 v114, v114, v115
	s_nop 0
	v_mov_b32_e32 v115, v114
	s_nop 1
	v_permlane32_swap_b32_e32 v115, v114
	s_and_saveexec_b64 s[36:37], s[6:7]
	s_cbranch_execz .LBB0_1030
	v_lshlrev_b64 v[116:117], 6, v[168:169]
	v_lshl_add_u64 v[116:117], s[14:15], 0, v[116:117]
	v_lshl_add_u64 v[116:117], s[34:35], 2, v[116:117]
	s_lshl_b32 s50, s52, 2
	v_lshl_add_u64 v[116:117], v[116:117], 0, s[50:51]
	s_waitcnt lgkmcnt(0)
	v_add_f32_e32 v114, v114, v115
	global_store_dword v[116:117], v114, off
.LBB0_1030:
	s_or_b64 exec, exec, s[36:37]
	v_lshlrev_b32_e32 v114, 16, v150
	s_waitcnt lgkmcnt(0)
	v_and_b32_e32 v115, 0xffff0000, v150
	v_lshlrev_b32_e32 v116, 16, v151
	v_and_b32_e32 v117, 0xffff0000, v151
	v_pk_add_f32 v[112:113], v[112:113], v[116:117]
	v_pk_add_f32 v[110:111], v[110:111], v[114:115]
	v_lshlrev_b32_e32 v114, 16, v152
	v_and_b32_e32 v115, 0xffff0000, v152
	v_lshlrev_b32_e32 v116, 16, v153
	v_and_b32_e32 v117, 0xffff0000, v153
	v_pk_add_f32 v[116:117], v[108:109], v[116:117]
	v_pk_add_f32 v[114:115], v[106:107], v[114:115]
	v_lshl_add_u64 v[122:123], s[16:17], 0, v[180:181]
	v_cvt_pk_bf16_f32 v106, v110, v111
	v_cvt_pk_bf16_f32 v107, v112, v113
	v_cvt_pk_bf16_f32 v108, v114, v115
	v_cvt_pk_bf16_f32 v109, v116, v117
	v_lshl_add_u64 v[122:123], v[164:165], 1, v[122:123]
	global_store_dwordx4 v[122:123], v[106:109], off
	v_mul_f32_e32 v111, v111, v111
	v_fmac_f32_e32 v111, v110, v110
	v_lshlrev_b32_e32 v106, 16, v146
	v_and_b32_e32 v107, 0xffff0000, v146
	v_lshlrev_b32_e32 v108, 16, v147
	v_and_b32_e32 v109, 0xffff0000, v147
	v_pk_add_f32 v[104:105], v[104:105], v[108:109]
	v_pk_add_f32 v[102:103], v[102:103], v[106:107]
	v_lshlrev_b32_e32 v106, 16, v148
	v_and_b32_e32 v107, 0xffff0000, v148
	v_lshlrev_b32_e32 v108, 16, v149
	v_and_b32_e32 v109, 0xffff0000, v149
	v_pk_add_f32 v[108:109], v[100:101], v[108:109]
	v_pk_add_f32 v[106:107], v[98:99], v[106:107]
	v_cvt_pk_bf16_f32 v98, v102, v103
	v_cvt_pk_bf16_f32 v99, v104, v105
	v_cvt_pk_bf16_f32 v100, v106, v107
	v_cvt_pk_bf16_f32 v101, v108, v109
	global_store_dwordx4 v[122:123], v[98:101], off offset:256
	v_fmac_f32_e32 v111, v112, v112
	v_fmac_f32_e32 v111, v113, v113
	v_mul_f32_e32 v98, v103, v103
	v_fmac_f32_e32 v98, v102, v102
	v_fmac_f32_e32 v98, v104, v104
	v_fmac_f32_e32 v98, v105, v105
	v_fmac_f32_e32 v111, v114, v114
	v_fmac_f32_e32 v98, v106, v106
	v_fmac_f32_e32 v111, v115, v115
	v_fmac_f32_e32 v98, v107, v107
	v_fmac_f32_e32 v111, v116, v116
	v_fmac_f32_e32 v98, v108, v108
	v_fmac_f32_e32 v111, v117, v117
	v_fmac_f32_e32 v98, v109, v109
	v_add_f32_e32 v98, v111, v98
	v_mov_b32_e32 v99, v98
	s_nop 1
	v_permlane16_swap_b32_e32 v99, v98
	s_waitcnt lgkmcnt(0)
	v_add_f32_e32 v98, v98, v99
	s_nop 0
	v_mov_b32_e32 v99, v98
	s_nop 1
	v_permlane32_swap_b32_e32 v99, v98
	s_and_saveexec_b64 s[36:37], s[6:7]
	s_cbranch_execz .LBB0_1032
	v_lshlrev_b64 v[100:101], 6, v[178:179]
	v_lshl_add_u64 v[100:101], s[14:15], 0, v[100:101]
	v_lshl_add_u64 v[100:101], s[34:35], 2, v[100:101]
	s_lshl_b32 s50, s52, 2
	v_lshl_add_u64 v[100:101], v[100:101], 0, s[50:51]
	s_waitcnt lgkmcnt(0)
	v_add_f32_e32 v98, v98, v99
	global_store_dword v[100:101], v98, off
; DI unsigned pack_bf16(float lo, float hi) { f32v2 f = {lo, hi}; bf16v2 b = __builtin_convertvector(f, bf16v2); return __builtin_bit_cast(unsigned, b); }
; DI float bf_lo(unsigned u) { return __uint_as_float(u << 16); }
; DI float bf_hi(unsigned u) { return __uint_as_float(u & 0xffff0000u); }
; DI float shx(float v, int o) { int l = (int)__builtin_amdgcn_mbcnt_hi(~0u, __builtin_amdgcn_mbcnt_lo(~0u, 0u)); asm volatile("" : "+v"(l)); return __int_as_float(__builtin_amdgcn_ds_bpermute((l ^ o) << 2, __float_as_int(v))); }
;     DI void operator()(const f32x4 (&acc)[2][2][4][2], const pg8::Unit& u, int wr, int wc, int fr, int fq, int) const {
;     ...
;             for (int m = 0; m < 4; ++m) { const size_t ro = (size_t)(row0 + ai * 128 + m * 16) * D + col0;
;                 float sq = 0.f;
; #pragma unroll
;                 for (int bj = 0; bj < 2; ++bj) {
;                     const u32x4 rr = r[m][bj];
;                     const f32x4 v0 = (f32x4){bf_lo(rr[0]), bf_hi(rr[0]), bf_lo(rr[1]), bf_hi(rr[1])} + acc[ai][bj][m][0];
;                     const f32x4 v1 = (f32x4){bf_lo(rr[2]), bf_hi(rr[2]), bf_lo(rr[3]), bf_hi(rr[3])} + acc[ai][bj][m][1];
;                     if (LAST) { *(f32x4*)(out + ro + bj * 128) = v0; *(f32x4*)(out + ro + bj * 128 + 4) = v1; }
;                     else {
;                         u32x4 w; w.x = pack_bf16(v0[0], v0[1]); w.y = pack_bf16(v0[2], v0[3]); w.z = pack_bf16(v1[0], v1[1]); w.w = pack_bf16(v1[2], v1[3]);
;                         *(u32x4*)(ho + ro + bj * 128) = w;
;                         sq += v0[0] * v0[0] + v0[1] * v0[1] + v0[2] * v0[2] + v0[3] * v0[3] + v1[0] * v1[0] + v1[1] * v1[1] + v1[2] * v1[2] + v1[3] * v1[3];
;                     }
;                 }
;                 if (!LAST) {
;                     sq += shx(sq, 16); sq += shx(sq, 32);
;                     if (fq == 0) ss[(size_t)(row0 + ai * 128 + m * 16) * 16 + u.pn * 4 + wc] = sq;
.LBB0_1032:
	s_or_b64 exec, exec, s[36:37]
	v_lshlrev_b32_e32 v98, 16, v142
	s_waitcnt lgkmcnt(0)
	v_and_b32_e32 v99, 0xffff0000, v142
	v_lshlrev_b32_e32 v100, 16, v143
	v_and_b32_e32 v101, 0xffff0000, v143
	v_pk_add_f32 v[96:97], v[96:97], v[100:101]
	v_pk_add_f32 v[94:95], v[94:95], v[98:99]
	v_lshlrev_b32_e32 v98, 16, v144
	v_and_b32_e32 v99, 0xffff0000, v144
	v_lshlrev_b32_e32 v100, 16, v145
	v_and_b32_e32 v101, 0xffff0000, v145
	v_pk_add_f32 v[100:101], v[92:93], v[100:101]
	v_pk_add_f32 v[98:99], v[90:91], v[98:99]
	v_lshl_add_u64 v[102:103], s[16:17], 0, v[176:177]
	v_cvt_pk_bf16_f32 v90, v94, v95
	v_cvt_pk_bf16_f32 v91, v96, v97
	v_cvt_pk_bf16_f32 v92, v98, v99
	v_cvt_pk_bf16_f32 v93, v100, v101
	v_lshl_add_u64 v[102:103], v[164:165], 1, v[102:103]
	global_store_dwordx4 v[102:103], v[90:93], off
	v_mul_f32_e32 v95, v95, v95
	v_fmac_f32_e32 v95, v94, v94
	v_lshlrev_b32_e32 v90, 16, v134
	v_and_b32_e32 v91, 0xffff0000, v134
	v_lshlrev_b32_e32 v92, 16, v135
	v_and_b32_e32 v93, 0xffff0000, v135
	v_pk_add_f32 v[88:89], v[88:89], v[92:93]
	v_pk_add_f32 v[86:87], v[86:87], v[90:91]
	v_lshlrev_b32_e32 v90, 16, v136
	v_and_b32_e32 v91, 0xffff0000, v136
	v_lshlrev_b32_e32 v92, 16, v137
	v_and_b32_e32 v93, 0xffff0000, v137
	v_pk_add_f32 v[92:93], v[84:85], v[92:93]
	v_pk_add_f32 v[90:91], v[82:83], v[90:91]
	v_cvt_pk_bf16_f32 v82, v86, v87
	v_cvt_pk_bf16_f32 v83, v88, v89
	v_cvt_pk_bf16_f32 v84, v90, v91
	v_cvt_pk_bf16_f32 v85, v92, v93
	global_store_dwordx4 v[102:103], v[82:85], off offset:256
	v_fmac_f32_e32 v95, v96, v96
	v_fmac_f32_e32 v95, v97, v97
	v_mul_f32_e32 v82, v87, v87
	v_fmac_f32_e32 v82, v86, v86
	v_fmac_f32_e32 v82, v88, v88
	v_fmac_f32_e32 v82, v89, v89
	v_fmac_f32_e32 v95, v98, v98
	v_fmac_f32_e32 v82, v90, v90
	v_fmac_f32_e32 v95, v99, v99
	v_fmac_f32_e32 v82, v91, v91
	v_fmac_f32_e32 v95, v100, v100
	v_fmac_f32_e32 v82, v92, v92
	v_fmac_f32_e32 v95, v101, v101
	v_fmac_f32_e32 v82, v93, v93
	v_add_f32_e32 v82, v95, v82
	v_mov_b32_e32 v83, v82
	s_nop 1
	v_permlane16_swap_b32_e32 v83, v82
	s_waitcnt lgkmcnt(0)
	v_add_f32_e32 v82, v82, v83
	s_nop 0
	v_mov_b32_e32 v83, v82
	s_nop 1
	v_permlane32_swap_b32_e32 v83, v82
	s_and_saveexec_b64 s[36:37], s[6:7]
	v_readlane_b32 s85, v255, 40
	v_readlane_b32 s86, v255, 41
	s_movk_i32 s84, 0xfff
	s_cbranch_execz .LBB0_1034
	v_lshlrev_b64 v[84:85], 6, v[172:173]
	v_lshl_add_u64 v[84:85], s[14:15], 0, v[84:85]
	v_lshl_add_u64 v[84:85], s[34:35], 2, v[84:85]
	s_lshl_b32 s50, s52, 2
	v_lshl_add_u64 v[84:85], v[84:85], 0, s[50:51]
	s_waitcnt lgkmcnt(0)
	v_add_f32_e32 v82, v82, v83
	global_store_dword v[84:85], v82, off
.LBB0_1034:
	s_or_b64 exec, exec, s[36:37]
	v_lshlrev_b32_e32 v82, 16, v126
	s_waitcnt lgkmcnt(0)
	v_and_b32_e32 v83, 0xffff0000, v126
	v_lshlrev_b32_e32 v84, 16, v127
	v_and_b32_e32 v85, 0xffff0000, v127
	v_pk_add_f32 v[80:81], v[80:81], v[84:85]
	v_pk_add_f32 v[78:79], v[78:79], v[82:83]
	v_lshlrev_b32_e32 v82, 16, v128
	v_and_b32_e32 v83, 0xffff0000, v128
	v_lshlrev_b32_e32 v84, 16, v129
	v_and_b32_e32 v85, 0xffff0000, v129
	v_pk_add_f32 v[84:85], v[76:77], v[84:85]
	v_pk_add_f32 v[82:83], v[74:75], v[82:83]
	v_lshl_add_u64 v[86:87], s[16:17], 0, v[174:175]
	v_cvt_pk_bf16_f32 v74, v78, v79
	v_cvt_pk_bf16_f32 v75, v80, v81
	v_cvt_pk_bf16_f32 v76, v82, v83
	v_cvt_pk_bf16_f32 v77, v84, v85
	v_lshl_add_u64 v[86:87], v[164:165], 1, v[86:87]
	global_store_dwordx4 v[86:87], v[74:77], off
	v_mul_f32_e32 v79, v79, v79
	v_fmac_f32_e32 v79, v78, v78
	v_lshlrev_b32_e32 v74, 16, v118
	v_and_b32_e32 v75, 0xffff0000, v118
	v_lshlrev_b32_e32 v76, 16, v119
	v_and_b32_e32 v77, 0xffff0000, v119
	v_pk_add_f32 v[72:73], v[72:73], v[76:77]
	v_pk_add_f32 v[70:71], v[70:71], v[74:75]
	v_lshlrev_b32_e32 v74, 16, v120
	v_and_b32_e32 v75, 0xffff0000, v120
	v_lshlrev_b32_e32 v76, 16, v121
	v_and_b32_e32 v77, 0xffff0000, v121
	v_pk_add_f32 v[76:77], v[68:69], v[76:77]
	v_pk_add_f32 v[74:75], v[66:67], v[74:75]
	v_cvt_pk_bf16_f32 v66, v70, v71
	v_cvt_pk_bf16_f32 v67, v72, v73
	v_cvt_pk_bf16_f32 v68, v74, v75
	v_cvt_pk_bf16_f32 v69, v76, v77
	global_store_dwordx4 v[86:87], v[66:69], off offset:256
	v_fmac_f32_e32 v79, v80, v80
	v_fmac_f32_e32 v79, v81, v81
	v_mul_f32_e32 v66, v71, v71
	v_fmac_f32_e32 v66, v70, v70
	v_fmac_f32_e32 v66, v72, v72
	v_fmac_f32_e32 v66, v73, v73
	v_fmac_f32_e32 v79, v82, v82
	v_fmac_f32_e32 v66, v74, v74
	v_fmac_f32_e32 v79, v83, v83
	v_fmac_f32_e32 v66, v75, v75
	v_fmac_f32_e32 v79, v84, v84
	v_fmac_f32_e32 v66, v76, v76
	v_fmac_f32_e32 v79, v85, v85
	v_fmac_f32_e32 v66, v77, v77
	v_add_f32_e32 v66, v79, v66
	v_mov_b32_e32 v67, v66
	s_nop 1
	v_permlane16_swap_b32_e32 v67, v66
	s_waitcnt lgkmcnt(0)
	v_add_f32_e32 v66, v66, v67
	s_nop 0
	v_mov_b32_e32 v67, v66
	s_nop 1
	v_permlane32_swap_b32_e32 v67, v66
	s_and_saveexec_b64 s[36:37], s[6:7]
	s_cbranch_execz .LBB0_1036
	v_lshlrev_b64 v[68:69], 6, v[170:171]
	v_lshl_add_u64 v[68:69], s[14:15], 0, v[68:69]
	v_lshl_add_u64 v[68:69], s[34:35], 2, v[68:69]
	s_lshl_b32 s50, s52, 2
	v_lshl_add_u64 v[68:69], v[68:69], 0, s[50:51]
	s_waitcnt lgkmcnt(0)
	v_add_f32_e32 v66, v66, v67
	global_store_dword v[68:69], v66, off
; DI unsigned pack_bf16(float lo, float hi) { f32v2 f = {lo, hi}; bf16v2 b = __builtin_convertvector(f, bf16v2); return __builtin_bit_cast(unsigned, b); }
; DI float bf_lo(unsigned u) { return __uint_as_float(u << 16); }
; DI float bf_hi(unsigned u) { return __uint_as_float(u & 0xffff0000u); }
; DI float shx(float v, int o) { int l = (int)__builtin_amdgcn_mbcnt_hi(~0u, __builtin_amdgcn_mbcnt_lo(~0u, 0u)); asm volatile("" : "+v"(l)); return __int_as_float(__builtin_amdgcn_ds_bpermute((l ^ o) << 2, __float_as_int(v))); }
;     DI void operator()(const f32x4 (&acc)[2][2][4][2], const pg8::Unit& u, int wr, int wc, int fr, int fq, int) const {
;     ...
;         for (int ai = 0; ai < 2; ++ai) {
;             u32x4 r[4][2];
; #pragma unroll
;             for (int m = 0; m < 4; ++m) { const size_t ro = (size_t)(row0 + ai * 128 + m * 16) * D + col0;
; #pragma unroll
;                 for (int bj = 0; bj < 2; ++bj) r[m][bj] = *(const u32x4*)(hb + ro + bj * 128); }
;             asm volatile("" ::: "memory");
; #pragma unroll
;             for (int m = 0; m < 4; ++m) { const size_t ro = (size_t)(row0 + ai * 128 + m * 16) * D + col0;
;                 float sq = 0.f;
; #pragma unroll
;                 for (int bj = 0; bj < 2; ++bj) {
;                     const u32x4 rr = r[m][bj];
;                     const f32x4 v0 = (f32x4){bf_lo(rr[0]), bf_hi(rr[0]), bf_lo(rr[1]), bf_hi(rr[1])} + acc[ai][bj][m][0];
;                     const f32x4 v1 = (f32x4){bf_lo(rr[2]), bf_hi(rr[2]), bf_lo(rr[3]), bf_hi(rr[3])} + acc[ai][bj][m][1];
;                     if (LAST) { *(f32x4*)(out + ro + bj * 128) = v0; *(f32x4*)(out + ro + bj * 128 + 4) = v1; }
;                     else {
;                         u32x4 w; w.x = pack_bf16(v0[0], v0[1]); w.y = pack_bf16(v0[2], v0[3]); w.z = pack_bf16(v1[0], v1[1]); w.w = pack_bf16(v1[2], v1[3]);
;                         *(u32x4*)(ho + ro + bj * 128) = w;
;                         sq += v0[0] * v0[0] + v0[1] * v0[1] + v0[2] * v0[2] + v0[3] * v0[3] + v1[0] * v1[0] + v1[1] * v1[1] + v1[2] * v1[2] + v1[3] * v1[3];
;                     }
;                 }
;                 if (!LAST) {
;                     sq += shx(sq, 16); sq += shx(sq, 32);
;                     if (fq == 0) ss[(size_t)(row0 + ai * 128 + m * 16) * 16 + u.pn * 4 + wc] = sq;
.LBB0_1036:
	s_or_b64 exec, exec, s[36:37]
	v_add_u32_e32 v102, 0x80, v168
	v_ashrrev_i32_e32 v103, 31, v102
	v_lshlrev_b64 v[112:113], 11, v[102:103]
	s_waitcnt lgkmcnt(0)
	v_lshl_add_u64 v[66:67], v[166:167], 0, v[112:113]
	global_load_dwordx4 v[104:107], v[66:67], off
	global_load_dwordx4 v[108:111], v[66:67], off offset:256
	v_add_u32_e32 v98, 0x90, v168
	v_ashrrev_i32_e32 v99, 31, v98
	v_add_u32_e32 v92, 0xa0, v168
	v_lshlrev_b64 v[100:101], 11, v[98:99]
	v_ashrrev_i32_e32 v93, 31, v92
	v_add_u32_e32 v90, 0xb0, v168
	v_lshl_add_u64 v[66:67], v[166:167], 0, v[100:101]
	v_lshlrev_b64 v[96:97], 11, v[92:93]
	v_ashrrev_i32_e32 v91, 31, v90
	global_load_dwordx4 v[86:89], v[66:67], off
	global_load_dwordx4 v[82:85], v[66:67], off offset:256
	v_lshl_add_u64 v[66:67], v[166:167], 0, v[96:97]
	v_lshlrev_b64 v[94:95], 11, v[90:91]
	global_load_dwordx4 v[78:81], v[66:67], off
	global_load_dwordx4 v[74:77], v[66:67], off offset:256
	v_lshl_add_u64 v[66:67], v[166:167], 0, v[94:95]
	global_load_dwordx4 v[70:73], v[66:67], off
	s_nop 0
	global_load_dwordx4 v[66:69], v[66:67], off offset:256
	v_lshl_add_u64 v[112:113], s[16:17], 0, v[112:113]
	v_lshl_add_u64 v[112:113], v[164:165], 1, v[112:113]
	s_waitcnt vmcnt(7)
	v_lshlrev_b32_e32 v114, 16, v104
	v_and_b32_e32 v115, 0xffff0000, v104
	v_lshlrev_b32_e32 v104, 16, v105
	v_and_b32_e32 v105, 0xffff0000, v105
	v_pk_add_f32 v[64:65], v[64:65], v[104:105]
	v_lshlrev_b32_e32 v104, 16, v106
	v_and_b32_e32 v105, 0xffff0000, v106
	v_lshlrev_b32_e32 v106, 16, v107
	v_and_b32_e32 v107, 0xffff0000, v107
	v_pk_add_f32 v[62:63], v[62:63], v[114:115]
	v_pk_add_f32 v[106:107], v[60:61], v[106:107]
	v_pk_add_f32 v[104:105], v[58:59], v[104:105]
	v_cvt_pk_bf16_f32 v58, v62, v63
	v_cvt_pk_bf16_f32 v59, v64, v65
	v_cvt_pk_bf16_f32 v60, v104, v105
	v_cvt_pk_bf16_f32 v61, v106, v107
	global_store_dwordx4 v[112:113], v[58:61], off
	v_mul_f32_e32 v63, v63, v63
	v_fmac_f32_e32 v63, v62, v62
	s_waitcnt vmcnt(7)
	v_lshlrev_b32_e32 v58, 16, v108
	v_and_b32_e32 v59, 0xffff0000, v108
	v_lshlrev_b32_e32 v60, 16, v109
	v_and_b32_e32 v61, 0xffff0000, v109
	v_pk_add_f32 v[56:57], v[56:57], v[60:61]
	v_pk_add_f32 v[54:55], v[54:55], v[58:59]
	v_lshlrev_b32_e32 v58, 16, v110
	v_and_b32_e32 v59, 0xffff0000, v110
	v_lshlrev_b32_e32 v60, 16, v111
	v_and_b32_e32 v61, 0xffff0000, v111
	v_pk_add_f32 v[60:61], v[52:53], v[60:61]
	v_pk_add_f32 v[58:59], v[50:51], v[58:59]
	v_cvt_pk_bf16_f32 v50, v54, v55
	v_cvt_pk_bf16_f32 v51, v56, v57
	v_cvt_pk_bf16_f32 v52, v58, v59
	v_cvt_pk_bf16_f32 v53, v60, v61
	global_store_dwordx4 v[112:113], v[50:53], off offset:256
	v_fmac_f32_e32 v63, v64, v64
	v_fmac_f32_e32 v63, v65, v65
	v_mul_f32_e32 v50, v55, v55
	v_fmac_f32_e32 v50, v54, v54
	v_fmac_f32_e32 v50, v56, v56
	v_fmac_f32_e32 v50, v57, v57
	v_fmac_f32_e32 v63, v104, v104
	v_fmac_f32_e32 v50, v58, v58
	v_fmac_f32_e32 v63, v105, v105
	v_fmac_f32_e32 v50, v59, v59
	v_fmac_f32_e32 v63, v106, v106
	v_fmac_f32_e32 v50, v60, v60
	v_fmac_f32_e32 v63, v107, v107
	v_fmac_f32_e32 v50, v61, v61
	v_add_f32_e32 v50, v63, v50
	v_mov_b32_e32 v51, v50
	s_nop 1
	v_permlane16_swap_b32_e32 v51, v50
	s_waitcnt lgkmcnt(0)
	v_add_f32_e32 v50, v50, v51
	s_nop 0
	v_mov_b32_e32 v51, v50
	s_nop 1
	v_permlane32_swap_b32_e32 v51, v50
	s_and_saveexec_b64 s[36:37], s[6:7]
	s_cbranch_execz .LBB0_1038
	v_lshlrev_b64 v[52:53], 6, v[102:103]
	v_lshl_add_u64 v[52:53], s[14:15], 0, v[52:53]
	v_lshl_add_u64 v[52:53], s[34:35], 2, v[52:53]
	s_lshl_b32 s50, s52, 2
	v_lshl_add_u64 v[52:53], v[52:53], 0, s[50:51]
	s_waitcnt lgkmcnt(0)
	v_add_f32_e32 v50, v50, v51
	global_store_dword v[52:53], v50, off
.LBB0_1038:
	s_or_b64 exec, exec, s[36:37]
	s_waitcnt vmcnt(7)
	v_lshlrev_b32_e32 v50, 16, v86
	s_waitcnt lgkmcnt(0)
	v_and_b32_e32 v51, 0xffff0000, v86
	v_lshlrev_b32_e32 v52, 16, v87
	v_and_b32_e32 v53, 0xffff0000, v87
	v_pk_add_f32 v[48:49], v[48:49], v[52:53]
	v_pk_add_f32 v[46:47], v[46:47], v[50:51]
	v_lshlrev_b32_e32 v50, 16, v88
	v_and_b32_e32 v51, 0xffff0000, v88
	v_lshlrev_b32_e32 v52, 16, v89
	v_and_b32_e32 v53, 0xffff0000, v89
	v_pk_add_f32 v[52:53], v[44:45], v[52:53]
	v_pk_add_f32 v[50:51], v[42:43], v[50:51]
	v_lshl_add_u64 v[54:55], s[16:17], 0, v[100:101]
	v_cvt_pk_bf16_f32 v42, v46, v47
	v_cvt_pk_bf16_f32 v43, v48, v49
	v_cvt_pk_bf16_f32 v44, v50, v51
	v_cvt_pk_bf16_f32 v45, v52, v53
	v_lshl_add_u64 v[54:55], v[164:165], 1, v[54:55]
	global_store_dwordx4 v[54:55], v[42:45], off
	v_mul_f32_e32 v47, v47, v47
	v_fmac_f32_e32 v47, v46, v46
	s_waitcnt vmcnt(7)
	v_lshlrev_b32_e32 v42, 16, v82
	v_and_b32_e32 v43, 0xffff0000, v82
	v_lshlrev_b32_e32 v44, 16, v83
	v_and_b32_e32 v45, 0xffff0000, v83
	v_pk_add_f32 v[40:41], v[40:41], v[44:45]
	v_pk_add_f32 v[38:39], v[38:39], v[42:43]
	v_lshlrev_b32_e32 v42, 16, v84
	v_and_b32_e32 v43, 0xffff0000, v84
	v_lshlrev_b32_e32 v44, 16, v85
	v_and_b32_e32 v45, 0xffff0000, v85
	v_pk_add_f32 v[44:45], v[36:37], v[44:45]
	v_pk_add_f32 v[42:43], v[34:35], v[42:43]
	v_cvt_pk_bf16_f32 v34, v38, v39
	v_cvt_pk_bf16_f32 v35, v40, v41
	v_cvt_pk_bf16_f32 v36, v42, v43
	v_cvt_pk_bf16_f32 v37, v44, v45
	global_store_dwordx4 v[54:55], v[34:37], off offset:256
	v_fmac_f32_e32 v47, v48, v48
	v_fmac_f32_e32 v47, v49, v49
	v_mul_f32_e32 v34, v39, v39
	v_fmac_f32_e32 v34, v38, v38
	v_fmac_f32_e32 v34, v40, v40
	v_fmac_f32_e32 v34, v41, v41
	v_fmac_f32_e32 v47, v50, v50
	v_fmac_f32_e32 v34, v42, v42
	v_fmac_f32_e32 v47, v51, v51
	v_fmac_f32_e32 v34, v43, v43
	v_fmac_f32_e32 v47, v52, v52
	v_fmac_f32_e32 v34, v44, v44
	v_fmac_f32_e32 v47, v53, v53
	v_fmac_f32_e32 v34, v45, v45
	v_add_f32_e32 v34, v47, v34
	v_mov_b32_e32 v35, v34
	s_nop 1
	v_permlane16_swap_b32_e32 v35, v34
	s_waitcnt lgkmcnt(0)
	v_add_f32_e32 v34, v34, v35
	s_nop 0
	v_mov_b32_e32 v35, v34
	s_nop 1
	v_permlane32_swap_b32_e32 v35, v34
	s_and_saveexec_b64 s[36:37], s[6:7]
	s_cbranch_execz .LBB0_1040
	v_lshlrev_b64 v[36:37], 6, v[98:99]
	v_lshl_add_u64 v[36:37], s[14:15], 0, v[36:37]
	v_lshl_add_u64 v[36:37], s[34:35], 2, v[36:37]
	s_lshl_b32 s50, s52, 2
	v_lshl_add_u64 v[36:37], v[36:37], 0, s[50:51]
	s_waitcnt lgkmcnt(0)
	v_add_f32_e32 v34, v34, v35
	global_store_dword v[36:37], v34, off
; DI unsigned pack_bf16(float lo, float hi) { f32v2 f = {lo, hi}; bf16v2 b = __builtin_convertvector(f, bf16v2); return __builtin_bit_cast(unsigned, b); }
; DI float bf_lo(unsigned u) { return __uint_as_float(u << 16); }
; DI float bf_hi(unsigned u) { return __uint_as_float(u & 0xffff0000u); }
; DI float shx(float v, int o) { int l = (int)__builtin_amdgcn_mbcnt_hi(~0u, __builtin_amdgcn_mbcnt_lo(~0u, 0u)); asm volatile("" : "+v"(l)); return __int_as_float(__builtin_amdgcn_ds_bpermute((l ^ o) << 2, __float_as_int(v))); }
;     DI void operator()(const f32x4 (&acc)[2][2][4][2], const pg8::Unit& u, int wr, int wc, int fr, int fq, int) const {
;     ...
;             for (int m = 0; m < 4; ++m) { const size_t ro = (size_t)(row0 + ai * 128 + m * 16) * D + col0;
;                 float sq = 0.f;
; #pragma unroll
;                 for (int bj = 0; bj < 2; ++bj) {
;                     const u32x4 rr = r[m][bj];
;                     const f32x4 v0 = (f32x4){bf_lo(rr[0]), bf_hi(rr[0]), bf_lo(rr[1]), bf_hi(rr[1])} + acc[ai][bj][m][0];
;                     const f32x4 v1 = (f32x4){bf_lo(rr[2]), bf_hi(rr[2]), bf_lo(rr[3]), bf_hi(rr[3])} + acc[ai][bj][m][1];
;                     if (LAST) { *(f32x4*)(out + ro + bj * 128) = v0; *(f32x4*)(out + ro + bj * 128 + 4) = v1; }
;                     else {
;                         u32x4 w; w.x = pack_bf16(v0[0], v0[1]); w.y = pack_bf16(v0[2], v0[3]); w.z = pack_bf16(v1[0], v1[1]); w.w = pack_bf16(v1[2], v1[3]);
;                         *(u32x4*)(ho + ro + bj * 128) = w;
;                         sq += v0[0] * v0[0] + v0[1] * v0[1] + v0[2] * v0[2] + v0[3] * v0[3] + v1[0] * v1[0] + v1[1] * v1[1] + v1[2] * v1[2] + v1[3] * v1[3];
;                     }
;                 }
;                 if (!LAST) {
;                     sq += shx(sq, 16); sq += shx(sq, 32);
;                     if (fq == 0) ss[(size_t)(row0 + ai * 128 + m * 16) * 16 + u.pn * 4 + wc] = sq;
.LBB0_1040:
	s_or_b64 exec, exec, s[36:37]
	s_waitcnt vmcnt(7)
	v_lshlrev_b32_e32 v34, 16, v78
	s_waitcnt lgkmcnt(0)
	v_and_b32_e32 v35, 0xffff0000, v78
	v_lshlrev_b32_e32 v36, 16, v79
	v_and_b32_e32 v37, 0xffff0000, v79
	v_pk_add_f32 v[32:33], v[32:33], v[36:37]
	v_pk_add_f32 v[30:31], v[30:31], v[34:35]
	v_lshlrev_b32_e32 v34, 16, v80
	v_and_b32_e32 v35, 0xffff0000, v80
	v_lshlrev_b32_e32 v36, 16, v81
	v_and_b32_e32 v37, 0xffff0000, v81
	v_pk_add_f32 v[36:37], v[28:29], v[36:37]
	v_pk_add_f32 v[34:35], v[26:27], v[34:35]
	v_lshl_add_u64 v[38:39], s[16:17], 0, v[96:97]
	v_cvt_pk_bf16_f32 v26, v30, v31
	v_cvt_pk_bf16_f32 v27, v32, v33
	v_cvt_pk_bf16_f32 v28, v34, v35
	v_cvt_pk_bf16_f32 v29, v36, v37
	v_lshl_add_u64 v[38:39], v[164:165], 1, v[38:39]
	global_store_dwordx4 v[38:39], v[26:29], off
	v_mul_f32_e32 v31, v31, v31
	v_fmac_f32_e32 v31, v30, v30
	s_waitcnt vmcnt(7)
	v_lshlrev_b32_e32 v26, 16, v74
	v_and_b32_e32 v27, 0xffff0000, v74
	v_lshlrev_b32_e32 v28, 16, v75
	v_and_b32_e32 v29, 0xffff0000, v75
	v_pk_add_f32 v[24:25], v[24:25], v[28:29]
	v_pk_add_f32 v[22:23], v[22:23], v[26:27]
	v_lshlrev_b32_e32 v26, 16, v76
	v_and_b32_e32 v27, 0xffff0000, v76
	v_lshlrev_b32_e32 v28, 16, v77
	v_and_b32_e32 v29, 0xffff0000, v77
	v_pk_add_f32 v[28:29], v[20:21], v[28:29]
	v_pk_add_f32 v[26:27], v[18:19], v[26:27]
	v_cvt_pk_bf16_f32 v18, v22, v23
	v_cvt_pk_bf16_f32 v19, v24, v25
	v_cvt_pk_bf16_f32 v20, v26, v27
	v_cvt_pk_bf16_f32 v21, v28, v29
	global_store_dwordx4 v[38:39], v[18:21], off offset:256
	v_fmac_f32_e32 v31, v32, v32
	v_fmac_f32_e32 v31, v33, v33
	v_mul_f32_e32 v18, v23, v23
	v_fmac_f32_e32 v18, v22, v22
	v_fmac_f32_e32 v18, v24, v24
	v_fmac_f32_e32 v18, v25, v25
	v_fmac_f32_e32 v31, v34, v34
	v_fmac_f32_e32 v18, v26, v26
	v_fmac_f32_e32 v31, v35, v35
	v_fmac_f32_e32 v18, v27, v27
	v_fmac_f32_e32 v31, v36, v36
	v_fmac_f32_e32 v18, v28, v28
	v_fmac_f32_e32 v31, v37, v37
	v_fmac_f32_e32 v18, v29, v29
	v_add_f32_e32 v18, v31, v18
	v_mov_b32_e32 v19, v18
	s_nop 1
	v_permlane16_swap_b32_e32 v19, v18
	s_waitcnt lgkmcnt(0)
	v_add_f32_e32 v18, v18, v19
	s_nop 0
	v_mov_b32_e32 v19, v18
	s_nop 1
	v_permlane32_swap_b32_e32 v19, v18
	s_and_saveexec_b64 s[36:37], s[6:7]
	s_cbranch_execz .LBB0_1042
	v_lshlrev_b64 v[20:21], 6, v[92:93]
	v_lshl_add_u64 v[20:21], s[14:15], 0, v[20:21]
	v_lshl_add_u64 v[20:21], s[34:35], 2, v[20:21]
	s_lshl_b32 s50, s52, 2
	v_lshl_add_u64 v[20:21], v[20:21], 0, s[50:51]
	s_waitcnt lgkmcnt(0)
	v_add_f32_e32 v18, v18, v19
	global_store_dword v[20:21], v18, off
.LBB0_1042:
	s_or_b64 exec, exec, s[36:37]
	s_waitcnt vmcnt(7)
	v_lshlrev_b32_e32 v18, 16, v70
	s_waitcnt lgkmcnt(0)
	v_and_b32_e32 v19, 0xffff0000, v70
	v_lshlrev_b32_e32 v20, 16, v71
	v_and_b32_e32 v21, 0xffff0000, v71
	v_pk_add_f32 v[16:17], v[16:17], v[20:21]
	v_pk_add_f32 v[14:15], v[14:15], v[18:19]
	v_lshlrev_b32_e32 v18, 16, v72
	v_and_b32_e32 v19, 0xffff0000, v72
	v_lshlrev_b32_e32 v20, 16, v73
	v_and_b32_e32 v21, 0xffff0000, v73
	v_pk_add_f32 v[20:21], v[12:13], v[20:21]
	v_pk_add_f32 v[18:19], v[10:11], v[18:19]
	v_lshl_add_u64 v[22:23], s[16:17], 0, v[94:95]
	v_cvt_pk_bf16_f32 v10, v14, v15
	v_cvt_pk_bf16_f32 v11, v16, v17
	v_cvt_pk_bf16_f32 v12, v18, v19
	v_cvt_pk_bf16_f32 v13, v20, v21
	v_lshl_add_u64 v[22:23], v[164:165], 1, v[22:23]
	global_store_dwordx4 v[22:23], v[10:13], off
	v_mul_f32_e32 v15, v15, v15
	v_fmac_f32_e32 v15, v14, v14
	s_waitcnt vmcnt(7)
	v_lshlrev_b32_e32 v10, 16, v66
	v_and_b32_e32 v11, 0xffff0000, v66
	v_lshlrev_b32_e32 v12, 16, v67
	v_and_b32_e32 v13, 0xffff0000, v67
	v_pk_add_f32 v[8:9], v[8:9], v[12:13]
	v_pk_add_f32 v[6:7], v[6:7], v[10:11]
	v_lshlrev_b32_e32 v10, 16, v68
	v_and_b32_e32 v11, 0xffff0000, v68
	v_lshlrev_b32_e32 v12, 16, v69
	v_and_b32_e32 v13, 0xffff0000, v69
	v_pk_add_f32 v[12:13], v[4:5], v[12:13]
	v_pk_add_f32 v[10:11], v[2:3], v[10:11]
	v_cvt_pk_bf16_f32 v2, v6, v7
	v_cvt_pk_bf16_f32 v3, v8, v9
	v_cvt_pk_bf16_f32 v4, v10, v11
	v_cvt_pk_bf16_f32 v5, v12, v13
	global_store_dwordx4 v[22:23], v[2:5], off offset:256
	v_fmac_f32_e32 v15, v16, v16
	v_fmac_f32_e32 v15, v17, v17
	v_mul_f32_e32 v2, v7, v7
	v_fmac_f32_e32 v2, v6, v6
	v_fmac_f32_e32 v2, v8, v8
	v_fmac_f32_e32 v2, v9, v9
	v_fmac_f32_e32 v15, v18, v18
	v_fmac_f32_e32 v2, v10, v10
	v_fmac_f32_e32 v15, v19, v19
	v_fmac_f32_e32 v2, v11, v11
	v_fmac_f32_e32 v15, v20, v20
	v_fmac_f32_e32 v2, v12, v12
	v_fmac_f32_e32 v15, v21, v21
	v_fmac_f32_e32 v2, v13, v13
	v_add_f32_e32 v2, v15, v2
	v_mov_b32_e32 v3, v2
	s_nop 1
	v_permlane16_swap_b32_e32 v3, v2
	s_waitcnt lgkmcnt(0)
	v_add_f32_e32 v2, v2, v3
	s_nop 0
	v_mov_b32_e32 v3, v2
	s_nop 1
	v_permlane32_swap_b32_e32 v3, v2
	s_and_saveexec_b64 s[36:37], s[6:7]
	s_cbranch_execz .LBB0_1044
	v_lshlrev_b64 v[4:5], 6, v[90:91]
	v_lshl_add_u64 v[4:5], s[14:15], 0, v[4:5]
	v_lshl_add_u64 v[4:5], s[34:35], 2, v[4:5]
	s_lshl_b32 s50, s52, 2
	v_lshl_add_u64 v[4:5], v[4:5], 0, s[50:51]
	s_waitcnt lgkmcnt(0)
	v_add_f32_e32 v2, v2, v3
	global_store_dword v[4:5], v2, off

; DI unsigned pack_bf16(float lo, float hi) { f32v2 f = {lo, hi}; bf16v2 b = __builtin_convertvector(f, bf16v2); return __builtin_bit_cast(unsigned, b); }
; DI float bf_lo(unsigned u) { return __uint_as_float(u << 16); }
; DI float bf_hi(unsigned u) { return __uint_as_float(u & 0xffff0000u); }
; DI float shx(float v, int o) { int l = (int)__builtin_amdgcn_mbcnt_hi(~0u, __builtin_amdgcn_mbcnt_lo(~0u, 0u)); asm volatile("" : "+v"(l)); return __int_as_float(__builtin_amdgcn_ds_bpermute((l ^ o) << 2, __float_as_int(v))); }
;     DI void operator()(const f32x4 (&acc)[2][2][4][2], const pg8::Unit& u, int wr, int wc, int fr, int fq, int) const {
;     ...
;         for (int ai = 0; ai < 2; ++ai) {
;             u32x4 r[4][2];
; #pragma unroll
;             for (int m = 0; m < 4; ++m) { const size_t ro = (size_t)(row0 + ai * 128 + m * 16) * D + col0;
; #pragma unroll
;                 for (int bj = 0; bj < 2; ++bj) r[m][bj] = *(const u32x4*)(hb + ro + bj * 128); }
;             asm volatile("" ::: "memory");
; #pragma unroll
;             for (int m = 0; m < 4; ++m) { const size_t ro = (size_t)(row0 + ai * 128 + m * 16) * D + col0;
;                 float sq = 0.f;
; #pragma unroll
;                 for (int bj = 0; bj < 2; ++bj) {
;                     const u32x4 rr = r[m][bj];
;                     const f32x4 v0 = (f32x4){bf_lo(rr[0]), bf_hi(rr[0]), bf_lo(rr[1]), bf_hi(rr[1])} + acc[ai][bj][m][0];
;                     const f32x4 v1 = (f32x4){bf_lo(rr[2]), bf_hi(rr[2]), bf_lo(rr[3]), bf_hi(rr[3])} + acc[ai][bj][m][1];
;                     if (LAST) { *(f32x4*)(out + ro + bj * 128) = v0; *(f32x4*)(out + ro + bj * 128 + 4) = v1; }
;                     else {
;                         u32x4 w; w.x = pack_bf16(v0[0], v0[1]); w.y = pack_bf16(v0[2], v0[3]); w.z = pack_bf16(v1[0], v1[1]); w.w = pack_bf16(v1[2], v1[3]);
;                         *(u32x4*)(ho + ro + bj * 128) = w;
;                         sq += v0[0] * v0[0] + v0[1] * v0[1] + v0[2] * v0[2] + v0[3] * v0[3] + v1[0] * v1[0] + v1[1] * v1[1] + v1[2] * v1[2] + v1[3] * v1[3];
;                     }
;                 }
;                 if (!LAST) {
;                     sq += shx(sq, 16); sq += shx(sq, 32);
;                     if (fq == 0) ss[(size_t)(row0 + ai * 128 + m * 16) * 16 + u.pn * 4 + wc] = sq;
.LBB0_1315:
	v_lshl_or_b32 v164, s58, 8, v184
	v_lshl_add_u32 v168, s59, 8, v182
	v_ashrrev_i32_e32 v165, 31, v164
	v_lshlrev_b64 v[196:197], 1, v[164:165]
	v_ashrrev_i32_e32 v169, 31, v168
	v_lshl_add_u64 v[166:167], s[10:11], 0, v[196:197]
	v_lshlrev_b64 v[198:199], 11, v[168:169]
	v_lshl_add_u64 v[118:119], v[166:167], 0, v[198:199]
	global_load_dwordx4 v[186:189], v[118:119], off
	global_load_dwordx4 v[190:193], v[118:119], off offset:256
	v_or_b32_e32 v178, 16, v168
	v_ashrrev_i32_e32 v179, 31, v178
	v_or_b32_e32 v172, 32, v168
	v_lshlrev_b64 v[180:181], 11, v[178:179]
	v_ashrrev_i32_e32 v173, 31, v172
	v_or_b32_e32 v170, 48, v168
	v_lshl_add_u64 v[118:119], v[166:167], 0, v[180:181]
	v_lshlrev_b64 v[176:177], 11, v[172:173]
	v_ashrrev_i32_e32 v171, 31, v170
	global_load_dwordx4 v[150:153], v[118:119], off
	global_load_dwordx4 v[146:149], v[118:119], off offset:256
	v_lshl_add_u64 v[118:119], v[166:167], 0, v[176:177]
	v_lshlrev_b64 v[174:175], 11, v[170:171]
	global_load_dwordx4 v[142:145], v[118:119], off
	global_load_dwordx4 v[134:137], v[118:119], off offset:256
	v_lshl_add_u64 v[118:119], v[166:167], 0, v[174:175]
	global_load_dwordx4 v[126:129], v[118:119], off
	s_nop 0
	global_load_dwordx4 v[118:121], v[118:119], off offset:256
	v_lshl_add_u64 v[198:199], s[14:15], 0, v[198:199]
	v_lshl_add_u64 v[196:197], v[198:199], 0, v[196:197]
	s_lshl_b32 s22, s58, 2
	s_ashr_i32 s23, s22, 31
	s_waitcnt vmcnt(0)
	v_lshlrev_b32_e32 v200, 16, v186
	v_and_b32_e32 v201, 0xffff0000, v186
	v_lshlrev_b32_e32 v186, 16, v187
	v_and_b32_e32 v187, 0xffff0000, v187
	v_pk_add_f32 v[140:141], v[140:141], v[186:187]
	v_lshlrev_b32_e32 v186, 16, v188
	v_and_b32_e32 v187, 0xffff0000, v188
	v_lshlrev_b32_e32 v188, 16, v189
	v_and_b32_e32 v189, 0xffff0000, v189
	v_pk_add_f32 v[138:139], v[138:139], v[200:201]
	v_pk_add_f32 v[188:189], v[132:133], v[188:189]
	v_pk_add_f32 v[186:187], v[130:131], v[186:187]
	v_cvt_pk_bf16_f32 v130, v138, v139
	v_cvt_pk_bf16_f32 v131, v140, v141
	v_cvt_pk_bf16_f32 v132, v186, v187
	v_cvt_pk_bf16_f32 v133, v188, v189
	global_store_dwordx4 v[196:197], v[130:133], off
	v_mul_f32_e32 v139, v139, v139
	v_fmac_f32_e32 v139, v138, v138
	v_lshlrev_b32_e32 v130, 16, v190
	v_and_b32_e32 v131, 0xffff0000, v190
	v_lshlrev_b32_e32 v132, 16, v191
	v_and_b32_e32 v133, 0xffff0000, v191
	v_pk_add_f32 v[124:125], v[124:125], v[132:133]
	v_pk_add_f32 v[122:123], v[122:123], v[130:131]
	v_lshlrev_b32_e32 v130, 16, v192
	v_and_b32_e32 v131, 0xffff0000, v192
	v_lshlrev_b32_e32 v132, 16, v193
	v_and_b32_e32 v133, 0xffff0000, v193
	v_pk_add_f32 v[132:133], v[116:117], v[132:133]
	v_pk_add_f32 v[130:131], v[114:115], v[130:131]
	v_cvt_pk_bf16_f32 v114, v122, v123
	v_cvt_pk_bf16_f32 v115, v124, v125
	v_cvt_pk_bf16_f32 v116, v130, v131
	v_cvt_pk_bf16_f32 v117, v132, v133
	global_store_dwordx4 v[196:197], v[114:117], off offset:256
	v_fmac_f32_e32 v139, v140, v140
	v_fmac_f32_e32 v139, v141, v141
	v_mul_f32_e32 v114, v123, v123
	v_fmac_f32_e32 v114, v122, v122
	v_fmac_f32_e32 v114, v124, v124
	v_fmac_f32_e32 v114, v125, v125
	v_fmac_f32_e32 v139, v186, v186
	v_fmac_f32_e32 v114, v130, v130
	v_fmac_f32_e32 v139, v187, v187
	v_fmac_f32_e32 v114, v131, v131
	v_fmac_f32_e32 v139, v188, v188
	v_fmac_f32_e32 v114, v132, v132
	v_fmac_f32_e32 v139, v189, v189
	v_fmac_f32_e32 v114, v133, v133
	v_add_f32_e32 v114, v139, v114
	v_mov_b32_e32 v115, v114
	s_nop 1
	v_permlane16_swap_b32_e32 v115, v114
	s_waitcnt lgkmcnt(0)
	v_add_f32_e32 v114, v114, v115
	s_nop 0
	v_mov_b32_e32 v115, v114
	s_nop 1
	v_permlane32_swap_b32_e32 v115, v114
	s_and_saveexec_b64 s[24:25], s[0:1]
	s_movk_i32 s54, 0xffef
	s_cbranch_execz .LBB0_1317
	v_lshlrev_b64 v[116:117], 6, v[168:169]
	v_lshl_add_u64 v[116:117], s[12:13], 0, v[116:117]
	v_lshl_add_u64 v[116:117], s[22:23], 2, v[116:117]
	s_lshl_b32 s50, s41, 2
	v_lshl_add_u64 v[116:117], v[116:117], 0, s[50:51]
	s_waitcnt lgkmcnt(0)
	v_add_f32_e32 v114, v114, v115
	global_store_dword v[116:117], v114, off
.LBB0_1317:
	s_or_b64 exec, exec, s[24:25]
	v_lshlrev_b32_e32 v114, 16, v150
	s_waitcnt lgkmcnt(0)
	v_and_b32_e32 v115, 0xffff0000, v150
	v_lshlrev_b32_e32 v116, 16, v151
	v_and_b32_e32 v117, 0xffff0000, v151
	v_pk_add_f32 v[112:113], v[112:113], v[116:117]
	v_pk_add_f32 v[110:111], v[110:111], v[114:115]
	v_lshlrev_b32_e32 v114, 16, v152
	v_and_b32_e32 v115, 0xffff0000, v152
	v_lshlrev_b32_e32 v116, 16, v153
	v_and_b32_e32 v117, 0xffff0000, v153
	v_pk_add_f32 v[116:117], v[108:109], v[116:117]
	v_pk_add_f32 v[114:115], v[106:107], v[114:115]
	v_lshl_add_u64 v[122:123], s[14:15], 0, v[180:181]
	v_cvt_pk_bf16_f32 v106, v110, v111
	v_cvt_pk_bf16_f32 v107, v112, v113
	v_cvt_pk_bf16_f32 v108, v114, v115
	v_cvt_pk_bf16_f32 v109, v116, v117
	v_lshl_add_u64 v[122:123], v[164:165], 1, v[122:123]
	global_store_dwordx4 v[122:123], v[106:109], off
	v_mul_f32_e32 v111, v111, v111
	v_fmac_f32_e32 v111, v110, v110
	v_lshlrev_b32_e32 v106, 16, v146
	v_and_b32_e32 v107, 0xffff0000, v146
	v_lshlrev_b32_e32 v108, 16, v147
	v_and_b32_e32 v109, 0xffff0000, v147
	v_pk_add_f32 v[104:105], v[104:105], v[108:109]
	v_pk_add_f32 v[102:103], v[102:103], v[106:107]
	v_lshlrev_b32_e32 v106, 16, v148
	v_and_b32_e32 v107, 0xffff0000, v148
	v_lshlrev_b32_e32 v108, 16, v149
	v_and_b32_e32 v109, 0xffff0000, v149
	v_pk_add_f32 v[108:109], v[100:101], v[108:109]
	v_pk_add_f32 v[106:107], v[98:99], v[106:107]
	v_cvt_pk_bf16_f32 v98, v102, v103
	v_cvt_pk_bf16_f32 v99, v104, v105
	v_cvt_pk_bf16_f32 v100, v106, v107
	v_cvt_pk_bf16_f32 v101, v108, v109
	global_store_dwordx4 v[122:123], v[98:101], off offset:256
	v_fmac_f32_e32 v111, v112, v112
	v_fmac_f32_e32 v111, v113, v113
	v_mul_f32_e32 v98, v103, v103
	v_fmac_f32_e32 v98, v102, v102
	v_fmac_f32_e32 v98, v104, v104
	v_fmac_f32_e32 v98, v105, v105
	v_fmac_f32_e32 v111, v114, v114
	v_fmac_f32_e32 v98, v106, v106
	v_fmac_f32_e32 v111, v115, v115
	v_fmac_f32_e32 v98, v107, v107
	v_fmac_f32_e32 v111, v116, v116
	v_fmac_f32_e32 v98, v108, v108
	v_fmac_f32_e32 v111, v117, v117
	v_fmac_f32_e32 v98, v109, v109
	v_add_f32_e32 v98, v111, v98
	v_mov_b32_e32 v99, v98
	s_nop 1
	v_permlane16_swap_b32_e32 v99, v98
	s_waitcnt lgkmcnt(0)
	v_add_f32_e32 v98, v98, v99
	s_nop 0
	v_mov_b32_e32 v99, v98
	s_nop 1
	v_permlane32_swap_b32_e32 v99, v98
	s_and_saveexec_b64 s[24:25], s[0:1]
	s_cbranch_execz .LBB0_1319
	v_lshlrev_b64 v[100:101], 6, v[178:179]
	v_lshl_add_u64 v[100:101], s[12:13], 0, v[100:101]
	v_lshl_add_u64 v[100:101], s[22:23], 2, v[100:101]
	s_lshl_b32 s50, s41, 2
	v_lshl_add_u64 v[100:101], v[100:101], 0, s[50:51]
	s_waitcnt lgkmcnt(0)
	v_add_f32_e32 v98, v98, v99
	global_store_dword v[100:101], v98, off
; DI unsigned pack_bf16(float lo, float hi) { f32v2 f = {lo, hi}; bf16v2 b = __builtin_convertvector(f, bf16v2); return __builtin_bit_cast(unsigned, b); }
; DI float bf_lo(unsigned u) { return __uint_as_float(u << 16); }
; DI float bf_hi(unsigned u) { return __uint_as_float(u & 0xffff0000u); }
; DI float shx(float v, int o) { int l = (int)__builtin_amdgcn_mbcnt_hi(~0u, __builtin_amdgcn_mbcnt_lo(~0u, 0u)); asm volatile("" : "+v"(l)); return __int_as_float(__builtin_amdgcn_ds_bpermute((l ^ o) << 2, __float_as_int(v))); }
;     DI void operator()(const f32x4 (&acc)[2][2][4][2], const pg8::Unit& u, int wr, int wc, int fr, int fq, int) const {
;     ...
;             for (int m = 0; m < 4; ++m) { const size_t ro = (size_t)(row0 + ai * 128 + m * 16) * D + col0;
;                 float sq = 0.f;
; #pragma unroll
;                 for (int bj = 0; bj < 2; ++bj) {
;                     const u32x4 rr = r[m][bj];
;                     const f32x4 v0 = (f32x4){bf_lo(rr[0]), bf_hi(rr[0]), bf_lo(rr[1]), bf_hi(rr[1])} + acc[ai][bj][m][0];
;                     const f32x4 v1 = (f32x4){bf_lo(rr[2]), bf_hi(rr[2]), bf_lo(rr[3]), bf_hi(rr[3])} + acc[ai][bj][m][1];
;                     if (LAST) { *(f32x4*)(out + ro + bj * 128) = v0; *(f32x4*)(out + ro + bj * 128 + 4) = v1; }
;                     else {
;                         u32x4 w; w.x = pack_bf16(v0[0], v0[1]); w.y = pack_bf16(v0[2], v0[3]); w.z = pack_bf16(v1[0], v1[1]); w.w = pack_bf16(v1[2], v1[3]);
;                         *(u32x4*)(ho + ro + bj * 128) = w;
;                         sq += v0[0] * v0[0] + v0[1] * v0[1] + v0[2] * v0[2] + v0[3] * v0[3] + v1[0] * v1[0] + v1[1] * v1[1] + v1[2] * v1[2] + v1[3] * v1[3];
;                     }
;                 }
;                 if (!LAST) {
;                     sq += shx(sq, 16); sq += shx(sq, 32);
;                     if (fq == 0) ss[(size_t)(row0 + ai * 128 + m * 16) * 16 + u.pn * 4 + wc] = sq;
.LBB0_1319:
	s_or_b64 exec, exec, s[24:25]
	v_lshlrev_b32_e32 v98, 16, v142
	s_waitcnt lgkmcnt(0)
	v_and_b32_e32 v99, 0xffff0000, v142
	v_lshlrev_b32_e32 v100, 16, v143
	v_and_b32_e32 v101, 0xffff0000, v143
	v_pk_add_f32 v[96:97], v[96:97], v[100:101]
	v_pk_add_f32 v[94:95], v[94:95], v[98:99]
	v_lshlrev_b32_e32 v98, 16, v144
	v_and_b32_e32 v99, 0xffff0000, v144
	v_lshlrev_b32_e32 v100, 16, v145
	v_and_b32_e32 v101, 0xffff0000, v145
	v_pk_add_f32 v[100:101], v[92:93], v[100:101]
	v_pk_add_f32 v[98:99], v[90:91], v[98:99]
	v_lshl_add_u64 v[102:103], s[14:15], 0, v[176:177]
	v_cvt_pk_bf16_f32 v90, v94, v95
	v_cvt_pk_bf16_f32 v91, v96, v97
	v_cvt_pk_bf16_f32 v92, v98, v99
	v_cvt_pk_bf16_f32 v93, v100, v101
	v_lshl_add_u64 v[102:103], v[164:165], 1, v[102:103]
	global_store_dwordx4 v[102:103], v[90:93], off
	v_mul_f32_e32 v95, v95, v95
	v_fmac_f32_e32 v95, v94, v94
	v_lshlrev_b32_e32 v90, 16, v134
	v_and_b32_e32 v91, 0xffff0000, v134
	v_lshlrev_b32_e32 v92, 16, v135
	v_and_b32_e32 v93, 0xffff0000, v135
	v_pk_add_f32 v[88:89], v[88:89], v[92:93]
	v_pk_add_f32 v[86:87], v[86:87], v[90:91]
	v_lshlrev_b32_e32 v90, 16, v136
	v_and_b32_e32 v91, 0xffff0000, v136
	v_lshlrev_b32_e32 v92, 16, v137
	v_and_b32_e32 v93, 0xffff0000, v137
	v_pk_add_f32 v[92:93], v[84:85], v[92:93]
	v_pk_add_f32 v[90:91], v[82:83], v[90:91]
	v_cvt_pk_bf16_f32 v82, v86, v87
	v_cvt_pk_bf16_f32 v83, v88, v89
	v_cvt_pk_bf16_f32 v84, v90, v91
	v_cvt_pk_bf16_f32 v85, v92, v93
	global_store_dwordx4 v[102:103], v[82:85], off offset:256
	v_fmac_f32_e32 v95, v96, v96
	v_fmac_f32_e32 v95, v97, v97
	v_mul_f32_e32 v82, v87, v87
	v_fmac_f32_e32 v82, v86, v86
	v_fmac_f32_e32 v82, v88, v88
	v_fmac_f32_e32 v82, v89, v89
	v_fmac_f32_e32 v95, v98, v98
	v_fmac_f32_e32 v82, v90, v90
	v_fmac_f32_e32 v95, v99, v99
	v_fmac_f32_e32 v82, v91, v91
	v_fmac_f32_e32 v95, v100, v100
	v_fmac_f32_e32 v82, v92, v92
	v_fmac_f32_e32 v95, v101, v101
	v_fmac_f32_e32 v82, v93, v93
	v_add_f32_e32 v82, v95, v82
	v_mov_b32_e32 v83, v82
	s_nop 1
	v_permlane16_swap_b32_e32 v83, v82
	s_waitcnt lgkmcnt(0)
	v_add_f32_e32 v82, v82, v83
	s_nop 0
	v_mov_b32_e32 v83, v82
	s_nop 1
	v_permlane32_swap_b32_e32 v83, v82
	s_and_saveexec_b64 s[24:25], s[0:1]
	s_cbranch_execz .LBB0_1321
	v_lshlrev_b64 v[84:85], 6, v[172:173]
	v_lshl_add_u64 v[84:85], s[12:13], 0, v[84:85]
	v_lshl_add_u64 v[84:85], s[22:23], 2, v[84:85]
	s_lshl_b32 s50, s41, 2
	v_lshl_add_u64 v[84:85], v[84:85], 0, s[50:51]
	s_waitcnt lgkmcnt(0)
	v_add_f32_e32 v82, v82, v83
	global_store_dword v[84:85], v82, off
.LBB0_1321:
	s_or_b64 exec, exec, s[24:25]
	v_lshlrev_b32_e32 v82, 16, v126
	s_waitcnt lgkmcnt(0)
	v_and_b32_e32 v83, 0xffff0000, v126
	v_lshlrev_b32_e32 v84, 16, v127
	v_and_b32_e32 v85, 0xffff0000, v127
	v_pk_add_f32 v[80:81], v[80:81], v[84:85]
	v_pk_add_f32 v[78:79], v[78:79], v[82:83]
	v_lshlrev_b32_e32 v82, 16, v128
	v_and_b32_e32 v83, 0xffff0000, v128
	v_lshlrev_b32_e32 v84, 16, v129
	v_and_b32_e32 v85, 0xffff0000, v129
	v_pk_add_f32 v[84:85], v[76:77], v[84:85]
	v_pk_add_f32 v[82:83], v[74:75], v[82:83]
	v_lshl_add_u64 v[86:87], s[14:15], 0, v[174:175]
	v_cvt_pk_bf16_f32 v74, v78, v79
	v_cvt_pk_bf16_f32 v75, v80, v81
	v_cvt_pk_bf16_f32 v76, v82, v83
	v_cvt_pk_bf16_f32 v77, v84, v85
	v_lshl_add_u64 v[86:87], v[164:165], 1, v[86:87]
	global_store_dwordx4 v[86:87], v[74:77], off
	v_mul_f32_e32 v79, v79, v79
	v_fmac_f32_e32 v79, v78, v78
	v_lshlrev_b32_e32 v74, 16, v118
	v_and_b32_e32 v75, 0xffff0000, v118
	v_lshlrev_b32_e32 v76, 16, v119
	v_and_b32_e32 v77, 0xffff0000, v119
	v_pk_add_f32 v[72:73], v[72:73], v[76:77]
	v_pk_add_f32 v[70:71], v[70:71], v[74:75]
	v_lshlrev_b32_e32 v74, 16, v120
	v_and_b32_e32 v75, 0xffff0000, v120
	v_lshlrev_b32_e32 v76, 16, v121
	v_and_b32_e32 v77, 0xffff0000, v121
	v_pk_add_f32 v[76:77], v[68:69], v[76:77]
	v_pk_add_f32 v[74:75], v[66:67], v[74:75]
	v_cvt_pk_bf16_f32 v66, v70, v71
	v_cvt_pk_bf16_f32 v67, v72, v73
	v_cvt_pk_bf16_f32 v68, v74, v75
	v_cvt_pk_bf16_f32 v69, v76, v77
	global_store_dwordx4 v[86:87], v[66:69], off offset:256
	v_fmac_f32_e32 v79, v80, v80
	v_fmac_f32_e32 v79, v81, v81
	v_mul_f32_e32 v66, v71, v71
	v_fmac_f32_e32 v66, v70, v70
	v_fmac_f32_e32 v66, v72, v72
	v_fmac_f32_e32 v66, v73, v73
	v_fmac_f32_e32 v79, v82, v82
	v_fmac_f32_e32 v66, v74, v74
	v_fmac_f32_e32 v79, v83, v83
	v_fmac_f32_e32 v66, v75, v75
	v_fmac_f32_e32 v79, v84, v84
	v_fmac_f32_e32 v66, v76, v76
	v_fmac_f32_e32 v79, v85, v85
	v_fmac_f32_e32 v66, v77, v77
	v_add_f32_e32 v66, v79, v66
	v_mov_b32_e32 v67, v66
	s_nop 1
	v_permlane16_swap_b32_e32 v67, v66
	s_waitcnt lgkmcnt(0)
	v_add_f32_e32 v66, v66, v67
	s_nop 0
	v_mov_b32_e32 v67, v66
	s_nop 1
	v_permlane32_swap_b32_e32 v67, v66
	s_and_saveexec_b64 s[24:25], s[0:1]
	s_cbranch_execz .LBB0_1323
	v_lshlrev_b64 v[68:69], 6, v[170:171]
	v_lshl_add_u64 v[68:69], s[12:13], 0, v[68:69]
	v_lshl_add_u64 v[68:69], s[22:23], 2, v[68:69]
	s_lshl_b32 s50, s41, 2
	v_lshl_add_u64 v[68:69], v[68:69], 0, s[50:51]
	s_waitcnt lgkmcnt(0)
	v_add_f32_e32 v66, v66, v67
	global_store_dword v[68:69], v66, off
; DI unsigned pack_bf16(float lo, float hi) { f32v2 f = {lo, hi}; bf16v2 b = __builtin_convertvector(f, bf16v2); return __builtin_bit_cast(unsigned, b); }
; DI float bf_lo(unsigned u) { return __uint_as_float(u << 16); }
; DI float bf_hi(unsigned u) { return __uint_as_float(u & 0xffff0000u); }
; DI float shx(float v, int o) { int l = (int)__builtin_amdgcn_mbcnt_hi(~0u, __builtin_amdgcn_mbcnt_lo(~0u, 0u)); asm volatile("" : "+v"(l)); return __int_as_float(__builtin_amdgcn_ds_bpermute((l ^ o) << 2, __float_as_int(v))); }
;     DI void operator()(const f32x4 (&acc)[2][2][4][2], const pg8::Unit& u, int wr, int wc, int fr, int fq, int) const {
;     ...
;         for (int ai = 0; ai < 2; ++ai) {
;             u32x4 r[4][2];
; #pragma unroll
;             for (int m = 0; m < 4; ++m) { const size_t ro = (size_t)(row0 + ai * 128 + m * 16) * D + col0;
; #pragma unroll
;                 for (int bj = 0; bj < 2; ++bj) r[m][bj] = *(const u32x4*)(hb + ro + bj * 128); }
;             asm volatile("" ::: "memory");
; #pragma unroll
;             for (int m = 0; m < 4; ++m) { const size_t ro = (size_t)(row0 + ai * 128 + m * 16) * D + col0;
;                 float sq = 0.f;
; #pragma unroll
;                 for (int bj = 0; bj < 2; ++bj) {
;                     const u32x4 rr = r[m][bj];
;                     const f32x4 v0 = (f32x4){bf_lo(rr[0]), bf_hi(rr[0]), bf_lo(rr[1]), bf_hi(rr[1])} + acc[ai][bj][m][0];
;                     const f32x4 v1 = (f32x4){bf_lo(rr[2]), bf_hi(rr[2]), bf_lo(rr[3]), bf_hi(rr[3])} + acc[ai][bj][m][1];
;                     if (LAST) { *(f32x4*)(out + ro + bj * 128) = v0; *(f32x4*)(out + ro + bj * 128 + 4) = v1; }
;                     else {
;                         u32x4 w; w.x = pack_bf16(v0[0], v0[1]); w.y = pack_bf16(v0[2], v0[3]); w.z = pack_bf16(v1[0], v1[1]); w.w = pack_bf16(v1[2], v1[3]);
;                         *(u32x4*)(ho + ro + bj * 128) = w;
;                         sq += v0[0] * v0[0] + v0[1] * v0[1] + v0[2] * v0[2] + v0[3] * v0[3] + v1[0] * v1[0] + v1[1] * v1[1] + v1[2] * v1[2] + v1[3] * v1[3];
;                     }
;                 }
;                 if (!LAST) {
;                     sq += shx(sq, 16); sq += shx(sq, 32);
;                     if (fq == 0) ss[(size_t)(row0 + ai * 128 + m * 16) * 16 + u.pn * 4 + wc] = sq;
.LBB0_1323:
	s_or_b64 exec, exec, s[24:25]
	v_add_u32_e32 v102, 0x80, v168
	v_ashrrev_i32_e32 v103, 31, v102
	v_lshlrev_b64 v[112:113], 11, v[102:103]
	s_waitcnt lgkmcnt(0)
	v_lshl_add_u64 v[66:67], v[166:167], 0, v[112:113]
	global_load_dwordx4 v[104:107], v[66:67], off
	global_load_dwordx4 v[108:111], v[66:67], off offset:256
	v_add_u32_e32 v98, 0x90, v168
	v_ashrrev_i32_e32 v99, 31, v98
	v_add_u32_e32 v92, 0xa0, v168
	v_lshlrev_b64 v[100:101], 11, v[98:99]
	v_ashrrev_i32_e32 v93, 31, v92
	v_add_u32_e32 v90, 0xb0, v168
	v_lshl_add_u64 v[66:67], v[166:167], 0, v[100:101]
	v_lshlrev_b64 v[96:97], 11, v[92:93]
	v_ashrrev_i32_e32 v91, 31, v90
	global_load_dwordx4 v[86:89], v[66:67], off
	global_load_dwordx4 v[82:85], v[66:67], off offset:256
	v_lshl_add_u64 v[66:67], v[166:167], 0, v[96:97]
	v_lshlrev_b64 v[94:95], 11, v[90:91]
	global_load_dwordx4 v[78:81], v[66:67], off
	global_load_dwordx4 v[74:77], v[66:67], off offset:256
	v_lshl_add_u64 v[66:67], v[166:167], 0, v[94:95]
	global_load_dwordx4 v[70:73], v[66:67], off
	s_nop 0
	global_load_dwordx4 v[66:69], v[66:67], off offset:256
	v_lshl_add_u64 v[112:113], s[14:15], 0, v[112:113]
	v_lshl_add_u64 v[112:113], v[164:165], 1, v[112:113]
	s_waitcnt vmcnt(7)
	v_lshlrev_b32_e32 v114, 16, v104
	v_and_b32_e32 v115, 0xffff0000, v104
	v_lshlrev_b32_e32 v104, 16, v105
	v_and_b32_e32 v105, 0xffff0000, v105
	v_pk_add_f32 v[64:65], v[64:65], v[104:105]
	v_lshlrev_b32_e32 v104, 16, v106
	v_and_b32_e32 v105, 0xffff0000, v106
	v_lshlrev_b32_e32 v106, 16, v107
	v_and_b32_e32 v107, 0xffff0000, v107
	v_pk_add_f32 v[62:63], v[62:63], v[114:115]
	v_pk_add_f32 v[106:107], v[60:61], v[106:107]
	v_pk_add_f32 v[104:105], v[58:59], v[104:105]
	v_cvt_pk_bf16_f32 v58, v62, v63
	v_cvt_pk_bf16_f32 v59, v64, v65
	v_cvt_pk_bf16_f32 v60, v104, v105
	v_cvt_pk_bf16_f32 v61, v106, v107
	global_store_dwordx4 v[112:113], v[58:61], off
	v_mul_f32_e32 v63, v63, v63
	v_fmac_f32_e32 v63, v62, v62
	s_waitcnt vmcnt(7)
	v_lshlrev_b32_e32 v58, 16, v108
	v_and_b32_e32 v59, 0xffff0000, v108
	v_lshlrev_b32_e32 v60, 16, v109
	v_and_b32_e32 v61, 0xffff0000, v109
	v_pk_add_f32 v[56:57], v[56:57], v[60:61]
	v_pk_add_f32 v[54:55], v[54:55], v[58:59]
	v_lshlrev_b32_e32 v58, 16, v110
	v_and_b32_e32 v59, 0xffff0000, v110
	v_lshlrev_b32_e32 v60, 16, v111
	v_and_b32_e32 v61, 0xffff0000, v111
	v_pk_add_f32 v[60:61], v[52:53], v[60:61]
	v_pk_add_f32 v[58:59], v[50:51], v[58:59]
	v_cvt_pk_bf16_f32 v50, v54, v55
	v_cvt_pk_bf16_f32 v51, v56, v57
	v_cvt_pk_bf16_f32 v52, v58, v59
	v_cvt_pk_bf16_f32 v53, v60, v61
	global_store_dwordx4 v[112:113], v[50:53], off offset:256
	v_fmac_f32_e32 v63, v64, v64
	v_fmac_f32_e32 v63, v65, v65
	v_mul_f32_e32 v50, v55, v55
	v_fmac_f32_e32 v50, v54, v54
	v_fmac_f32_e32 v50, v56, v56
	v_fmac_f32_e32 v50, v57, v57
	v_fmac_f32_e32 v63, v104, v104
	v_fmac_f32_e32 v50, v58, v58
	v_fmac_f32_e32 v63, v105, v105
	v_fmac_f32_e32 v50, v59, v59
	v_fmac_f32_e32 v63, v106, v106
	v_fmac_f32_e32 v50, v60, v60
	v_fmac_f32_e32 v63, v107, v107
	v_fmac_f32_e32 v50, v61, v61
	v_add_f32_e32 v50, v63, v50
	v_mov_b32_e32 v51, v50
	s_nop 1
	v_permlane16_swap_b32_e32 v51, v50
	s_waitcnt lgkmcnt(0)
	v_add_f32_e32 v50, v50, v51
	s_nop 0
	v_mov_b32_e32 v51, v50
	s_nop 1
	v_permlane32_swap_b32_e32 v51, v50
	s_and_saveexec_b64 s[24:25], s[0:1]
	s_cbranch_execz .LBB0_1325
	v_lshlrev_b64 v[52:53], 6, v[102:103]
	v_lshl_add_u64 v[52:53], s[12:13], 0, v[52:53]
	v_lshl_add_u64 v[52:53], s[22:23], 2, v[52:53]
	s_lshl_b32 s50, s41, 2
	v_lshl_add_u64 v[52:53], v[52:53], 0, s[50:51]
	s_waitcnt lgkmcnt(0)
	v_add_f32_e32 v50, v50, v51
	global_store_dword v[52:53], v50, off
.LBB0_1325:
	s_or_b64 exec, exec, s[24:25]
	s_waitcnt vmcnt(7)
	v_lshlrev_b32_e32 v50, 16, v86
	s_waitcnt lgkmcnt(0)
	v_and_b32_e32 v51, 0xffff0000, v86
	v_lshlrev_b32_e32 v52, 16, v87
	v_and_b32_e32 v53, 0xffff0000, v87
	v_pk_add_f32 v[48:49], v[48:49], v[52:53]
	v_pk_add_f32 v[46:47], v[46:47], v[50:51]
	v_lshlrev_b32_e32 v50, 16, v88
	v_and_b32_e32 v51, 0xffff0000, v88
	v_lshlrev_b32_e32 v52, 16, v89
	v_and_b32_e32 v53, 0xffff0000, v89
	v_pk_add_f32 v[52:53], v[44:45], v[52:53]
	v_pk_add_f32 v[50:51], v[42:43], v[50:51]
	v_lshl_add_u64 v[54:55], s[14:15], 0, v[100:101]
	v_cvt_pk_bf16_f32 v42, v46, v47
	v_cvt_pk_bf16_f32 v43, v48, v49
	v_cvt_pk_bf16_f32 v44, v50, v51
	v_cvt_pk_bf16_f32 v45, v52, v53
	v_lshl_add_u64 v[54:55], v[164:165], 1, v[54:55]
	global_store_dwordx4 v[54:55], v[42:45], off
	v_mul_f32_e32 v47, v47, v47
	v_fmac_f32_e32 v47, v46, v46
	s_waitcnt vmcnt(7)
	v_lshlrev_b32_e32 v42, 16, v82
	v_and_b32_e32 v43, 0xffff0000, v82
	v_lshlrev_b32_e32 v44, 16, v83
	v_and_b32_e32 v45, 0xffff0000, v83
	v_pk_add_f32 v[40:41], v[40:41], v[44:45]
	v_pk_add_f32 v[38:39], v[38:39], v[42:43]
	v_lshlrev_b32_e32 v42, 16, v84
	v_and_b32_e32 v43, 0xffff0000, v84
	v_lshlrev_b32_e32 v44, 16, v85
	v_and_b32_e32 v45, 0xffff0000, v85
	v_pk_add_f32 v[44:45], v[36:37], v[44:45]
	v_pk_add_f32 v[42:43], v[34:35], v[42:43]
	v_cvt_pk_bf16_f32 v34, v38, v39
	v_cvt_pk_bf16_f32 v35, v40, v41
	v_cvt_pk_bf16_f32 v36, v42, v43
	v_cvt_pk_bf16_f32 v37, v44, v45
	global_store_dwordx4 v[54:55], v[34:37], off offset:256
	v_fmac_f32_e32 v47, v48, v48
	v_fmac_f32_e32 v47, v49, v49
	v_mul_f32_e32 v34, v39, v39
	v_fmac_f32_e32 v34, v38, v38
	v_fmac_f32_e32 v34, v40, v40
	v_fmac_f32_e32 v34, v41, v41
	v_fmac_f32_e32 v47, v50, v50
	v_fmac_f32_e32 v34, v42, v42
	v_fmac_f32_e32 v47, v51, v51
	v_fmac_f32_e32 v34, v43, v43
	v_fmac_f32_e32 v47, v52, v52
	v_fmac_f32_e32 v34, v44, v44
	v_fmac_f32_e32 v47, v53, v53
	v_fmac_f32_e32 v34, v45, v45
	v_add_f32_e32 v34, v47, v34
	v_mov_b32_e32 v35, v34
	s_nop 1
	v_permlane16_swap_b32_e32 v35, v34
	s_waitcnt lgkmcnt(0)
	v_add_f32_e32 v34, v34, v35
	s_nop 0
	v_mov_b32_e32 v35, v34
	s_nop 1
	v_permlane32_swap_b32_e32 v35, v34
	s_and_saveexec_b64 s[24:25], s[0:1]
	s_cbranch_execz .LBB0_1327
	v_lshlrev_b64 v[36:37], 6, v[98:99]
	v_lshl_add_u64 v[36:37], s[12:13], 0, v[36:37]
	v_lshl_add_u64 v[36:37], s[22:23], 2, v[36:37]
	s_lshl_b32 s50, s41, 2
	v_lshl_add_u64 v[36:37], v[36:37], 0, s[50:51]
	s_waitcnt lgkmcnt(0)
	v_add_f32_e32 v34, v34, v35
	global_store_dword v[36:37], v34, off
; DI unsigned pack_bf16(float lo, float hi) { f32v2 f = {lo, hi}; bf16v2 b = __builtin_convertvector(f, bf16v2); return __builtin_bit_cast(unsigned, b); }
; DI float bf_lo(unsigned u) { return __uint_as_float(u << 16); }
; DI float bf_hi(unsigned u) { return __uint_as_float(u & 0xffff0000u); }
; DI float shx(float v, int o) { int l = (int)__builtin_amdgcn_mbcnt_hi(~0u, __builtin_amdgcn_mbcnt_lo(~0u, 0u)); asm volatile("" : "+v"(l)); return __int_as_float(__builtin_amdgcn_ds_bpermute((l ^ o) << 2, __float_as_int(v))); }
;     DI void operator()(const f32x4 (&acc)[2][2][4][2], const pg8::Unit& u, int wr, int wc, int fr, int fq, int) const {
;     ...
;             for (int m = 0; m < 4; ++m) { const size_t ro = (size_t)(row0 + ai * 128 + m * 16) * D + col0;
;                 float sq = 0.f;
; #pragma unroll
;                 for (int bj = 0; bj < 2; ++bj) {
;                     const u32x4 rr = r[m][bj];
;                     const f32x4 v0 = (f32x4){bf_lo(rr[0]), bf_hi(rr[0]), bf_lo(rr[1]), bf_hi(rr[1])} + acc[ai][bj][m][0];
;                     const f32x4 v1 = (f32x4){bf_lo(rr[2]), bf_hi(rr[2]), bf_lo(rr[3]), bf_hi(rr[3])} + acc[ai][bj][m][1];
;                     if (LAST) { *(f32x4*)(out + ro + bj * 128) = v0; *(f32x4*)(out + ro + bj * 128 + 4) = v1; }
;                     else {
;                         u32x4 w; w.x = pack_bf16(v0[0], v0[1]); w.y = pack_bf16(v0[2], v0[3]); w.z = pack_bf16(v1[0], v1[1]); w.w = pack_bf16(v1[2], v1[3]);
;                         *(u32x4*)(ho + ro + bj * 128) = w;
;                         sq += v0[0] * v0[0] + v0[1] * v0[1] + v0[2] * v0[2] + v0[3] * v0[3] + v1[0] * v1[0] + v1[1] * v1[1] + v1[2] * v1[2] + v1[3] * v1[3];
;                     }
;                 }
;                 if (!LAST) {
;                     sq += shx(sq, 16); sq += shx(sq, 32);
;                     if (fq == 0) ss[(size_t)(row0 + ai * 128 + m * 16) * 16 + u.pn * 4 + wc] = sq;
.LBB0_1327:
	s_or_b64 exec, exec, s[24:25]
	s_waitcnt vmcnt(7)
	v_lshlrev_b32_e32 v34, 16, v78
	s_waitcnt lgkmcnt(0)
	v_and_b32_e32 v35, 0xffff0000, v78
	v_lshlrev_b32_e32 v36, 16, v79
	v_and_b32_e32 v37, 0xffff0000, v79
	v_pk_add_f32 v[32:33], v[32:33], v[36:37]
	v_pk_add_f32 v[30:31], v[30:31], v[34:35]
	v_lshlrev_b32_e32 v34, 16, v80
	v_and_b32_e32 v35, 0xffff0000, v80
	v_lshlrev_b32_e32 v36, 16, v81
	v_and_b32_e32 v37, 0xffff0000, v81
	v_pk_add_f32 v[36:37], v[28:29], v[36:37]
	v_pk_add_f32 v[34:35], v[26:27], v[34:35]
	v_lshl_add_u64 v[38:39], s[14:15], 0, v[96:97]
	v_cvt_pk_bf16_f32 v26, v30, v31
	v_cvt_pk_bf16_f32 v27, v32, v33
	v_cvt_pk_bf16_f32 v28, v34, v35
	v_cvt_pk_bf16_f32 v29, v36, v37
	v_lshl_add_u64 v[38:39], v[164:165], 1, v[38:39]
	global_store_dwordx4 v[38:39], v[26:29], off
	v_mul_f32_e32 v31, v31, v31
	v_fmac_f32_e32 v31, v30, v30
	s_waitcnt vmcnt(7)
	v_lshlrev_b32_e32 v26, 16, v74
	v_and_b32_e32 v27, 0xffff0000, v74
	v_lshlrev_b32_e32 v28, 16, v75
	v_and_b32_e32 v29, 0xffff0000, v75
	v_pk_add_f32 v[24:25], v[24:25], v[28:29]
	v_pk_add_f32 v[22:23], v[22:23], v[26:27]
	v_lshlrev_b32_e32 v26, 16, v76
	v_and_b32_e32 v27, 0xffff0000, v76
	v_lshlrev_b32_e32 v28, 16, v77
	v_and_b32_e32 v29, 0xffff0000, v77
	v_pk_add_f32 v[28:29], v[20:21], v[28:29]
	v_pk_add_f32 v[26:27], v[18:19], v[26:27]
	v_cvt_pk_bf16_f32 v18, v22, v23
	v_cvt_pk_bf16_f32 v19, v24, v25
	v_cvt_pk_bf16_f32 v20, v26, v27
	v_cvt_pk_bf16_f32 v21, v28, v29
	global_store_dwordx4 v[38:39], v[18:21], off offset:256
	v_fmac_f32_e32 v31, v32, v32
	v_fmac_f32_e32 v31, v33, v33
	v_mul_f32_e32 v18, v23, v23
	v_fmac_f32_e32 v18, v22, v22
	v_fmac_f32_e32 v18, v24, v24
	v_fmac_f32_e32 v18, v25, v25
	v_fmac_f32_e32 v31, v34, v34
	v_fmac_f32_e32 v18, v26, v26
	v_fmac_f32_e32 v31, v35, v35
	v_fmac_f32_e32 v18, v27, v27
	v_fmac_f32_e32 v31, v36, v36
	v_fmac_f32_e32 v18, v28, v28
	v_fmac_f32_e32 v31, v37, v37
	v_fmac_f32_e32 v18, v29, v29
	v_add_f32_e32 v18, v31, v18
	v_mov_b32_e32 v19, v18
	s_nop 1
	v_permlane16_swap_b32_e32 v19, v18
	s_waitcnt lgkmcnt(0)
	v_add_f32_e32 v18, v18, v19
	s_nop 0
	v_mov_b32_e32 v19, v18
	s_nop 1
	v_permlane32_swap_b32_e32 v19, v18
	s_and_saveexec_b64 s[24:25], s[0:1]
	s_cbranch_execz .LBB0_1329
	v_lshlrev_b64 v[20:21], 6, v[92:93]
	v_lshl_add_u64 v[20:21], s[12:13], 0, v[20:21]
	v_lshl_add_u64 v[20:21], s[22:23], 2, v[20:21]
	s_lshl_b32 s50, s41, 2
	v_lshl_add_u64 v[20:21], v[20:21], 0, s[50:51]
	s_waitcnt lgkmcnt(0)
	v_add_f32_e32 v18, v18, v19
	global_store_dword v[20:21], v18, off
.LBB0_1329:
	s_or_b64 exec, exec, s[24:25]
	s_waitcnt vmcnt(7)
	v_lshlrev_b32_e32 v18, 16, v70
	s_waitcnt lgkmcnt(0)
	v_and_b32_e32 v19, 0xffff0000, v70
	v_lshlrev_b32_e32 v20, 16, v71
	v_and_b32_e32 v21, 0xffff0000, v71
	v_pk_add_f32 v[16:17], v[16:17], v[20:21]
	v_pk_add_f32 v[14:15], v[14:15], v[18:19]
	v_lshlrev_b32_e32 v18, 16, v72
	v_and_b32_e32 v19, 0xffff0000, v72
	v_lshlrev_b32_e32 v20, 16, v73
	v_and_b32_e32 v21, 0xffff0000, v73
	v_pk_add_f32 v[20:21], v[12:13], v[20:21]
	v_pk_add_f32 v[18:19], v[10:11], v[18:19]
	v_lshl_add_u64 v[22:23], s[14:15], 0, v[94:95]
	v_cvt_pk_bf16_f32 v10, v14, v15
	v_cvt_pk_bf16_f32 v11, v16, v17
	v_cvt_pk_bf16_f32 v12, v18, v19
	v_cvt_pk_bf16_f32 v13, v20, v21
	v_lshl_add_u64 v[22:23], v[164:165], 1, v[22:23]
	global_store_dwordx4 v[22:23], v[10:13], off
	v_mul_f32_e32 v15, v15, v15
	v_fmac_f32_e32 v15, v14, v14
	s_waitcnt vmcnt(7)
	v_lshlrev_b32_e32 v10, 16, v66
	v_and_b32_e32 v11, 0xffff0000, v66
	v_lshlrev_b32_e32 v12, 16, v67
	v_and_b32_e32 v13, 0xffff0000, v67
	v_pk_add_f32 v[8:9], v[8:9], v[12:13]
	v_pk_add_f32 v[6:7], v[6:7], v[10:11]
	v_lshlrev_b32_e32 v10, 16, v68
	v_and_b32_e32 v11, 0xffff0000, v68
	v_lshlrev_b32_e32 v12, 16, v69
	v_and_b32_e32 v13, 0xffff0000, v69
	v_pk_add_f32 v[12:13], v[4:5], v[12:13]
	v_pk_add_f32 v[10:11], v[2:3], v[10:11]
	v_cvt_pk_bf16_f32 v2, v6, v7
	v_cvt_pk_bf16_f32 v3, v8, v9
	v_cvt_pk_bf16_f32 v4, v10, v11
	v_cvt_pk_bf16_f32 v5, v12, v13
	global_store_dwordx4 v[22:23], v[2:5], off offset:256
	v_fmac_f32_e32 v15, v16, v16
	v_fmac_f32_e32 v15, v17, v17
	v_mul_f32_e32 v2, v7, v7
	v_fmac_f32_e32 v2, v6, v6
	v_fmac_f32_e32 v2, v8, v8
	v_fmac_f32_e32 v2, v9, v9
	v_fmac_f32_e32 v15, v18, v18
	v_fmac_f32_e32 v2, v10, v10
	v_fmac_f32_e32 v15, v19, v19
	v_fmac_f32_e32 v2, v11, v11
	v_fmac_f32_e32 v15, v20, v20
	v_fmac_f32_e32 v2, v12, v12
	v_fmac_f32_e32 v15, v21, v21
	v_fmac_f32_e32 v2, v13, v13
	v_add_f32_e32 v2, v15, v2
	v_mov_b32_e32 v3, v2
	s_nop 1
	v_permlane16_swap_b32_e32 v3, v2
	s_waitcnt lgkmcnt(0)
	v_add_f32_e32 v2, v2, v3
	s_nop 0
	v_mov_b32_e32 v3, v2
	s_nop 1
	v_permlane32_swap_b32_e32 v3, v2
	s_and_saveexec_b64 s[24:25], s[0:1]
	s_cbranch_execz .LBB0_1331
	v_lshlrev_b64 v[4:5], 6, v[90:91]
	v_lshl_add_u64 v[4:5], s[12:13], 0, v[4:5]
	v_lshl_add_u64 v[4:5], s[22:23], 2, v[4:5]
	s_lshl_b32 s50, s41, 2
	v_lshl_add_u64 v[4:5], v[4:5], 0, s[50:51]
	s_waitcnt lgkmcnt(0)
	v_add_f32_e32 v2, v2, v3
	global_store_dword v[4:5], v2, off
